# v40 + gamma/beta/row-stat loads in the SwiGLU and gate epilogues fetched as 64B-contiguous segments (lane exchange after load)
# baseline (speedup 1.0000x reference)
; __device__ __forceinline__ float xsum16(float v) { const auto r = __builtin_amdgcn_permlane16_swap(__float_as_uint(v), __float_as_uint(v), false, false); return __uint_as_float(r[0]) + __uint_as_float(r[1]); }
; __device__ __forceinline__ float xsum32(float v) { const auto r = __builtin_amdgcn_permlane32_swap(__float_as_uint(v), __float_as_uint(v), false, false); return __uint_as_float(r[0]) + __uint_as_float(r[1]); }
; __device__ __forceinline__ void row_stats4(const float* st, int rowb, int fq, float (&mu)[4], float (&rs)[4]) {
;     f32x4 a[4], b[4];
; #pragma unroll
;     for (int m = 0; m < 4; ++m) { const f32x4* p = (const f32x4*)(st + (size_t)(rowb + m * 16) * 32 + fq * 8); a[m] = p[0]; b[m] = p[1]; }
; #pragma unroll
;     for (int m = 0; m < 4; ++m) { float s1 = (a[m][0] + a[m][2]) + (b[m][0] + b[m][2]), s2 = (a[m][1] + a[m][3]) + (b[m][1] + b[m][3]);
;         s1 = xsum32(xsum16(s1)); s2 = xsum32(xsum16(s2));
;         const float mm = s1 * (1.0f / 1024.0f); mu[m] = mm; rs[m] = rsqrtf(fmaxf(s2 * (1.0f / 1024.0f) - mm * mm, 0.f) + LN_EPS_); }
;     __device__ __forceinline__ void operator()(const f32x4 (&acc)[2][2][4][2], const pg8::Unit& u, int wr, int wc, int fr, int fq) const {
;         const int row0 = u.pm * 256 + wr * 64 + fr, cl = wc * 32 + fq * 8, cB0 = u.pn * 256 + cl;
;         f32x4 g0[2], g1[2], b0[2], b1[2];
; #pragma unroll
;         for (int n = 0; n < 2; ++n) { g0[n] = *(const f32x4*)(gW + cB0 + 4 * n); g1[n] = *(const f32x4*)(gW + cB0 + 128 + 4 * n); b0[n] = *(const f32x4*)(bW + cB0 + 4 * n); b1[n] = *(const f32x4*)(bW + cB0 + 128 + 4 * n); }
;         float muA[4], rsA[4], muB[4], rsB[4]; row_stats4(st, row0, fq, muA, rsA); row_stats4(st, row0 + 128, fq, muB, rsB);
.LBB0_291:
	s_lshl_b32 s9, s2, 8
	v_lshl_or_b32 v62, s44, 8, v220
	s_add_i32 s9, s9, s19
	v_ashrrev_i32_e32 v63, 31, v62
	v_readlane_b32 s16, v250, 41
	v_lshlrev_b64 v[62:63], 2, v[62:63]
	v_readlane_b32 s17, v250, 42
	v_or_b32_e32 v208, s9, v213
	v_ashrrev_i32_e32 v209, 31, v208
	v_lshl_add_u64 v[64:65], s[16:17], 0, v[62:63]
	v_readlane_b32 s16, v250, 60
	v_readlane_b32 s17, v250, 61
	v_lshlrev_b64 v[162:163], 7, v[208:209]
	v_lshl_add_u64 v[218:219], v[202:203], 0, v[162:163]
	v_lshl_add_u64 v[82:83], s[16:17], 0, v[62:63]
	s_nop 1
	v_bfe_u32 v67, v227, 4, 2
	v_sub_u32_e32 v66, 0, v67
	v_lshlrev_b32_e32 v66, 4, v66
	v_ashrrev_i32_e32 v67, 31, v66
	v_lshl_add_u64 v[66:67], v[64:65], 0, v[66:67]
	global_load_dwordx4 v[74:77], v[66:67], off offset:64
	global_load_dwordx4 v[94:97], v[66:67], off
	s_nop 1
	v_bfe_u32 v71, v227, 4, 2
	v_sub_u32_e32 v70, 0, v71
	v_lshlrev_b32_e32 v70, 4, v70
	v_ashrrev_i32_e32 v71, 31, v70
	v_lshl_add_u64 v[70:71], v[64:65], 0, v[70:71]
	global_load_dwordx4 v[66:69], v[70:71], off offset:576
	global_load_dwordx4 v[86:89], v[70:71], off offset:512
	s_nop 1
	v_bfe_u32 v63, v227, 4, 2
	v_sub_u32_e32 v62, 0, v63
	v_lshlrev_b32_e32 v62, 4, v62
	v_ashrrev_i32_e32 v63, 31, v62
	v_lshl_add_u64 v[62:63], v[82:83], 0, v[62:63]
	global_load_dwordx4 v[70:73], v[62:63], off offset:64
	global_load_dwordx4 v[90:93], v[62:63], off
	s_nop 0
	s_nop 1
	v_bfe_u32 v163, v227, 4, 2
	v_sub_u32_e32 v162, 0, v163
	v_lshlrev_b32_e32 v162, 4, v162
	v_ashrrev_i32_e32 v163, 31, v162
	v_lshl_add_u64 v[162:163], v[82:83], 0, v[162:163]
	global_load_dwordx4 v[62:65], v[162:163], off offset:576
	s_nop 0
	global_load_dwordx4 v[82:85], v[162:163], off offset:512
	s_nop 0
	s_nop 1
	v_bfe_u32 v163, v227, 4, 2
	v_sub_u32_e32 v162, 0, v163
	v_lshlrev_b32_e32 v162, 4, v162
	v_ashrrev_i32_e32 v163, 31, v162
	v_lshl_add_u64 v[162:163], v[218:219], 0, v[162:163]
	global_load_dwordx4 v[234:237], v[162:163], off
	global_load_dwordx4 v[238:241], v[162:163], off offset:64
	v_or_b32_e32 v162, 16, v208
	v_ashrrev_i32_e32 v163, 31, v162
	v_lshlrev_b64 v[162:163], 7, v[162:163]
	v_lshl_add_u64 v[162:163], v[202:203], 0, v[162:163]
	s_nop 1
	v_bfe_u32 v165, v227, 4, 2
	v_sub_u32_e32 v164, 0, v165
	v_lshlrev_b32_e32 v164, 4, v164
	v_ashrrev_i32_e32 v165, 31, v164
	v_lshl_add_u64 v[164:165], v[162:163], 0, v[164:165]
	global_load_dwordx4 v[182:185], v[164:165], off
	global_load_dwordx4 v[178:181], v[164:165], off offset:64
	v_or_b32_e32 v162, 32, v208
	v_ashrrev_i32_e32 v163, 31, v162
	v_lshlrev_b64 v[162:163], 7, v[162:163]
	v_lshl_add_u64 v[162:163], v[202:203], 0, v[162:163]
	s_nop 1
	v_bfe_u32 v171, v227, 4, 2
	v_sub_u32_e32 v170, 0, v171
	v_lshlrev_b32_e32 v170, 4, v170
	v_ashrrev_i32_e32 v171, 31, v170
	v_lshl_add_u64 v[170:171], v[162:163], 0, v[170:171]
	global_load_dwordx4 v[166:169], v[170:171], off
	s_nop 0
	global_load_dwordx4 v[162:165], v[170:171], off offset:64
	v_or_b32_e32 v170, 48, v208
	v_ashrrev_i32_e32 v171, 31, v170
	v_lshlrev_b64 v[170:171], 7, v[170:171]
	v_lshl_add_u64 v[174:175], v[202:203], 0, v[170:171]
	s_nop 1
	v_bfe_u32 v187, v227, 4, 2
	v_sub_u32_e32 v186, 0, v187
	v_lshlrev_b32_e32 v186, 4, v186
	v_ashrrev_i32_e32 v187, 31, v186
	v_lshl_add_u64 v[186:187], v[174:175], 0, v[186:187]
	global_load_dwordx4 v[170:173], v[186:187], off
	s_nop 0
	global_load_dwordx4 v[174:177], v[186:187], off offset:64
	s_mov_b32 s16, 0x3a800000
	s_mov_b32 s11, 0x800000
	s_movk_i32 s2, 0x4000
	s_mov_b64 s[28:29], 0x4800
	v_readlane_b32 s30, v253, 41
	v_readlane_b32 s31, v253, 42
	s_movk_i32 s38, 0x33c0
	s_waitcnt vmcnt(14)
	v_permlane32_swap_b32_e32 v94, v74
	v_permlane32_swap_b32_e32 v95, v75
	v_permlane32_swap_b32_e32 v96, v76
	v_permlane32_swap_b32_e32 v97, v77
	v_permlane16_swap_b32_e32 v94, v74
	v_permlane16_swap_b32_e32 v95, v75
	v_permlane16_swap_b32_e32 v96, v76
	v_permlane16_swap_b32_e32 v97, v77
	v_xor_b32_e32 v77, 0x80000000, v77
	v_xor_b32_e32 v76, 0x80000000, v76
	s_waitcnt vmcnt(12)
	v_permlane32_swap_b32_e32 v86, v66
	v_permlane32_swap_b32_e32 v87, v67
	v_permlane32_swap_b32_e32 v88, v68
	v_permlane32_swap_b32_e32 v89, v69
	v_permlane16_swap_b32_e32 v86, v66
	v_permlane16_swap_b32_e32 v87, v67
	v_permlane16_swap_b32_e32 v88, v68
	v_permlane16_swap_b32_e32 v89, v69
	v_xor_b32_e32 v69, 0x80000000, v69
	v_xor_b32_e32 v89, 0x80000000, v89
	v_xor_b32_e32 v88, 0x80000000, v88
	v_xor_b32_e32 v68, 0x80000000, v68
	s_waitcnt vmcnt(6)
	v_permlane32_swap_b32_e32 v234, v238
	v_permlane32_swap_b32_e32 v235, v239
	v_permlane32_swap_b32_e32 v236, v240
	v_permlane32_swap_b32_e32 v237, v241
	v_permlane16_swap_b32_e32 v234, v238
	v_permlane16_swap_b32_e32 v235, v239
	v_permlane16_swap_b32_e32 v236, v240
	v_permlane16_swap_b32_e32 v237, v241
	v_mov_b32_e32 v186, v234
	v_mov_b32_e32 v187, v238
	v_mov_b32_e32 v188, v236
	v_mov_b32_e32 v189, v240
	v_pk_add_f32 v[186:187], v[186:187], v[188:189]
	v_mov_b32_e32 v238, v235
	v_pk_add_f32 v[186:187], v[186:187], v[186:187] op_sel:[0,1] op_sel_hi:[1,0]
	v_mov_b32_e32 v240, v237
	v_pk_add_f32 v[188:189], v[238:239], v[240:241]
	v_mov_b32_e32 v0, v186
	v_pk_add_f32 v[188:189], v[188:189], v[188:189] op_sel:[0,1] op_sel_hi:[1,0]
	s_nop 0
	v_permlane16_swap_b32_e32 v186, v0
	v_add_f32_e32 v187, v186, v0
	v_mov_b32_e32 v0, v188
	s_nop 1
	v_permlane16_swap_b32_e32 v188, v0
	v_add_f32_e32 v186, v188, v0
	v_mov_b32_e32 v189, v187
	v_mov_b32_e32 v188, v186
	s_nop 0
	v_permlane32_swap_b32_e32 v187, v189
	v_permlane32_swap_b32_e32 v186, v188
	v_pk_add_f32 v[186:187], v[186:187], v[188:189]
	s_waitcnt vmcnt(4)
; __device__ __forceinline__ float xsum16(float v) { const auto r = __builtin_amdgcn_permlane16_swap(__float_as_uint(v), __float_as_uint(v), false, false); return __uint_as_float(r[0]) + __uint_as_float(r[1]); }
; __device__ __forceinline__ float xsum32(float v) { const auto r = __builtin_amdgcn_permlane32_swap(__float_as_uint(v), __float_as_uint(v), false, false); return __uint_as_float(r[0]) + __uint_as_float(r[1]); }
; __device__ __forceinline__ void row_stats4(const float* st, int rowb, int fq, float (&mu)[4], float (&rs)[4]) {
;     f32x4 a[4], b[4];
; #pragma unroll
;     for (int m = 0; m < 4; ++m) { const f32x4* p = (const f32x4*)(st + (size_t)(rowb + m * 16) * 32 + fq * 8); a[m] = p[0]; b[m] = p[1]; }
; #pragma unroll
;     for (int m = 0; m < 4; ++m) { float s1 = (a[m][0] + a[m][2]) + (b[m][0] + b[m][2]), s2 = (a[m][1] + a[m][3]) + (b[m][1] + b[m][3]);
;         s1 = xsum32(xsum16(s1)); s2 = xsum32(xsum16(s2));
;         const float mm = s1 * (1.0f / 1024.0f); mu[m] = mm; rs[m] = rsqrtf(fmaxf(s2 * (1.0f / 1024.0f) - mm * mm, 0.f) + LN_EPS_); }
;     __device__ __forceinline__ void operator()(const f32x4 (&acc)[2][2][4][2], const pg8::Unit& u, int wr, int wc, int fr, int fq) const {
;     ...
;             for (int m = 0; m < 4; ++m) { const float mu = ai ? muB[m] : muA[m], rs = ai ? rsB[m] : rsA[m]; f32x4 h[2];
; #pragma unroll
;                 for (int n = 0; n < 2; ++n) { const f32x4 zg = (acc[ai][0][m][n] - g0[n] * mu) * rs + b0[n], zu = (acc[ai][1][m][n] - g1[n] * mu) * rs + b1[n]; h[n] = silu_mul(zg, zu); }
	v_permlane32_swap_b32_e32 v182, v178
	v_permlane32_swap_b32_e32 v183, v179
	v_permlane32_swap_b32_e32 v184, v180
	v_permlane32_swap_b32_e32 v185, v181
	v_permlane16_swap_b32_e32 v182, v178
	v_permlane16_swap_b32_e32 v183, v179
	v_permlane16_swap_b32_e32 v184, v180
	v_permlane16_swap_b32_e32 v185, v181
	v_mov_b32_e32 v188, v184
	v_pk_mul_f32 v[210:211], v[186:187], s[16:17] op_sel_hi:[1,0]
	v_mov_b32_e32 v187, v178
	v_fma_f32 v0, -v211, v211, v210
	v_max_f32_e32 v0, 0, v0
	v_add_f32_e32 v0, 0x3727c5ac, v0
	v_cmp_gt_f32_e32 vcc, s11, v0
	v_mul_f32_e32 v186, 0x4b800000, v0
	v_mov_b32_e32 v189, v180
	v_cndmask_b32_e32 v0, v0, v186, vcc
	v_rsq_f32_e32 v0, v0
	v_mov_b32_e32 v178, v183
	v_mov_b32_e32 v180, v185
	v_pk_add_f32 v[178:179], v[178:179], v[180:181]
	v_mul_f32_e32 v186, 0x45800000, v0
	v_cndmask_b32_e32 v212, v0, v186, vcc
	v_mov_b32_e32 v186, v182
	v_pk_add_f32 v[186:187], v[186:187], v[188:189]
	v_pk_add_f32 v[178:179], v[178:179], v[178:179] op_sel:[0,1] op_sel_hi:[1,0]
	v_pk_add_f32 v[186:187], v[186:187], v[186:187] op_sel:[0,1] op_sel_hi:[1,0]
	v_pk_fma_f32 v[154:155], v[86:87], v[210:211], v[154:155] op_sel:[0,1,0] neg_lo:[1,0,0] neg_hi:[1,0,0]
	v_mov_b32_e32 v0, v186
	s_nop 1
	v_permlane16_swap_b32_e32 v186, v0
	v_add_f32_e32 v179, v186, v0
	v_mov_b32_e32 v0, v178
	s_nop 1
	v_permlane16_swap_b32_e32 v178, v0
	v_add_f32_e32 v178, v178, v0
	v_mov_b32_e32 v181, v179
	v_mov_b32_e32 v180, v178
	s_nop 0
	v_permlane32_swap_b32_e32 v179, v181
	v_permlane32_swap_b32_e32 v178, v180
	v_pk_add_f32 v[178:179], v[178:179], v[180:181]
	s_waitcnt vmcnt(2)
	v_permlane32_swap_b32_e32 v166, v162
	v_permlane32_swap_b32_e32 v167, v163
	v_permlane32_swap_b32_e32 v168, v164
	v_permlane32_swap_b32_e32 v169, v165
	v_permlane16_swap_b32_e32 v166, v162
	v_permlane16_swap_b32_e32 v167, v163
	v_permlane16_swap_b32_e32 v168, v164
	v_permlane16_swap_b32_e32 v169, v165
	v_mov_b32_e32 v180, v168
	v_pk_mul_f32 v[214:215], v[178:179], s[16:17] op_sel_hi:[1,0]
	v_mov_b32_e32 v179, v162
	v_fma_f32 v0, -v215, v215, v214
	v_max_f32_e32 v0, 0, v0
	v_add_f32_e32 v0, 0x3727c5ac, v0
	v_cmp_gt_f32_e32 vcc, s11, v0
	v_mul_f32_e32 v178, 0x4b800000, v0
	v_mov_b32_e32 v181, v164
	v_cndmask_b32_e32 v0, v0, v178, vcc
	v_rsq_f32_e32 v0, v0
	v_mov_b32_e32 v162, v167
	v_mov_b32_e32 v164, v169
	v_pk_add_f32 v[162:163], v[162:163], v[164:165]
	v_mul_f32_e32 v178, 0x45800000, v0
	v_cndmask_b32_e32 v216, v0, v178, vcc
	v_mov_b32_e32 v178, v166
	v_pk_add_f32 v[178:179], v[178:179], v[180:181]
	v_pk_add_f32 v[162:163], v[162:163], v[162:163] op_sel:[0,1] op_sel_hi:[1,0]
	v_pk_add_f32 v[178:179], v[178:179], v[178:179] op_sel:[0,1] op_sel_hi:[1,0]
	v_add_u32_e32 v166, 0x80, v208
	v_mov_b32_e32 v0, v178
	s_nop 1
	v_permlane16_swap_b32_e32 v178, v0
	v_add_f32_e32 v163, v178, v0
	v_mov_b32_e32 v0, v162
	s_nop 1
	v_permlane16_swap_b32_e32 v162, v0
	v_add_f32_e32 v162, v162, v0
	v_mov_b32_e32 v165, v163
	v_mov_b32_e32 v164, v162
	s_nop 0
	v_permlane32_swap_b32_e32 v163, v165
	v_permlane32_swap_b32_e32 v162, v164
	v_pk_add_f32 v[162:163], v[162:163], v[164:165]
	s_waitcnt vmcnt(0)
	v_permlane32_swap_b32_e32 v170, v174
	v_permlane32_swap_b32_e32 v171, v175
	v_permlane32_swap_b32_e32 v172, v176
	v_permlane32_swap_b32_e32 v173, v177
	v_permlane16_swap_b32_e32 v170, v174
	v_permlane16_swap_b32_e32 v171, v175
	v_permlane16_swap_b32_e32 v172, v176
	v_permlane16_swap_b32_e32 v173, v177
	v_mov_b32_e32 v164, v172
	v_pk_mul_f32 v[178:179], v[162:163], s[16:17] op_sel_hi:[1,0]
	v_mov_b32_e32 v163, v174
	v_fma_f32 v0, -v179, v179, v178
	v_max_f32_e32 v0, 0, v0
	v_add_f32_e32 v0, 0x3727c5ac, v0
	v_cmp_gt_f32_e32 vcc, s11, v0
	v_mul_f32_e32 v162, 0x4b800000, v0
	v_mov_b32_e32 v165, v176
	v_cndmask_b32_e32 v0, v0, v162, vcc
	v_rsq_f32_e32 v0, v0
	v_mov_b32_e32 v174, v171
	v_mov_b32_e32 v176, v173
	v_ashrrev_i32_e32 v167, 31, v166
	v_mul_f32_e32 v162, 0x45800000, v0
	v_cndmask_b32_e32 v180, v0, v162, vcc
	v_mov_b32_e32 v162, v170
	v_pk_add_f32 v[162:163], v[162:163], v[164:165]
	v_pk_add_f32 v[164:165], v[174:175], v[176:177]
	v_pk_add_f32 v[162:163], v[162:163], v[162:163] op_sel:[0,1] op_sel_hi:[1,0]
	v_pk_add_f32 v[164:165], v[164:165], v[164:165] op_sel:[0,1] op_sel_hi:[1,0]
	v_mov_b32_e32 v0, v162
	s_nop 1
	v_permlane16_swap_b32_e32 v162, v0
	v_add_f32_e32 v163, v162, v0
	v_mov_b32_e32 v0, v164
	s_nop 1
	v_permlane16_swap_b32_e32 v164, v0
	v_add_f32_e32 v162, v164, v0
	v_mov_b32_e32 v165, v163
	v_mov_b32_e32 v164, v162
	s_nop 0
	v_permlane32_swap_b32_e32 v163, v165
	v_permlane32_swap_b32_e32 v162, v164
	v_pk_add_f32 v[162:163], v[162:163], v[164:165]
	v_lshl_add_u64 v[168:169], v[218:219], 0, s[28:29]
	v_pk_mul_f32 v[170:171], v[162:163], s[16:17] op_sel_hi:[1,0]
	s_mov_b64 s[28:29], 0x5000
	v_fma_f32 v0, -v171, v171, v170
	v_max_f32_e32 v0, 0, v0
	v_add_f32_e32 v0, 0x3727c5ac, v0
	v_cmp_gt_f32_e32 vcc, s11, v0
	v_mul_f32_e32 v162, 0x4b800000, v0
	v_permlane32_swap_b32_e32 v82, v62
	v_permlane32_swap_b32_e32 v83, v63
	v_permlane32_swap_b32_e32 v84, v64
	v_permlane32_swap_b32_e32 v85, v65
	v_permlane16_swap_b32_e32 v82, v62
	v_permlane16_swap_b32_e32 v83, v63
	v_permlane16_swap_b32_e32 v84, v64
	v_permlane16_swap_b32_e32 v85, v65
	v_pk_fma_f32 v[154:155], v[154:155], v[212:213], v[82:83] op_sel_hi:[1,0,1]
	v_cndmask_b32_e32 v0, v0, v162, vcc
	v_rsq_f32_e32 v0, v0
	v_pk_fma_f32 v[156:157], v[88:89], v[210:211], v[156:157] op_sel:[0,1,0]
	v_pk_fma_f32 v[150:151], v[74:75], v[210:211], v[150:151] op_sel:[0,1,0] neg_lo:[1,0,0] neg_hi:[1,0,0]
	v_pk_fma_f32 v[156:157], v[156:157], v[212:213], v[84:85] op_sel_hi:[1,0,1]
	v_mul_f32_e32 v162, 0x45800000, v0
	v_cndmask_b32_e32 v172, v0, v162, vcc
; __device__ __forceinline__ float xsum16(float v) { const auto r = __builtin_amdgcn_permlane16_swap(__float_as_uint(v), __float_as_uint(v), false, false); return __uint_as_float(r[0]) + __uint_as_float(r[1]); }
; __device__ __forceinline__ float xsum32(float v) { const auto r = __builtin_amdgcn_permlane32_swap(__float_as_uint(v), __float_as_uint(v), false, false); return __uint_as_float(r[0]) + __uint_as_float(r[1]); }
; __device__ __forceinline__ u32x4 pack8(const f32x4 a, const f32x4 b) { u32x4 w; w.x = cvt_pk_bf16(a[0], a[1]); w.y = cvt_pk_bf16(a[2], a[3]); w.z = cvt_pk_bf16(b[0], b[1]); w.w = cvt_pk_bf16(b[2], b[3]); return w; }
; __device__ __forceinline__ void row_stats4(const float* st, int rowb, int fq, float (&mu)[4], float (&rs)[4]) {
;     f32x4 a[4], b[4];
; #pragma unroll
;     for (int m = 0; m < 4; ++m) { const f32x4* p = (const f32x4*)(st + (size_t)(rowb + m * 16) * 32 + fq * 8); a[m] = p[0]; b[m] = p[1]; }
; #pragma unroll
;     for (int m = 0; m < 4; ++m) { float s1 = (a[m][0] + a[m][2]) + (b[m][0] + b[m][2]), s2 = (a[m][1] + a[m][3]) + (b[m][1] + b[m][3]);
;         s1 = xsum32(xsum16(s1)); s2 = xsum32(xsum16(s2));
;         const float mm = s1 * (1.0f / 1024.0f); mu[m] = mm; rs[m] = rsqrtf(fmaxf(s2 * (1.0f / 1024.0f) - mm * mm, 0.f) + LN_EPS_); }
;     __device__ __forceinline__ void operator()(const f32x4 (&acc)[2][2][4][2], const pg8::Unit& u, int wr, int wc, int fr, int fq) const {
;     ...
;             for (int m = 0; m < 4; ++m) { const float mu = ai ? muB[m] : muA[m], rs = ai ? rsB[m] : rsA[m]; f32x4 h[2];
; #pragma unroll
;                 for (int n = 0; n < 2; ++n) { const f32x4 zg = (acc[ai][0][m][n] - g0[n] * mu) * rs + b0[n], zu = (acc[ai][1][m][n] - g1[n] * mu) * rs + b1[n]; h[n] = silu_mul(zg, zu); }
;                 ow[ai][m] = pack8(h[0], h[1]); }
	v_lshlrev_b64 v[162:163], 7, v[166:167]
	v_lshl_add_u64 v[162:163], v[202:203], 0, v[162:163]
	s_nop 1
	v_bfe_u32 v183, v227, 4, 2
	v_sub_u32_e32 v182, 0, v183
	v_lshlrev_b32_e32 v182, 4, v182
	v_ashrrev_i32_e32 v183, 31, v182
	v_lshl_add_u64 v[182:183], v[162:163], 0, v[182:183]
	global_load_dwordx4 v[174:177], v[182:183], off
	s_nop 0
	global_load_dwordx4 v[162:165], v[182:183], off offset:64
	v_add_co_u32_e32 v182, vcc, s2, v218
	s_movk_i32 s2, 0x5000
	s_nop 0
	v_addc_co_u32_e32 v183, vcc, 0, v219, vcc
	global_load_dwordx4 v[234:237], v[182:183], off offset:2048
	global_load_dwordx4 v[238:241], v[168:169], off offset:16
	v_add_co_u32_e32 v182, vcc, s2, v218
	v_lshl_add_u64 v[168:169], v[218:219], 0, s[28:29]
	s_nop 0
	v_addc_co_u32_e32 v183, vcc, 0, v219, vcc
	global_load_dwordx4 v[242:245], v[182:183], off
	global_load_dwordx4 v[246:249], v[168:169], off offset:16
	s_mov_b64 s[28:29], 0x5800
	v_lshl_add_u64 v[168:169], v[218:219], 0, s[28:29]
	global_load_dwordx4 v[186:189], v[182:183], off offset:2048
	global_load_dwordx4 v[190:193], v[168:169], off offset:16
	v_permlane32_swap_b32_e32 v90, v70
	v_permlane32_swap_b32_e32 v91, v71
	v_permlane32_swap_b32_e32 v92, v72
	v_permlane32_swap_b32_e32 v93, v73
	v_permlane16_swap_b32_e32 v90, v70
	v_permlane16_swap_b32_e32 v91, v71
	v_permlane16_swap_b32_e32 v92, v72
	v_permlane16_swap_b32_e32 v93, v73
	v_pk_fma_f32 v[150:151], v[150:151], v[212:213], v[70:71] op_sel_hi:[1,0,1]
	v_pk_fma_f32 v[152:153], v[76:77], v[210:211], v[152:153] op_sel:[0,1,0]
	v_pk_fma_f32 v[146:147], v[66:67], v[210:211], v[146:147] op_sel:[0,1,0] neg_lo:[1,0,0] neg_hi:[1,0,0]
	v_pk_fma_f32 v[152:153], v[152:153], v[212:213], v[72:73] op_sel_hi:[1,0,1]
	v_pk_fma_f32 v[146:147], v[146:147], v[212:213], v[62:63] op_sel_hi:[1,0,1]
	v_pk_fma_f32 v[148:149], v[68:69], v[210:211], v[148:149] op_sel:[0,1,0]
	v_pk_fma_f32 v[138:139], v[86:87], v[214:215], v[138:139] op_sel:[0,1,0] neg_lo:[1,0,0] neg_hi:[1,0,0]
	v_pk_fma_f32 v[148:149], v[148:149], v[212:213], v[64:65] op_sel_hi:[1,0,1]
	v_pk_fma_f32 v[138:139], v[138:139], v[216:217], v[82:83] op_sel_hi:[1,0,1]
	v_pk_fma_f32 v[140:141], v[88:89], v[214:215], v[140:141] op_sel:[0,1,0]
	v_pk_fma_f32 v[134:135], v[74:75], v[214:215], v[134:135] op_sel:[0,1,0] neg_lo:[1,0,0] neg_hi:[1,0,0]
	v_pk_fma_f32 v[140:141], v[140:141], v[216:217], v[84:85] op_sel_hi:[1,0,1]
	v_pk_fma_f32 v[134:135], v[134:135], v[216:217], v[70:71] op_sel_hi:[1,0,1]
	v_pk_fma_f32 v[136:137], v[76:77], v[214:215], v[136:137] op_sel:[0,1,0]
	v_pk_fma_f32 v[130:131], v[66:67], v[214:215], v[130:131] op_sel:[0,1,0] neg_lo:[1,0,0] neg_hi:[1,0,0]
	v_pk_fma_f32 v[136:137], v[136:137], v[216:217], v[72:73] op_sel_hi:[1,0,1]
	v_pk_fma_f32 v[130:131], v[130:131], v[216:217], v[62:63] op_sel_hi:[1,0,1]
	v_pk_fma_f32 v[132:133], v[68:69], v[214:215], v[132:133] op_sel:[0,1,0]
	v_pk_fma_f32 v[122:123], v[86:87], v[178:179], v[122:123] op_sel:[0,1,0] neg_lo:[1,0,0] neg_hi:[1,0,0]
	v_pk_fma_f32 v[132:133], v[132:133], v[216:217], v[64:65] op_sel_hi:[1,0,1]
	v_pk_fma_f32 v[122:123], v[122:123], v[180:181], v[82:83] op_sel_hi:[1,0,1]
	v_pk_fma_f32 v[124:125], v[88:89], v[178:179], v[124:125] op_sel:[0,1,0]
	v_pk_fma_f32 v[118:119], v[74:75], v[178:179], v[118:119] op_sel:[0,1,0] neg_lo:[1,0,0] neg_hi:[1,0,0]
	v_pk_fma_f32 v[124:125], v[124:125], v[180:181], v[84:85] op_sel_hi:[1,0,1]
	v_pk_fma_f32 v[118:119], v[118:119], v[180:181], v[70:71] op_sel_hi:[1,0,1]
	v_pk_fma_f32 v[120:121], v[76:77], v[178:179], v[120:121] op_sel:[0,1,0]
	v_pk_fma_f32 v[114:115], v[66:67], v[178:179], v[114:115] op_sel:[0,1,0] neg_lo:[1,0,0] neg_hi:[1,0,0]
	v_pk_fma_f32 v[120:121], v[120:121], v[180:181], v[72:73] op_sel_hi:[1,0,1]
	v_pk_fma_f32 v[114:115], v[114:115], v[180:181], v[62:63] op_sel_hi:[1,0,1]
	v_pk_fma_f32 v[116:117], v[68:69], v[178:179], v[116:117] op_sel:[0,1,0]
	v_pk_fma_f32 v[106:107], v[86:87], v[170:171], v[106:107] op_sel:[0,1,0] neg_lo:[1,0,0] neg_hi:[1,0,0]
	v_pk_fma_f32 v[116:117], v[116:117], v[180:181], v[64:65] op_sel_hi:[1,0,1]
	v_pk_fma_f32 v[106:107], v[106:107], v[172:173], v[82:83] op_sel_hi:[1,0,1]
	v_pk_fma_f32 v[108:109], v[88:89], v[170:171], v[108:109] op_sel:[0,1,0]
	v_pk_fma_f32 v[102:103], v[74:75], v[170:171], v[102:103] op_sel:[0,1,0] neg_lo:[1,0,0] neg_hi:[1,0,0]
	v_pk_fma_f32 v[108:109], v[108:109], v[172:173], v[84:85] op_sel_hi:[1,0,1]
	v_pk_fma_f32 v[102:103], v[102:103], v[172:173], v[70:71] op_sel_hi:[1,0,1]
	v_pk_fma_f32 v[104:105], v[76:77], v[170:171], v[104:105] op_sel:[0,1,0]
	v_pk_fma_f32 v[98:99], v[66:67], v[170:171], v[98:99] op_sel:[0,1,0] neg_lo:[1,0,0] neg_hi:[1,0,0]
	v_pk_fma_f32 v[104:105], v[104:105], v[172:173], v[72:73] op_sel_hi:[1,0,1]
	v_pk_fma_f32 v[98:99], v[98:99], v[172:173], v[62:63] op_sel_hi:[1,0,1]
	v_pk_fma_f32 v[100:101], v[68:69], v[170:171], v[100:101] op_sel:[0,1,0]
	s_ashr_i32 s2, s9, 8
	v_pk_fma_f32 v[100:101], v[100:101], v[172:173], v[64:65] op_sel_hi:[1,0,1]
	s_mul_hi_i32 s9, s2, 0x160000
	s_mul_i32 s2, s2, 0x160000
	s_waitcnt vmcnt(6)
	v_permlane32_swap_b32_e32 v174, v162
	v_permlane32_swap_b32_e32 v175, v163
	v_permlane32_swap_b32_e32 v176, v164
	v_permlane32_swap_b32_e32 v177, v165
	v_permlane16_swap_b32_e32 v174, v162
	v_permlane16_swap_b32_e32 v175, v163
	v_permlane16_swap_b32_e32 v176, v164
	v_permlane16_swap_b32_e32 v177, v165
	v_mov_b32_e32 v168, v174
	v_mov_b32_e32 v169, v162
	v_mov_b32_e32 v182, v176
	v_mov_b32_e32 v183, v164
	v_pk_add_f32 v[168:169], v[168:169], v[182:183]
	v_mov_b32_e32 v162, v175
	v_pk_add_f32 v[168:169], v[168:169], v[168:169] op_sel:[0,1] op_sel_hi:[1,0]
	v_mov_b32_e32 v164, v177
	v_pk_add_f32 v[162:163], v[162:163], v[164:165]
	v_mov_b32_e32 v0, v168
	v_pk_add_f32 v[162:163], v[162:163], v[162:163] op_sel:[0,1] op_sel_hi:[1,0]
	s_nop 0
	v_permlane16_swap_b32_e32 v168, v0
	v_add_f32_e32 v163, v168, v0
	v_mov_b32_e32 v0, v162
	s_nop 1
	v_permlane16_swap_b32_e32 v162, v0
	v_add_f32_e32 v162, v162, v0
	v_mov_b32_e32 v165, v163
	v_mov_b32_e32 v164, v162
	s_nop 0
	v_permlane32_swap_b32_e32 v163, v165
	v_permlane32_swap_b32_e32 v162, v164
	v_pk_add_f32 v[162:163], v[162:163], v[164:165]
	s_waitcnt vmcnt(5)
; __device__ __forceinline__ float xsum16(float v) { const auto r = __builtin_amdgcn_permlane16_swap(__float_as_uint(v), __float_as_uint(v), false, false); return __uint_as_float(r[0]) + __uint_as_float(r[1]); }
; __device__ __forceinline__ float sigmoid_f(float x) { return fast_rcp(1.0f + fast_exp2(-1.4426950408889634f * x)); }
; __device__ __forceinline__ f32x4 silu_mul(const f32x4 g, const f32x4 u) { f32x4 r;
; #pragma unroll
;     for (int e = 0; e < 4; ++e) r[e] = g[e] * sigmoid_f(g[e]) * u[e];
;     return r; }
; __device__ __forceinline__ void row_stats4(const float* st, int rowb, int fq, float (&mu)[4], float (&rs)[4]) {
;     f32x4 a[4], b[4];
; #pragma unroll
;     for (int m = 0; m < 4; ++m) { const f32x4* p = (const f32x4*)(st + (size_t)(rowb + m * 16) * 32 + fq * 8); a[m] = p[0]; b[m] = p[1]; }
; #pragma unroll
;     for (int m = 0; m < 4; ++m) { float s1 = (a[m][0] + a[m][2]) + (b[m][0] + b[m][2]), s2 = (a[m][1] + a[m][3]) + (b[m][1] + b[m][3]);
;         s1 = xsum32(xsum16(s1)); s2 = xsum32(xsum16(s2));
;         const float mm = s1 * (1.0f / 1024.0f); mu[m] = mm; rs[m] = rsqrtf(fmaxf(s2 * (1.0f / 1024.0f) - mm * mm, 0.f) + LN_EPS_); }
;     asm volatile("" ::: "memory");
; }
;     __device__ __forceinline__ void operator()(const f32x4 (&acc)[2][2][4][2], const pg8::Unit& u, int wr, int wc, int fr, int fq) const {
;         const int row0 = u.pm * 256 + wr * 64 + fr, cl = wc * 32 + fq * 8, cB0 = u.pn * 256 + cl;
;         f32x4 g0[2], g1[2], b0[2], b1[2];
; #pragma unroll
;         for (int n = 0; n < 2; ++n) { g0[n] = *(const f32x4*)(gW + cB0 + 4 * n); g1[n] = *(const f32x4*)(gW + cB0 + 128 + 4 * n); b0[n] = *(const f32x4*)(bW + cB0 + 4 * n); b1[n] = *(const f32x4*)(bW + cB0 + 128 + 4 * n); }
;         float muA[4], rsA[4], muB[4], rsB[4]; row_stats4(st, row0, fq, muA, rsA); row_stats4(st, row0 + 128, fq, muB, rsB);
;         u32x4 ow[2][4];
; #pragma unroll
;         for (int ai = 0; ai < 2; ++ai)
; #pragma unroll
;             for (int m = 0; m < 4; ++m) { const float mu = ai ? muB[m] : muA[m], rs = ai ? rsB[m] : rsA[m]; f32x4 h[2];
; #pragma unroll
;                 for (int n = 0; n < 2; ++n) { const f32x4 zg = (acc[ai][0][m][n] - g0[n] * mu) * rs + b0[n], zu = (acc[ai][1][m][n] - g1[n] * mu) * rs + b1[n]; h[n] = silu_mul(zg, zu); }
;                 ow[ai][m] = pack8(h[0], h[1]); }
	v_mov_b32_e32 v164, v236
	v_pk_mul_f32 v[182:183], v[162:163], s[16:17] op_sel_hi:[1,0]
	s_waitcnt vmcnt(4)
	v_mov_b32_e32 v163, v238
	v_fma_f32 v0, -v183, v183, v182
	v_max_f32_e32 v0, 0, v0
	v_add_f32_e32 v0, 0x3727c5ac, v0
	v_cmp_gt_f32_e32 vcc, s11, v0
	v_mul_f32_e32 v162, 0x4b800000, v0
	v_mov_b32_e32 v165, v240
	v_cndmask_b32_e32 v0, v0, v162, vcc
	v_rsq_f32_e32 v0, v0
	v_mov_b32_e32 v238, v235
	v_mov_b32_e32 v240, v237
	s_waitcnt vmcnt(1)
	v_mov_b32_e32 v218, v188
	v_mul_f32_e32 v162, 0x45800000, v0
	v_cndmask_b32_e32 v184, v0, v162, vcc
	v_mov_b32_e32 v162, v234
	v_pk_add_f32 v[162:163], v[162:163], v[164:165]
	v_pk_add_f32 v[164:165], v[238:239], v[240:241]
	v_pk_add_f32 v[162:163], v[162:163], v[162:163] op_sel:[0,1] op_sel_hi:[1,0]
	v_pk_add_f32 v[164:165], v[164:165], v[164:165] op_sel:[0,1] op_sel_hi:[1,0]
	v_mov_b32_e32 v0, v162
	s_nop 1
	v_permlane16_swap_b32_e32 v162, v0
	v_add_f32_e32 v163, v162, v0
	v_mov_b32_e32 v0, v164
	s_nop 1
	v_permlane16_swap_b32_e32 v164, v0
	v_add_f32_e32 v162, v164, v0
	v_mov_b32_e32 v165, v163
	v_mov_b32_e32 v164, v162
	s_nop 0
	v_permlane32_swap_b32_e32 v163, v165
	v_permlane32_swap_b32_e32 v162, v164
	v_pk_add_f32 v[162:163], v[162:163], v[164:165]
	v_mov_b32_e32 v164, v244
	v_pk_mul_f32 v[174:175], v[162:163], s[16:17] op_sel_hi:[1,0]
	v_mov_b32_e32 v163, v246
	v_fma_f32 v0, -v175, v175, v174
	v_max_f32_e32 v0, 0, v0
	v_add_f32_e32 v0, 0x3727c5ac, v0
	v_cmp_gt_f32_e32 vcc, s11, v0
	v_mul_f32_e32 v162, 0x4b800000, v0
	v_mov_b32_e32 v165, v248
	v_cndmask_b32_e32 v0, v0, v162, vcc
	v_rsq_f32_e32 v0, v0
	v_mov_b32_e32 v246, v243
	v_mov_b32_e32 v248, v245
	s_waitcnt vmcnt(0)
	v_mov_b32_e32 v219, v192
	v_mul_f32_e32 v162, 0x45800000, v0
	v_cndmask_b32_e32 v176, v0, v162, vcc
	v_mov_b32_e32 v162, v242
	v_pk_add_f32 v[162:163], v[162:163], v[164:165]
	v_pk_add_f32 v[164:165], v[246:247], v[248:249]
	v_pk_add_f32 v[162:163], v[162:163], v[162:163] op_sel:[0,1] op_sel_hi:[1,0]
	v_pk_add_f32 v[164:165], v[164:165], v[164:165] op_sel:[0,1] op_sel_hi:[1,0]
	v_mov_b32_e32 v0, v162
	s_nop 1
	v_permlane16_swap_b32_e32 v162, v0
	v_add_f32_e32 v163, v162, v0
	v_mov_b32_e32 v0, v164
	s_nop 1
	v_permlane16_swap_b32_e32 v164, v0
	v_add_f32_e32 v162, v164, v0
	v_mov_b32_e32 v165, v163
	v_mov_b32_e32 v164, v162
	s_nop 0
	v_permlane32_swap_b32_e32 v163, v165
	v_permlane32_swap_b32_e32 v162, v164
	v_pk_add_f32 v[162:163], v[162:163], v[164:165]
	v_mov_b32_e32 v192, v189
	v_pk_mul_f32 v[164:165], v[162:163], s[16:17] op_sel_hi:[1,0]
	v_mov_b32_e32 v163, v190
	v_fma_f32 v0, -v165, v165, v164
	v_max_f32_e32 v0, 0, v0
	v_add_f32_e32 v0, 0x3727c5ac, v0
	v_cmp_gt_f32_e32 vcc, s11, v0
	v_mul_f32_e32 v162, 0x4b800000, v0
	v_mov_b32_e32 v190, v187
	v_cndmask_b32_e32 v0, v0, v162, vcc
	v_rsq_f32_e32 v0, v0
	v_pk_fma_f32 v[78:79], v[94:95], v[182:183], v[78:79] op_sel:[0,1,0] neg_lo:[1,0,0] neg_hi:[1,0,0]
	v_pk_fma_f32 v[58:59], v[86:87], v[182:183], v[58:59] op_sel:[0,1,0] neg_lo:[1,0,0] neg_hi:[1,0,0]
	v_pk_fma_f32 v[78:79], v[78:79], v[184:185], v[90:91] op_sel_hi:[1,0,1]
	v_mul_f32_e32 v162, 0x45800000, v0
	v_cndmask_b32_e32 v168, v0, v162, vcc
	v_mov_b32_e32 v162, v186
	v_pk_add_f32 v[162:163], v[162:163], v[218:219]
	v_pk_add_f32 v[186:187], v[190:191], v[192:193]
	v_pk_add_f32 v[162:163], v[162:163], v[162:163] op_sel:[0,1] op_sel_hi:[1,0]
	v_pk_add_f32 v[186:187], v[186:187], v[186:187] op_sel:[0,1] op_sel_hi:[1,0]
	v_mov_b32_e32 v0, v162
	s_nop 1
	v_permlane16_swap_b32_e32 v162, v0
	v_add_f32_e32 v163, v162, v0
	v_mov_b32_e32 v0, v186
	s_nop 1
	v_permlane16_swap_b32_e32 v186, v0
	v_add_f32_e32 v162, v186, v0
	v_mov_b32_e32 v187, v163
	v_mov_b32_e32 v186, v162
	s_nop 0
	v_permlane32_swap_b32_e32 v163, v187
	v_permlane32_swap_b32_e32 v162, v186
	v_pk_add_f32 v[162:163], v[162:163], v[186:187]
	v_pk_fma_f32 v[186:187], v[94:95], v[210:211], v[158:159] op_sel:[0,1,0] neg_lo:[1,0,0] neg_hi:[1,0,0]
	v_pk_mul_f32 v[162:163], v[162:163], s[16:17] op_sel_hi:[1,0]
	v_xor_b32_e32 v159, 0x80000000, v97
	v_fma_f32 v0, -v163, v163, v162
	v_max_f32_e32 v0, 0, v0
	v_add_f32_e32 v0, 0x3727c5ac, v0
	v_cmp_gt_f32_e32 vcc, s11, v0
	v_mul_f32_e32 v167, 0x4b800000, v0
	v_xor_b32_e32 v158, 0x80000000, v96
	v_cndmask_b32_e32 v0, v0, v167, vcc
	v_rsq_f32_e32 v0, v0
	v_pk_fma_f32 v[96:97], v[158:159], v[210:211], v[160:161] op_sel:[0,1,0]
	v_pk_fma_f32 v[160:161], v[186:187], v[212:213], v[90:91] op_sel_hi:[1,0,1]
	v_pk_fma_f32 v[96:97], v[96:97], v[212:213], v[92:93] op_sel_hi:[1,0,1]
	v_mul_f32_e32 v167, 0x45800000, v0
	v_cndmask_b32_e32 v0, v0, v167, vcc
	v_mul_f32_e32 v167, 0xbfb8aa3b, v160
	v_exp_f32_e32 v167, v167
	v_pk_fma_f32 v[80:81], v[158:159], v[182:183], v[80:81] op_sel:[0,1,0]
	v_pk_fma_f32 v[58:59], v[58:59], v[184:185], v[82:83] op_sel_hi:[1,0,1]
	v_pk_fma_f32 v[80:81], v[80:81], v[184:185], v[92:93] op_sel_hi:[1,0,1]
	v_add_f32_e32 v167, 1.0, v167
	v_rcp_f32_e32 v186, v167
	v_mul_f32_e32 v167, 0xbfb8aa3b, v161
	v_exp_f32_e32 v167, v167
	v_pk_fma_f32 v[60:61], v[88:89], v[182:183], v[60:61] op_sel:[0,1,0]
	v_pk_fma_f32 v[54:55], v[74:75], v[182:183], v[54:55] op_sel:[0,1,0] neg_lo:[1,0,0] neg_hi:[1,0,0]
	v_pk_fma_f32 v[60:61], v[60:61], v[184:185], v[84:85] op_sel_hi:[1,0,1]
	v_add_f32_e32 v167, 1.0, v167
	v_rcp_f32_e32 v187, v167
	v_pk_fma_f32 v[54:55], v[54:55], v[184:185], v[70:71] op_sel_hi:[1,0,1]
	v_pk_fma_f32 v[56:57], v[76:77], v[182:183], v[56:57] op_sel:[0,1,0]
	v_pk_fma_f32 v[50:51], v[66:67], v[182:183], v[50:51] op_sel:[0,1,0] neg_lo:[1,0,0] neg_hi:[1,0,0]
	v_pk_mul_f32 v[160:161], v[160:161], v[186:187]
	v_pk_fma_f32 v[56:57], v[56:57], v[184:185], v[72:73] op_sel_hi:[1,0,1]
	v_pk_mul_f32 v[154:155], v[154:155], v[160:161]
; __device__ __forceinline__ float xsum16(float v) { const auto r = __builtin_amdgcn_permlane16_swap(__float_as_uint(v), __float_as_uint(v), false, false); return __uint_as_float(r[0]) + __uint_as_float(r[1]); }
; __device__ __forceinline__ float sigmoid_f(float x) { return fast_rcp(1.0f + fast_exp2(-1.4426950408889634f * x)); }
; __device__ __forceinline__ f32x4 silu_mul(const f32x4 g, const f32x4 u) { f32x4 r;
; #pragma unroll
;     for (int e = 0; e < 4; ++e) r[e] = g[e] * sigmoid_f(g[e]) * u[e];
;     return r; }
; __device__ __forceinline__ void row_stats4(const float* st, int rowb, int fq, float (&mu)[4], float (&rs)[4]) {
;     f32x4 a[4], b[4];
; #pragma unroll
;     for (int m = 0; m < 4; ++m) { const f32x4* p = (const f32x4*)(st + (size_t)(rowb + m * 16) * 32 + fq * 8); a[m] = p[0]; b[m] = p[1]; }
; #pragma unroll
;     for (int m = 0; m < 4; ++m) { float s1 = (a[m][0] + a[m][2]) + (b[m][0] + b[m][2]), s2 = (a[m][1] + a[m][3]) + (b[m][1] + b[m][3]);
;         s1 = xsum32(xsum16(s1)); s2 = xsum32(xsum16(s2));
;         const float mm = s1 * (1.0f / 1024.0f); mu[m] = mm; rs[m] = rsqrtf(fmaxf(s2 * (1.0f / 1024.0f) - mm * mm, 0.f) + LN_EPS_); }
;     asm volatile("" ::: "memory");
; }
;     __device__ __forceinline__ void operator()(const f32x4 (&acc)[2][2][4][2], const pg8::Unit& u, int wr, int wc, int fr, int fq) const {
;         const int row0 = u.pm * 256 + wr * 64 + fr, cl = wc * 32 + fq * 8, cB0 = u.pn * 256 + cl;
;         f32x4 g0[2], g1[2], b0[2], b1[2];
; #pragma unroll
;         for (int n = 0; n < 2; ++n) { g0[n] = *(const f32x4*)(gW + cB0 + 4 * n); g1[n] = *(const f32x4*)(gW + cB0 + 128 + 4 * n); b0[n] = *(const f32x4*)(bW + cB0 + 4 * n); b1[n] = *(const f32x4*)(bW + cB0 + 128 + 4 * n); }
;         float muA[4], rsA[4], muB[4], rsB[4]; row_stats4(st, row0, fq, muA, rsA); row_stats4(st, row0 + 128, fq, muB, rsB);
;         u32x4 ow[2][4];
; #pragma unroll
;         for (int ai = 0; ai < 2; ++ai)
; #pragma unroll
;             for (int m = 0; m < 4; ++m) { const float mu = ai ? muB[m] : muA[m], rs = ai ? rsB[m] : rsA[m]; f32x4 h[2];
; #pragma unroll
;                 for (int n = 0; n < 2; ++n) { const f32x4 zg = (acc[ai][0][m][n] - g0[n] * mu) * rs + b0[n], zu = (acc[ai][1][m][n] - g1[n] * mu) * rs + b1[n]; h[n] = silu_mul(zg, zu); }
;                 ow[ai][m] = pack8(h[0], h[1]); }
	v_mul_f32_e32 v160, 0xbfb8aa3b, v96
	v_mul_f32_e32 v161, 0xbfb8aa3b, v97
	v_exp_f32_e32 v160, v160
	v_exp_f32_e32 v161, v161
	v_pk_fma_f32 v[50:51], v[50:51], v[184:185], v[62:63] op_sel_hi:[1,0,1]
	v_pk_fma_f32 v[52:53], v[68:69], v[182:183], v[52:53] op_sel:[0,1,0]
	v_add_f32_e32 v160, 1.0, v160
	v_add_f32_e32 v161, 1.0, v161
	v_rcp_f32_e32 v160, v160
	v_rcp_f32_e32 v161, v161
	v_pk_fma_f32 v[46:47], v[94:95], v[174:175], v[46:47] op_sel:[0,1,0] neg_lo:[1,0,0] neg_hi:[1,0,0]
	v_pk_fma_f32 v[52:53], v[52:53], v[184:185], v[64:65] op_sel_hi:[1,0,1]
	v_pk_fma_f32 v[46:47], v[46:47], v[176:177], v[90:91] op_sel_hi:[1,0,1]
	v_pk_mul_f32 v[96:97], v[96:97], v[160:161]
	v_pk_fma_f32 v[48:49], v[158:159], v[174:175], v[48:49] op_sel:[0,1,0]
	v_pk_mul_f32 v[96:97], v[156:157], v[96:97]
	v_mul_f32_e32 v156, 0xbfb8aa3b, v150
	v_mul_f32_e32 v157, 0xbfb8aa3b, v151
	v_exp_f32_e32 v156, v156
	v_exp_f32_e32 v157, v157
	v_pk_fma_f32 v[42:43], v[86:87], v[174:175], v[42:43] op_sel:[0,1,0] neg_lo:[1,0,0] neg_hi:[1,0,0]
	v_pk_fma_f32 v[48:49], v[48:49], v[176:177], v[92:93] op_sel_hi:[1,0,1]
	v_add_f32_e32 v156, 1.0, v156
	v_add_f32_e32 v157, 1.0, v157
	v_rcp_f32_e32 v156, v156
	v_rcp_f32_e32 v157, v157
	v_pk_fma_f32 v[42:43], v[42:43], v[176:177], v[82:83] op_sel_hi:[1,0,1]
	v_pk_fma_f32 v[44:45], v[88:89], v[174:175], v[44:45] op_sel:[0,1,0]
	v_pk_fma_f32 v[38:39], v[74:75], v[174:175], v[38:39] op_sel:[0,1,0] neg_lo:[1,0,0] neg_hi:[1,0,0]
	v_pk_mul_f32 v[150:151], v[150:151], v[156:157]
	v_pk_fma_f32 v[44:45], v[44:45], v[176:177], v[84:85] op_sel_hi:[1,0,1]
	v_pk_mul_f32 v[150:151], v[146:147], v[150:151]
	v_mul_f32_e32 v146, 0xbfb8aa3b, v152
	v_mul_f32_e32 v147, 0xbfb8aa3b, v153
	v_exp_f32_e32 v146, v146
	v_exp_f32_e32 v147, v147
	v_pk_fma_f32 v[38:39], v[38:39], v[176:177], v[70:71] op_sel_hi:[1,0,1]
	v_pk_fma_f32 v[40:41], v[76:77], v[174:175], v[40:41] op_sel:[0,1,0]
	v_add_f32_e32 v146, 1.0, v146
	v_add_f32_e32 v147, 1.0, v147
	v_rcp_f32_e32 v146, v146
	v_rcp_f32_e32 v147, v147
	v_pk_fma_f32 v[34:35], v[66:67], v[174:175], v[34:35] op_sel:[0,1,0] neg_lo:[1,0,0] neg_hi:[1,0,0]
	v_pk_fma_f32 v[40:41], v[40:41], v[176:177], v[72:73] op_sel_hi:[1,0,1]
	v_pk_fma_f32 v[34:35], v[34:35], v[176:177], v[62:63] op_sel_hi:[1,0,1]
	v_pk_mul_f32 v[146:147], v[152:153], v[146:147]
	v_pk_fma_f32 v[36:37], v[68:69], v[174:175], v[36:37] op_sel:[0,1,0]
	v_pk_mul_f32 v[152:153], v[148:149], v[146:147]
	v_cvt_pk_bf16_f32 v147, v96, v97
	v_pk_fma_f32 v[96:97], v[94:95], v[214:215], v[142:143] op_sel:[0,1,0] neg_lo:[1,0,0] neg_hi:[1,0,0]
	v_pk_fma_f32 v[142:143], v[158:159], v[214:215], v[144:145] op_sel:[0,1,0]
	v_pk_fma_f32 v[96:97], v[96:97], v[216:217], v[90:91] op_sel_hi:[1,0,1]
	v_pk_fma_f32 v[142:143], v[142:143], v[216:217], v[92:93] op_sel_hi:[1,0,1]
	v_mul_f32_e32 v144, 0xbfb8aa3b, v96
	v_mul_f32_e32 v145, 0xbfb8aa3b, v97
	v_exp_f32_e32 v144, v144
	v_exp_f32_e32 v145, v145
	v_pk_fma_f32 v[30:31], v[94:95], v[164:165], v[30:31] op_sel:[0,1,0] neg_lo:[1,0,0] neg_hi:[1,0,0]
	v_pk_fma_f32 v[36:37], v[36:37], v[176:177], v[64:65] op_sel_hi:[1,0,1]
	v_add_f32_e32 v144, 1.0, v144
	v_add_f32_e32 v145, 1.0, v145
	v_rcp_f32_e32 v144, v144
	v_rcp_f32_e32 v145, v145
	v_pk_fma_f32 v[30:31], v[30:31], v[168:169], v[90:91] op_sel_hi:[1,0,1]
	v_pk_fma_f32 v[32:33], v[158:159], v[164:165], v[32:33] op_sel:[0,1,0]
	v_pk_fma_f32 v[26:27], v[86:87], v[164:165], v[26:27] op_sel:[0,1,0] neg_lo:[1,0,0] neg_hi:[1,0,0]
	v_pk_mul_f32 v[96:97], v[96:97], v[144:145]
	v_pk_fma_f32 v[32:33], v[32:33], v[168:169], v[92:93] op_sel_hi:[1,0,1]
	v_pk_mul_f32 v[96:97], v[138:139], v[96:97]
	v_mul_f32_e32 v138, 0xbfb8aa3b, v142
	v_mul_f32_e32 v139, 0xbfb8aa3b, v143
	v_exp_f32_e32 v138, v138
	v_exp_f32_e32 v139, v139
	v_pk_fma_f32 v[26:27], v[26:27], v[168:169], v[82:83] op_sel_hi:[1,0,1]
	v_pk_fma_f32 v[28:29], v[88:89], v[164:165], v[28:29] op_sel:[0,1,0]
	v_add_f32_e32 v138, 1.0, v138
	v_add_f32_e32 v139, 1.0, v139
	v_rcp_f32_e32 v138, v138
	v_rcp_f32_e32 v139, v139
	v_pk_fma_f32 v[22:23], v[74:75], v[164:165], v[22:23] op_sel:[0,1,0] neg_lo:[1,0,0] neg_hi:[1,0,0]
	v_pk_fma_f32 v[28:29], v[28:29], v[168:169], v[84:85] op_sel_hi:[1,0,1]
	v_pk_fma_f32 v[22:23], v[22:23], v[168:169], v[70:71] op_sel_hi:[1,0,1]
	v_pk_mul_f32 v[138:139], v[142:143], v[138:139]
	v_pk_fma_f32 v[24:25], v[76:77], v[164:165], v[24:25] op_sel:[0,1,0]
	v_pk_mul_f32 v[138:139], v[140:141], v[138:139]
	v_mul_f32_e32 v140, 0xbfb8aa3b, v134
	v_mul_f32_e32 v141, 0xbfb8aa3b, v135
	v_exp_f32_e32 v140, v140
	v_exp_f32_e32 v141, v141
	v_pk_fma_f32 v[18:19], v[66:67], v[164:165], v[18:19] op_sel:[0,1,0] neg_lo:[1,0,0] neg_hi:[1,0,0]
	v_pk_fma_f32 v[24:25], v[24:25], v[168:169], v[72:73] op_sel_hi:[1,0,1]
	v_add_f32_e32 v140, 1.0, v140
	v_add_f32_e32 v141, 1.0, v141
	v_rcp_f32_e32 v140, v140
	v_rcp_f32_e32 v141, v141
	v_pk_fma_f32 v[18:19], v[18:19], v[168:169], v[62:63] op_sel_hi:[1,0,1]
	v_pk_fma_f32 v[20:21], v[68:69], v[164:165], v[20:21] op_sel:[0,1,0]
	v_pk_fma_f32 v[14:15], v[94:95], v[162:163], v[14:15] op_sel:[0,1,0] neg_lo:[1,0,0] neg_hi:[1,0,0]
	v_pk_mul_f32 v[134:135], v[134:135], v[140:141]
	v_pk_fma_f32 v[20:21], v[20:21], v[168:169], v[64:65] op_sel_hi:[1,0,1]
	v_pk_mul_f32 v[134:135], v[130:131], v[134:135]
	v_mul_f32_e32 v130, 0xbfb8aa3b, v136
	v_mul_f32_e32 v131, 0xbfb8aa3b, v137
	v_exp_f32_e32 v130, v130
	v_exp_f32_e32 v131, v131
	v_pk_fma_f32 v[14:15], v[14:15], v[0:1], v[90:91] op_sel_hi:[1,0,1]
	v_pk_fma_f32 v[16:17], v[158:159], v[162:163], v[16:17] op_sel:[0,1,0]
	v_add_f32_e32 v130, 1.0, v130
	v_add_f32_e32 v131, 1.0, v131
	v_rcp_f32_e32 v130, v130
	v_rcp_f32_e32 v131, v131
; __device__ __forceinline__ u32x4 pack8(const f32x4 a, const f32x4 b) { u32x4 w; w.x = cvt_pk_bf16(a[0], a[1]); w.y = cvt_pk_bf16(a[2], a[3]); w.z = cvt_pk_bf16(b[0], b[1]); w.w = cvt_pk_bf16(b[2], b[3]); return w; }
; __device__ __forceinline__ void unpack8(const u32x4 w, f32x4& a, f32x4& b) {
;     a[0] = __uint_as_float(w.x << 16); a[1] = __uint_as_float(w.x & 0xffff0000u); a[2] = __uint_as_float(w.y << 16); a[3] = __uint_as_float(w.y & 0xffff0000u);
;     b[0] = __uint_as_float(w.z << 16); b[1] = __uint_as_float(w.z & 0xffff0000u); b[2] = __uint_as_float(w.w << 16); b[3] = __uint_as_float(w.w & 0xffff0000u); }
; __device__ __forceinline__ f32x4 silu_mul(const f32x4 g, const f32x4 u) { f32x4 r;
; #pragma unroll
;     for (int e = 0; e < 4; ++e) r[e] = g[e] * sigmoid_f(g[e]) * u[e];
;     return r; }
; __device__ __forceinline__ void row_stats4(const float* st, int rowb, int fq, float (&mu)[4], float (&rs)[4]) {
;     f32x4 a[4], b[4];
; #pragma unroll
;     for (int m = 0; m < 4; ++m) { const f32x4* p = (const f32x4*)(st + (size_t)(rowb + m * 16) * 32 + fq * 8); a[m] = p[0]; b[m] = p[1]; }
; #pragma unroll
;     for (int m = 0; m < 4; ++m) { float s1 = (a[m][0] + a[m][2]) + (b[m][0] + b[m][2]), s2 = (a[m][1] + a[m][3]) + (b[m][1] + b[m][3]);
;         s1 = xsum32(xsum16(s1)); s2 = xsum32(xsum16(s2));
;         const float mm = s1 * (1.0f / 1024.0f); mu[m] = mm; rs[m] = rsqrtf(fmaxf(s2 * (1.0f / 1024.0f) - mm * mm, 0.f) + LN_EPS_); }
;     asm volatile("" ::: "memory");
; }
;     __device__ __forceinline__ void operator()(const f32x4 (&acc)[2][2][4][2], const pg8::Unit& u, int wr, int wc, int fr, int fq) const {
;         const int row0 = u.pm * 256 + wr * 64 + fr, cl = wc * 32 + fq * 8, cB0 = u.pn * 256 + cl;
;         f32x4 g0[2], g1[2], b0[2], b1[2];
; #pragma unroll
;         for (int n = 0; n < 2; ++n) { g0[n] = *(const f32x4*)(gW + cB0 + 4 * n); g1[n] = *(const f32x4*)(gW + cB0 + 128 + 4 * n); b0[n] = *(const f32x4*)(bW + cB0 + 4 * n); b1[n] = *(const f32x4*)(bW + cB0 + 128 + 4 * n); }
;         float muA[4], rsA[4], muB[4], rsB[4]; row_stats4(st, row0, fq, muA, rsA); row_stats4(st, row0 + 128, fq, muB, rsB);
;         u32x4 ow[2][4];
; #pragma unroll
;         for (int ai = 0; ai < 2; ++ai)
; #pragma unroll
;             for (int m = 0; m < 4; ++m) { const float mu = ai ? muB[m] : muA[m], rs = ai ? rsB[m] : rsA[m]; f32x4 h[2];
; #pragma unroll
	v_pk_fma_f32 v[10:11], v[86:87], v[162:163], v[10:11] op_sel:[0,1,0] neg_lo:[1,0,0] neg_hi:[1,0,0]
	v_pk_fma_f32 v[16:17], v[16:17], v[0:1], v[92:93] op_sel_hi:[1,0,1]
	v_pk_fma_f32 v[10:11], v[10:11], v[0:1], v[82:83] op_sel_hi:[1,0,1]
	v_pk_mul_f32 v[130:131], v[136:137], v[130:131]
	v_pk_fma_f32 v[6:7], v[74:75], v[162:163], v[6:7] op_sel:[0,1,0] neg_lo:[1,0,0] neg_hi:[1,0,0]
	v_pk_mul_f32 v[136:137], v[132:133], v[130:131]
	v_cvt_pk_bf16_f32 v130, v96, v97
	v_pk_fma_f32 v[96:97], v[94:95], v[178:179], v[126:127] op_sel:[0,1,0] neg_lo:[1,0,0] neg_hi:[1,0,0]
	v_pk_fma_f32 v[126:127], v[158:159], v[178:179], v[128:129] op_sel:[0,1,0]
	v_pk_fma_f32 v[96:97], v[96:97], v[180:181], v[90:91] op_sel_hi:[1,0,1]
	v_pk_fma_f32 v[126:127], v[126:127], v[180:181], v[92:93] op_sel_hi:[1,0,1]
	v_mul_f32_e32 v128, 0xbfb8aa3b, v96
	v_mul_f32_e32 v129, 0xbfb8aa3b, v97
	v_exp_f32_e32 v128, v128
	v_exp_f32_e32 v129, v129
	v_pk_fma_f32 v[12:13], v[88:89], v[162:163], v[12:13] op_sel:[0,1,0]
	v_pk_fma_f32 v[8:9], v[76:77], v[162:163], v[8:9] op_sel:[0,1,0]
	v_add_f32_e32 v128, 1.0, v128
	v_add_f32_e32 v129, 1.0, v129
	v_rcp_f32_e32 v128, v128
	v_rcp_f32_e32 v129, v129
	v_pk_fma_f32 v[6:7], v[6:7], v[0:1], v[70:71] op_sel_hi:[1,0,1]
	v_pk_fma_f32 v[2:3], v[66:67], v[162:163], v[2:3] op_sel:[0,1,0] neg_lo:[1,0,0] neg_hi:[1,0,0]
	v_pk_fma_f32 v[4:5], v[68:69], v[162:163], v[4:5] op_sel:[0,1,0]
	v_pk_mul_f32 v[96:97], v[96:97], v[128:129]
	v_pk_fma_f32 v[12:13], v[12:13], v[0:1], v[84:85] op_sel_hi:[1,0,1]
	v_pk_mul_f32 v[96:97], v[122:123], v[96:97]
	v_mul_f32_e32 v122, 0xbfb8aa3b, v126
	v_mul_f32_e32 v123, 0xbfb8aa3b, v127
	v_exp_f32_e32 v122, v122
	v_exp_f32_e32 v123, v123
	v_pk_fma_f32 v[8:9], v[8:9], v[0:1], v[72:73] op_sel_hi:[1,0,1]
	v_pk_fma_f32 v[4:5], v[4:5], v[0:1], v[64:65] op_sel_hi:[1,0,1]
	v_add_f32_e32 v122, 1.0, v122
	v_add_f32_e32 v123, 1.0, v123
	v_rcp_f32_e32 v122, v122
	v_rcp_f32_e32 v123, v123
	v_pk_fma_f32 v[2:3], v[2:3], v[0:1], v[62:63] op_sel_hi:[1,0,1]
	v_mul_f32_e32 v0, 0xbfb8aa3b, v6
	v_exp_f32_e32 v0, v0
	v_pk_mul_f32 v[122:123], v[126:127], v[122:123]
	s_lshl_b32 s11, s44, 7
	v_pk_mul_f32 v[122:123], v[124:125], v[122:123]
	v_mul_f32_e32 v124, 0xbfb8aa3b, v118
	v_mul_f32_e32 v125, 0xbfb8aa3b, v119
	v_exp_f32_e32 v124, v124
	v_exp_f32_e32 v125, v125
	v_add_f32_e32 v0, 1.0, v0
	s_or_b32 s11, s11, s22
	v_add_f32_e32 v124, 1.0, v124
	v_add_f32_e32 v125, 1.0, v125
	v_rcp_f32_e32 v124, v124
	v_rcp_f32_e32 v125, v125
	s_ashr_i32 s16, s11, 6
	s_ashr_i32 s17, s16, 31
	s_add_u32 s2, s30, s2
	v_pk_mul_f32 v[118:119], v[118:119], v[124:125]
	s_addc_u32 s9, s31, s9
	v_pk_mul_f32 v[118:119], v[114:115], v[118:119]
	v_mul_f32_e32 v114, 0xbfb8aa3b, v120
	v_mul_f32_e32 v115, 0xbfb8aa3b, v121
	v_exp_f32_e32 v114, v114
	v_exp_f32_e32 v115, v115
	s_lshl_b64 s[16:17], s[16:17], 15
	s_add_u32 s28, s2, s16
	v_add_f32_e32 v114, 1.0, v114
	v_add_f32_e32 v115, 1.0, v115
	v_rcp_f32_e32 v114, v114
	v_rcp_f32_e32 v115, v115
	s_addc_u32 s29, s9, s17
	s_movk_i32 s2, 0x1000
	v_cvt_pk_bf16_f32 v146, v154, v155
	v_pk_mul_f32 v[114:115], v[120:121], v[114:115]
	v_cvt_pk_bf16_f32 v148, v150, v151
	v_pk_mul_f32 v[120:121], v[116:117], v[114:115]
	v_cvt_pk_bf16_f32 v114, v96, v97
	v_pk_fma_f32 v[96:97], v[94:95], v[170:171], v[110:111] op_sel:[0,1,0] neg_lo:[1,0,0] neg_hi:[1,0,0]
	v_pk_fma_f32 v[110:111], v[158:159], v[170:171], v[112:113] op_sel:[0,1,0]
	v_pk_fma_f32 v[96:97], v[96:97], v[172:173], v[90:91] op_sel_hi:[1,0,1]
	v_pk_fma_f32 v[110:111], v[110:111], v[172:173], v[92:93] op_sel_hi:[1,0,1]
	v_mul_f32_e32 v112, 0xbfb8aa3b, v96
	v_mul_f32_e32 v113, 0xbfb8aa3b, v97
	v_exp_f32_e32 v112, v112
	v_exp_f32_e32 v113, v113
	v_cvt_pk_bf16_f32 v149, v152, v153
	v_cvt_pk_bf16_f32 v115, v122, v123
	v_add_f32_e32 v112, 1.0, v112
	v_add_f32_e32 v113, 1.0, v113
	v_rcp_f32_e32 v112, v112
	v_rcp_f32_e32 v113, v113
	v_cvt_pk_bf16_f32 v116, v118, v119
	v_cvt_pk_bf16_f32 v117, v120, v121
	v_cvt_pk_bf16_f32 v131, v138, v139
	v_pk_mul_f32 v[96:97], v[96:97], v[112:113]
	v_cvt_pk_bf16_f32 v132, v134, v135
	v_pk_mul_f32 v[96:97], v[106:107], v[96:97]
	v_mul_f32_e32 v106, 0xbfb8aa3b, v110
	v_mul_f32_e32 v107, 0xbfb8aa3b, v111
	v_exp_f32_e32 v106, v106
	v_exp_f32_e32 v107, v107
	v_cvt_pk_bf16_f32 v133, v136, v137
	v_cvt_pk_bf16_f32 v96, v96, v97
	v_add_f32_e32 v106, 1.0, v106
	v_add_f32_e32 v107, 1.0, v107
	v_rcp_f32_e32 v106, v106
	v_rcp_f32_e32 v107, v107
	s_nop 0
	v_pk_mul_f32 v[106:107], v[110:111], v[106:107]
	s_nop 0
	v_pk_mul_f32 v[106:107], v[108:109], v[106:107]
	v_mul_f32_e32 v108, 0xbfb8aa3b, v102
	v_mul_f32_e32 v109, 0xbfb8aa3b, v103
	v_exp_f32_e32 v108, v108
	v_exp_f32_e32 v109, v109
	v_cvt_pk_bf16_f32 v97, v106, v107
	v_add_f32_e32 v108, 1.0, v108
	v_add_f32_e32 v109, 1.0, v109
	v_rcp_f32_e32 v108, v108
	v_rcp_f32_e32 v109, v109
	s_nop 0
	v_pk_mul_f32 v[102:103], v[102:103], v[108:109]
	s_nop 0
	v_pk_mul_f32 v[98:99], v[98:99], v[102:103]
	v_mul_f32_e32 v102, 0xbfb8aa3b, v104
	v_mul_f32_e32 v103, 0xbfb8aa3b, v105
	v_exp_f32_e32 v102, v102
	v_exp_f32_e32 v103, v103
	v_cvt_pk_bf16_f32 v98, v98, v99
	v_add_f32_e32 v102, 1.0, v102
	v_add_f32_e32 v103, 1.0, v103
	v_rcp_f32_e32 v102, v102
	v_rcp_f32_e32 v103, v103
	s_nop 0
	v_pk_mul_f32 v[102:103], v[104:105], v[102:103]
	s_nop 0
	v_pk_mul_f32 v[100:101], v[100:101], v[102:103]
	s_nop 0
	v_cvt_pk_bf16_f32 v99, v100, v101
	v_mul_f32_e32 v100, 0xbfb8aa3b, v78
	v_mul_f32_e32 v101, 0xbfb8aa3b, v79
	v_exp_f32_e32 v100, v100
	v_exp_f32_e32 v101, v101
	v_add_f32_e32 v100, 1.0, v100
	v_add_f32_e32 v101, 1.0, v101
	v_rcp_f32_e32 v100, v100
	v_rcp_f32_e32 v101, v101
	s_nop 0
	v_pk_mul_f32 v[78:79], v[78:79], v[100:101]
	s_nop 0
; __device__ __forceinline__ u32x4 pack8(const f32x4 a, const f32x4 b) { u32x4 w; w.x = cvt_pk_bf16(a[0], a[1]); w.y = cvt_pk_bf16(a[2], a[3]); w.z = cvt_pk_bf16(b[0], b[1]); w.w = cvt_pk_bf16(b[2], b[3]); return w; }
; __device__ __forceinline__ void unpack8(const u32x4 w, f32x4& a, f32x4& b) {
;     a[0] = __uint_as_float(w.x << 16); a[1] = __uint_as_float(w.x & 0xffff0000u); a[2] = __uint_as_float(w.y << 16); a[3] = __uint_as_float(w.y & 0xffff0000u);
;     b[0] = __uint_as_float(w.z << 16); b[1] = __uint_as_float(w.z & 0xffff0000u); b[2] = __uint_as_float(w.w << 16); b[3] = __uint_as_float(w.w & 0xffff0000u); }
; __device__ __forceinline__ f32x4 silu_mul(const f32x4 g, const f32x4 u) { f32x4 r;
; #pragma unroll
;     for (int e = 0; e < 4; ++e) r[e] = g[e] * sigmoid_f(g[e]) * u[e];
;     return r; }
; __device__ __forceinline__ void row_stats4(const float* st, int rowb, int fq, float (&mu)[4], float (&rs)[4]) {
;     f32x4 a[4], b[4];
; #pragma unroll
;     for (int m = 0; m < 4; ++m) { const f32x4* p = (const f32x4*)(st + (size_t)(rowb + m * 16) * 32 + fq * 8); a[m] = p[0]; b[m] = p[1]; }
; #pragma unroll
;     for (int m = 0; m < 4; ++m) { float s1 = (a[m][0] + a[m][2]) + (b[m][0] + b[m][2]), s2 = (a[m][1] + a[m][3]) + (b[m][1] + b[m][3]);
;         s1 = xsum32(xsum16(s1)); s2 = xsum32(xsum16(s2));
;         const float mm = s1 * (1.0f / 1024.0f); mu[m] = mm; rs[m] = rsqrtf(fmaxf(s2 * (1.0f / 1024.0f) - mm * mm, 0.f) + LN_EPS_); }
;     asm volatile("" ::: "memory");
; }
;     __device__ __forceinline__ void operator()(const f32x4 (&acc)[2][2][4][2], const pg8::Unit& u, int wr, int wc, int fr, int fq) const {
;         const int row0 = u.pm * 256 + wr * 64 + fr, cl = wc * 32 + fq * 8, cB0 = u.pn * 256 + cl;
;         f32x4 g0[2], g1[2], b0[2], b1[2];
; #pragma unroll
;         for (int n = 0; n < 2; ++n) { g0[n] = *(const f32x4*)(gW + cB0 + 4 * n); g1[n] = *(const f32x4*)(gW + cB0 + 128 + 4 * n); b0[n] = *(const f32x4*)(bW + cB0 + 4 * n); b1[n] = *(const f32x4*)(bW + cB0 + 128 + 4 * n); }
;         float muA[4], rsA[4], muB[4], rsB[4]; row_stats4(st, row0, fq, muA, rsA); row_stats4(st, row0 + 128, fq, muB, rsB);
;         u32x4 ow[2][4];
; #pragma unroll
;         for (int ai = 0; ai < 2; ++ai)
; #pragma unroll
;             for (int m = 0; m < 4; ++m) { const float mu = ai ? muB[m] : muA[m], rs = ai ? rsB[m] : rsA[m]; f32x4 h[2];
; #pragma unroll
	v_pk_mul_f32 v[58:59], v[58:59], v[78:79]
	v_mul_f32_e32 v78, 0xbfb8aa3b, v80
	v_mul_f32_e32 v79, 0xbfb8aa3b, v81
	v_exp_f32_e32 v78, v78
	v_exp_f32_e32 v79, v79
	v_add_f32_e32 v78, 1.0, v78
	v_add_f32_e32 v79, 1.0, v79
	v_rcp_f32_e32 v78, v78
	v_rcp_f32_e32 v79, v79
	s_nop 0
	v_pk_mul_f32 v[78:79], v[80:81], v[78:79]
	s_nop 0
	v_pk_mul_f32 v[60:61], v[60:61], v[78:79]
	v_mul_f32_e32 v78, 0xbfb8aa3b, v54
	v_mul_f32_e32 v79, 0xbfb8aa3b, v55
	v_exp_f32_e32 v78, v78
	v_exp_f32_e32 v79, v79
	v_add_f32_e32 v78, 1.0, v78
	v_add_f32_e32 v79, 1.0, v79
	v_rcp_f32_e32 v78, v78
	v_rcp_f32_e32 v79, v79
	s_nop 0
	v_pk_mul_f32 v[54:55], v[54:55], v[78:79]
	s_nop 0
	v_pk_mul_f32 v[54:55], v[50:51], v[54:55]
	v_mul_f32_e32 v50, 0xbfb8aa3b, v56
	v_mul_f32_e32 v51, 0xbfb8aa3b, v57
	v_exp_f32_e32 v50, v50
	v_exp_f32_e32 v51, v51
	v_add_f32_e32 v50, 1.0, v50
	v_add_f32_e32 v51, 1.0, v51
	v_rcp_f32_e32 v50, v50
	v_rcp_f32_e32 v51, v51
	s_nop 0
	v_pk_mul_f32 v[50:51], v[56:57], v[50:51]
	s_nop 0
	v_pk_mul_f32 v[56:57], v[52:53], v[50:51]
	v_cvt_pk_bf16_f32 v52, v54, v55
	v_mul_f32_e32 v54, 0xbfb8aa3b, v46
	v_mul_f32_e32 v55, 0xbfb8aa3b, v47
	v_exp_f32_e32 v54, v54
	v_exp_f32_e32 v55, v55
	v_cvt_pk_bf16_f32 v50, v58, v59
	v_cvt_pk_bf16_f32 v51, v60, v61
	v_add_f32_e32 v54, 1.0, v54
	v_add_f32_e32 v55, 1.0, v55
	v_rcp_f32_e32 v54, v54
	v_rcp_f32_e32 v55, v55
	v_cvt_pk_bf16_f32 v53, v56, v57
	v_pk_mul_f32 v[46:47], v[46:47], v[54:55]
	s_nop 0
	v_pk_mul_f32 v[42:43], v[42:43], v[46:47]
	v_mul_f32_e32 v46, 0xbfb8aa3b, v48
	v_mul_f32_e32 v47, 0xbfb8aa3b, v49
	v_exp_f32_e32 v46, v46
	v_exp_f32_e32 v47, v47
	v_add_f32_e32 v46, 1.0, v46
	v_add_f32_e32 v47, 1.0, v47
	v_rcp_f32_e32 v46, v46
	v_rcp_f32_e32 v47, v47
	s_nop 0
	v_pk_mul_f32 v[46:47], v[48:49], v[46:47]
	s_nop 0
	v_pk_mul_f32 v[44:45], v[44:45], v[46:47]
	v_mul_f32_e32 v46, 0xbfb8aa3b, v38
	v_mul_f32_e32 v47, 0xbfb8aa3b, v39
	v_exp_f32_e32 v46, v46
	v_exp_f32_e32 v47, v47
	v_add_f32_e32 v46, 1.0, v46
	v_add_f32_e32 v47, 1.0, v47
	v_rcp_f32_e32 v46, v46
	v_rcp_f32_e32 v47, v47
	s_nop 0
	v_pk_mul_f32 v[38:39], v[38:39], v[46:47]
	s_nop 0
	v_pk_mul_f32 v[38:39], v[34:35], v[38:39]
	v_mul_f32_e32 v34, 0xbfb8aa3b, v40
	v_mul_f32_e32 v35, 0xbfb8aa3b, v41
	v_exp_f32_e32 v34, v34
	v_exp_f32_e32 v35, v35
	v_add_f32_e32 v34, 1.0, v34
	v_add_f32_e32 v35, 1.0, v35
	v_rcp_f32_e32 v34, v34
	v_rcp_f32_e32 v35, v35
	s_nop 0
	v_pk_mul_f32 v[34:35], v[40:41], v[34:35]
	s_nop 0
	v_pk_mul_f32 v[40:41], v[36:37], v[34:35]
	v_cvt_pk_bf16_f32 v36, v38, v39
	v_mul_f32_e32 v38, 0xbfb8aa3b, v30
	v_mul_f32_e32 v39, 0xbfb8aa3b, v31
	v_exp_f32_e32 v38, v38
	v_exp_f32_e32 v39, v39
	v_cvt_pk_bf16_f32 v34, v42, v43
	v_cvt_pk_bf16_f32 v35, v44, v45
	v_add_f32_e32 v38, 1.0, v38
	v_add_f32_e32 v39, 1.0, v39
	v_rcp_f32_e32 v38, v38
	v_rcp_f32_e32 v39, v39
	v_cvt_pk_bf16_f32 v37, v40, v41
	v_pk_mul_f32 v[30:31], v[30:31], v[38:39]
	s_nop 0
	v_pk_mul_f32 v[26:27], v[26:27], v[30:31]
	v_mul_f32_e32 v30, 0xbfb8aa3b, v32
	v_mul_f32_e32 v31, 0xbfb8aa3b, v33
	v_exp_f32_e32 v30, v30
	v_exp_f32_e32 v31, v31
	v_add_f32_e32 v30, 1.0, v30
	v_add_f32_e32 v31, 1.0, v31
	v_rcp_f32_e32 v30, v30
	v_rcp_f32_e32 v31, v31
	s_nop 0
	v_pk_mul_f32 v[30:31], v[32:33], v[30:31]
	s_nop 0
	v_pk_mul_f32 v[28:29], v[28:29], v[30:31]
	v_mul_f32_e32 v30, 0xbfb8aa3b, v22
	v_mul_f32_e32 v31, 0xbfb8aa3b, v23
	v_exp_f32_e32 v30, v30
	v_exp_f32_e32 v31, v31
	v_add_f32_e32 v30, 1.0, v30
	v_add_f32_e32 v31, 1.0, v31
	v_rcp_f32_e32 v30, v30
	v_rcp_f32_e32 v31, v31
	s_nop 0
	v_pk_mul_f32 v[22:23], v[22:23], v[30:31]
	s_nop 0
	v_pk_mul_f32 v[22:23], v[18:19], v[22:23]
	v_mul_f32_e32 v18, 0xbfb8aa3b, v24
	v_mul_f32_e32 v19, 0xbfb8aa3b, v25
	v_exp_f32_e32 v18, v18
	v_exp_f32_e32 v19, v19
	v_add_f32_e32 v18, 1.0, v18
	v_add_f32_e32 v19, 1.0, v19
	v_rcp_f32_e32 v18, v18
	v_rcp_f32_e32 v19, v19
	s_nop 0
	v_pk_mul_f32 v[18:19], v[24:25], v[18:19]
	s_nop 0
	v_pk_mul_f32 v[24:25], v[20:21], v[18:19]
	v_cvt_pk_bf16_f32 v20, v22, v23
	v_mul_f32_e32 v22, 0xbfb8aa3b, v14
	v_mul_f32_e32 v23, 0xbfb8aa3b, v15
	v_exp_f32_e32 v22, v22
	v_exp_f32_e32 v23, v23
	v_cvt_pk_bf16_f32 v18, v26, v27
	v_cvt_pk_bf16_f32 v19, v28, v29
	v_add_f32_e32 v22, 1.0, v22
	v_add_f32_e32 v23, 1.0, v23
	v_rcp_f32_e32 v22, v22
	v_rcp_f32_e32 v23, v23
	v_cvt_pk_bf16_f32 v21, v24, v25
	v_pk_mul_f32 v[14:15], v[14:15], v[22:23]
	s_nop 0
	v_pk_mul_f32 v[10:11], v[10:11], v[14:15]
	v_mul_f32_e32 v14, 0xbfb8aa3b, v16
	v_mul_f32_e32 v15, 0xbfb8aa3b, v17
	v_exp_f32_e32 v14, v14
	v_exp_f32_e32 v15, v15
	v_add_f32_e32 v14, 1.0, v14
	v_add_f32_e32 v15, 1.0, v15
	v_rcp_f32_e32 v14, v14
	v_rcp_f32_e32 v15, v15
	s_nop 0
	v_pk_mul_f32 v[14:15], v[16:17], v[14:15]
	s_nop 0
	v_pk_mul_f32 v[12:13], v[12:13], v[14:15]
	v_rcp_f32_e32 v14, v0
	v_mul_f32_e32 v0, 0xbfb8aa3b, v7
	v_exp_f32_e32 v0, v0
	s_nop 0
	v_add_f32_e32 v0, 1.0, v0
	v_rcp_f32_e32 v15, v0
	v_mul_f32_e32 v0, 0xbfb8aa3b, v8
	v_exp_f32_e32 v0, v0
	v_pk_mul_f32 v[6:7], v[6:7], v[14:15]
	s_nop 0
	v_pk_mul_f32 v[6:7], v[2:3], v[6:7]
	v_add_f32_e32 v0, 1.0, v0
	v_rcp_f32_e32 v2, v0
	v_mul_f32_e32 v0, 0xbfb8aa3b, v9
	v_exp_f32_e32 v0, v0
	s_nop 0
	v_add_f32_e32 v0, 1.0, v0
	v_rcp_f32_e32 v3, v0
	v_lshlrev_b32_e32 v0, 6, v208
	v_and_or_b32 v0, v0, s38, v221
	v_lshlrev_b32_e32 v0, 1, v0
	v_pk_mul_f32 v[2:3], v[8:9], v[2:3]
	global_store_dwordx4 v0, v[146:149], s[28:29]
	global_store_dwordx4 v0, v[130:133], s[28:29] offset:2048
	v_pk_mul_f32 v[8:9], v[4:5], v[2:3]
	v_cvt_pk_bf16_f32 v4, v6, v7
	v_lshl_add_u64 v[6:7], s[28:29], 0, v[0:1]
	v_add_co_u32_e32 v6, vcc, s2, v6
	v_lshrrev_b32_e32 v0, 8, v166
	s_nop 0
	v_addc_co_u32_e32 v7, vcc, 0, v7, vcc
	global_store_dwordx4 v[6:7], v[114:117], off
	global_store_dwordx4 v[6:7], v[96:99], off offset:2048
	v_lshlrev_b32_e32 v6, 6, v166
	v_cvt_pk_bf16_f32 v5, v8, v9
	v_and_or_b32 v8, v6, s38, v221
	v_mul_hi_i32_i24_e32 v7, 0x160000, v0
	v_mul_i32_i24_e32 v6, 0x160000, v0
	v_lshl_add_u64 v[6:7], s[30:31], 0, v[6:7]
	v_lshl_add_u64 v[6:7], v[6:7], 0, s[16:17]
	v_lshlrev_b32_e32 v0, 1, v8
	v_lshl_add_u64 v[6:7], v[6:7], 0, v[0:1]
	global_store_dwordx4 v[6:7], v[50:53], off
	global_store_dwordx4 v[6:7], v[34:37], off offset:2048
	v_add_co_u32_e32 v6, vcc, 0x1000, v6
	s_mov_b64 s[28:29], -1
	s_nop 0
	v_addc_co_u32_e32 v7, vcc, 0, v7, vcc
	s_andn2_b64 vcc, exec, s[42:43]
	v_cvt_pk_bf16_f32 v2, v10, v11
	v_cvt_pk_bf16_f32 v3, v12, v13
	global_store_dwordx4 v[6:7], v[18:21], off
	global_store_dwordx4 v[6:7], v[2:5], off offset:2048
	s_cbranch_vccnz .LBB0_284
	s_andn2_b64 vcc, exec, s[4:5]
	s_cbranch_vccnz .LBB0_283
	s_barrier
	s_branch .LBB0_283

; __device__ __forceinline__ float xsum16(float v) { const auto r = __builtin_amdgcn_permlane16_swap(__float_as_uint(v), __float_as_uint(v), false, false); return __uint_as_float(r[0]) + __uint_as_float(r[1]); }
; __device__ __forceinline__ float xsum32(float v) { const auto r = __builtin_amdgcn_permlane32_swap(__float_as_uint(v), __float_as_uint(v), false, false); return __uint_as_float(r[0]) + __uint_as_float(r[1]); }
; __device__ __forceinline__ void row_stats4(const float* st, int rowb, int fq, float (&mu)[4], float (&rs)[4]) {
;     f32x4 a[4], b[4];
; #pragma unroll
;     for (int m = 0; m < 4; ++m) { const f32x4* p = (const f32x4*)(st + (size_t)(rowb + m * 16) * 32 + fq * 8); a[m] = p[0]; b[m] = p[1]; }
; #pragma unroll
;     for (int m = 0; m < 4; ++m) { float s1 = (a[m][0] + a[m][2]) + (b[m][0] + b[m][2]), s2 = (a[m][1] + a[m][3]) + (b[m][1] + b[m][3]);
;         s1 = xsum32(xsum16(s1)); s2 = xsum32(xsum16(s2));
;         const float mm = s1 * (1.0f / 1024.0f); mu[m] = mm; rs[m] = rsqrtf(fmaxf(s2 * (1.0f / 1024.0f) - mm * mm, 0.f) + LN_EPS_); }
;     __device__ __forceinline__ void operator()(const f32x4 (&acc)[2][2][4][2], const pg8::Unit& u, int wr, int wc, int fr, int fq) const {
;         const int row0 = u.pm * 256 + wr * 64 + fr, cl = wc * 32 + fq * 8, cB0 = u.pn * 256 + cl;
;         f32x4 gg[2][2], bb[2][2];
; #pragma unroll
;         for (int bj = 0; bj < 2; ++bj)
; #pragma unroll
;             for (int n = 0; n < 2; ++n) { gg[bj][n] = *(const f32x4*)(gW + cB0 + bj * 128 + 4 * n); bb[bj][n] = *(const f32x4*)(bW + cB0 + bj * 128 + 4 * n); }
;         float muA[4], rsA[4], muB[4], rsB[4]; row_stats4(st, row0, fq, muA, rsA); row_stats4(st, row0 + 128, fq, muB, rsB);
.LBB0_1369:
	v_lshl_or_b32 v220, s17, 8, v234
	v_ashrrev_i32_e32 v221, 31, v220
	v_readlane_b32 s16, v250, 52
	v_lshlrev_b64 v[46:47], 2, v[220:221]
	v_readlane_b32 s17, v250, 53
	v_lshl_add_u32 v222, s2, 8, v215
	v_ashrrev_i32_e32 v223, 31, v222
	v_lshl_add_u64 v[48:49], s[16:17], 0, v[46:47]
	v_readlane_b32 s16, v250, 54
	v_readlane_b32 s17, v250, 55
	v_lshlrev_b64 v[162:163], 7, v[222:223]
	v_lshl_add_u64 v[162:163], v[200:201], 0, v[162:163]
	v_lshl_add_u64 v[58:59], s[16:17], 0, v[46:47]
	s_nop 1
	v_bfe_u32 v51, v227, 4, 2
	v_sub_u32_e32 v50, 0, v51
	v_lshlrev_b32_e32 v50, 4, v50
	v_ashrrev_i32_e32 v51, 31, v50
	v_lshl_add_u64 v[50:51], v[48:49], 0, v[50:51]
	global_load_dwordx4 v[74:77], v[50:51], off offset:64
	global_load_dwordx4 v[86:89], v[50:51], off
	s_nop 1
	v_bfe_u32 v51, v227, 4, 2
	v_sub_u32_e32 v50, 0, v51
	v_lshlrev_b32_e32 v50, 4, v50
	v_ashrrev_i32_e32 v51, 31, v50
	v_lshl_add_u64 v[50:51], v[58:59], 0, v[50:51]
	global_load_dwordx4 v[70:73], v[50:51], off offset:64
	global_load_dwordx4 v[82:85], v[50:51], off
	s_nop 1
	v_bfe_u32 v47, v227, 4, 2
	v_sub_u32_e32 v46, 0, v47
	v_lshlrev_b32_e32 v46, 4, v46
	v_ashrrev_i32_e32 v47, 31, v46
	v_lshl_add_u64 v[46:47], v[48:49], 0, v[46:47]
	global_load_dwordx4 v[50:53], v[46:47], off offset:576
	global_load_dwordx4 v[62:65], v[46:47], off offset:512
	s_nop 0
	s_nop 1
	v_bfe_u32 v165, v227, 4, 2
	v_sub_u32_e32 v164, 0, v165
	v_lshlrev_b32_e32 v164, 4, v164
	v_ashrrev_i32_e32 v165, 31, v164
	v_lshl_add_u64 v[164:165], v[58:59], 0, v[164:165]
	global_load_dwordx4 v[46:49], v[164:165], off offset:576
	s_nop 0
	global_load_dwordx4 v[58:61], v[164:165], off offset:512
	s_nop 0
	s_nop 1
	v_bfe_u32 v165, v227, 4, 2
	v_sub_u32_e32 v164, 0, v165
	v_lshlrev_b32_e32 v164, 4, v164
	v_ashrrev_i32_e32 v165, 31, v164
	v_lshl_add_u64 v[164:165], v[162:163], 0, v[164:165]
	global_load_dwordx4 v[186:189], v[164:165], off
	global_load_dwordx4 v[190:193], v[164:165], off offset:64
	v_or_b32_e32 v210, 16, v222
	v_ashrrev_i32_e32 v211, 31, v210
	v_lshlrev_b64 v[162:163], 7, v[210:211]
	v_lshl_add_u64 v[162:163], v[200:201], 0, v[162:163]
	s_nop 1
	v_bfe_u32 v165, v227, 4, 2
	v_sub_u32_e32 v164, 0, v165
	v_lshlrev_b32_e32 v164, 4, v164
	v_ashrrev_i32_e32 v165, 31, v164
	v_lshl_add_u64 v[164:165], v[162:163], 0, v[164:165]
	global_load_dwordx4 v[182:185], v[164:165], off
	global_load_dwordx4 v[178:181], v[164:165], off offset:64
	v_or_b32_e32 v208, 32, v222
	v_ashrrev_i32_e32 v209, 31, v208
	v_lshlrev_b64 v[162:163], 7, v[208:209]
	v_lshl_add_u64 v[162:163], v[200:201], 0, v[162:163]
	s_nop 1
	v_bfe_u32 v171, v227, 4, 2
	v_sub_u32_e32 v170, 0, v171
	v_lshlrev_b32_e32 v170, 4, v170
	v_ashrrev_i32_e32 v171, 31, v170
	v_lshl_add_u64 v[170:171], v[162:163], 0, v[170:171]
	global_load_dwordx4 v[166:169], v[170:171], off
	s_nop 0
	global_load_dwordx4 v[162:165], v[170:171], off offset:64
	v_or_b32_e32 v206, 48, v222
	v_ashrrev_i32_e32 v207, 31, v206
	v_lshlrev_b64 v[170:171], 7, v[206:207]
	v_lshl_add_u64 v[174:175], v[200:201], 0, v[170:171]
	s_nop 1
	v_bfe_u32 v213, v227, 4, 2
	v_sub_u32_e32 v212, 0, v213
	v_lshlrev_b32_e32 v212, 4, v212
	v_ashrrev_i32_e32 v213, 31, v212
	v_lshl_add_u64 v[212:213], v[174:175], 0, v[212:213]
	global_load_dwordx4 v[170:173], v[212:213], off
	s_nop 0
	global_load_dwordx4 v[174:177], v[212:213], off offset:64
	s_mov_b32 s2, 0x3a800000
	s_mov_b32 s1, 0x800000
	v_readlane_b32 s16, v253, 41
	v_readlane_b32 s17, v253, 42
	s_mov_b64 s[28:29], -1
	s_waitcnt vmcnt(14)
	v_permlane32_swap_b32_e32 v86, v74
	v_permlane32_swap_b32_e32 v87, v75
	v_permlane32_swap_b32_e32 v88, v76
	v_permlane32_swap_b32_e32 v89, v77
	v_permlane16_swap_b32_e32 v86, v74
	v_permlane16_swap_b32_e32 v87, v75
	v_permlane16_swap_b32_e32 v88, v76
	v_permlane16_swap_b32_e32 v89, v77
	v_xor_b32_e32 v77, 0x80000000, v77
	v_xor_b32_e32 v89, 0x80000000, v89
	v_xor_b32_e32 v88, 0x80000000, v88
	v_xor_b32_e32 v76, 0x80000000, v76
	s_waitcnt vmcnt(10)
	v_permlane32_swap_b32_e32 v62, v50
	v_permlane32_swap_b32_e32 v63, v51
	v_permlane32_swap_b32_e32 v64, v52
	v_permlane32_swap_b32_e32 v65, v53
	v_permlane16_swap_b32_e32 v62, v50
	v_permlane16_swap_b32_e32 v63, v51
	v_permlane16_swap_b32_e32 v64, v52
	v_permlane16_swap_b32_e32 v65, v53
	v_xor_b32_e32 v53, 0x80000000, v53
	v_xor_b32_e32 v52, 0x80000000, v52
	v_xor_b32_e32 v65, 0x80000000, v65
	s_waitcnt vmcnt(6)
	v_permlane32_swap_b32_e32 v186, v190
	v_permlane32_swap_b32_e32 v187, v191
	v_permlane32_swap_b32_e32 v188, v192
	v_permlane32_swap_b32_e32 v189, v193
	v_permlane16_swap_b32_e32 v186, v190
	v_permlane16_swap_b32_e32 v187, v191
	v_permlane16_swap_b32_e32 v188, v192
	v_permlane16_swap_b32_e32 v189, v193
	v_mov_b32_e32 v212, v186
	v_mov_b32_e32 v213, v190
	v_mov_b32_e32 v216, v188
	v_mov_b32_e32 v217, v192
	v_mov_b32_e32 v190, v187
	v_mov_b32_e32 v192, v189
	v_pk_add_f32 v[212:213], v[212:213], v[216:217]
	v_pk_add_f32 v[186:187], v[190:191], v[192:193]
	v_pk_add_f32 v[212:213], v[212:213], v[212:213] op_sel:[0,1] op_sel_hi:[1,0]
	v_pk_add_f32 v[186:187], v[186:187], v[186:187] op_sel:[0,1] op_sel_hi:[1,0]
	v_xor_b32_e32 v64, 0x80000000, v64
	v_mov_b32_e32 v187, v212
	v_mov_b32_e32 v188, v186
	s_nop 0
	v_permlane16_swap_b32_e32 v212, v187
	v_permlane16_swap_b32_e32 v186, v188
	v_add_f32_e32 v187, v212, v187
	v_add_f32_e32 v186, v186, v188
	v_mov_b32_e32 v189, v187
	v_mov_b32_e32 v188, v186
	s_nop 0
	v_permlane32_swap_b32_e32 v187, v189
	v_permlane32_swap_b32_e32 v186, v188
	v_pk_add_f32 v[186:187], v[186:187], v[188:189]
	s_waitcnt vmcnt(4)
; __device__ __forceinline__ float xsum16(float v) { const auto r = __builtin_amdgcn_permlane16_swap(__float_as_uint(v), __float_as_uint(v), false, false); return __uint_as_float(r[0]) + __uint_as_float(r[1]); }
; __device__ __forceinline__ float xsum32(float v) { const auto r = __builtin_amdgcn_permlane32_swap(__float_as_uint(v), __float_as_uint(v), false, false); return __uint_as_float(r[0]) + __uint_as_float(r[1]); }
; __device__ __forceinline__ void row_stats4(const float* st, int rowb, int fq, float (&mu)[4], float (&rs)[4]) {
;     f32x4 a[4], b[4];
; #pragma unroll
;     for (int m = 0; m < 4; ++m) { const f32x4* p = (const f32x4*)(st + (size_t)(rowb + m * 16) * 32 + fq * 8); a[m] = p[0]; b[m] = p[1]; }
; #pragma unroll
;     for (int m = 0; m < 4; ++m) { float s1 = (a[m][0] + a[m][2]) + (b[m][0] + b[m][2]), s2 = (a[m][1] + a[m][3]) + (b[m][1] + b[m][3]);
;         s1 = xsum32(xsum16(s1)); s2 = xsum32(xsum16(s2));
;         const float mm = s1 * (1.0f / 1024.0f); mu[m] = mm; rs[m] = rsqrtf(fmaxf(s2 * (1.0f / 1024.0f) - mm * mm, 0.f) + LN_EPS_); }
;     __device__ __forceinline__ void operator()(const f32x4 (&acc)[2][2][4][2], const pg8::Unit& u, int wr, int wc, int fr, int fq) const {
;         const int row0 = u.pm * 256 + wr * 64 + fr, cl = wc * 32 + fq * 8, cB0 = u.pn * 256 + cl;
;         f32x4 gg[2][2], bb[2][2];
; #pragma unroll
;         for (int bj = 0; bj < 2; ++bj)
; #pragma unroll
;             for (int n = 0; n < 2; ++n) { gg[bj][n] = *(const f32x4*)(gW + cB0 + bj * 128 + 4 * n); bb[bj][n] = *(const f32x4*)(bW + cB0 + bj * 128 + 4 * n); }
;         float muA[4], rsA[4], muB[4], rsB[4]; row_stats4(st, row0, fq, muA, rsA); row_stats4(st, row0 + 128, fq, muB, rsB);
	v_permlane32_swap_b32_e32 v182, v178
	v_permlane32_swap_b32_e32 v183, v179
	v_permlane32_swap_b32_e32 v184, v180
	v_permlane32_swap_b32_e32 v185, v181
	v_permlane16_swap_b32_e32 v182, v178
	v_permlane16_swap_b32_e32 v183, v179
	v_permlane16_swap_b32_e32 v184, v180
	v_permlane16_swap_b32_e32 v185, v181
	v_mov_b32_e32 v188, v184
	v_pk_mul_f32 v[228:229], v[186:187], s[2:3] op_sel_hi:[1,0]
	v_mov_b32_e32 v189, v180
	v_fma_f32 v186, -v229, v229, v228
	v_max_f32_e32 v186, 0, v186
	v_add_f32_e32 v186, 0x3727c5ac, v186
	v_cmp_gt_f32_e32 vcc, s1, v186
	v_mul_f32_e32 v187, 0x4b800000, v186
	v_mov_b32_e32 v180, v185
	v_cndmask_b32_e32 v186, v186, v187, vcc
	v_rsq_f32_e32 v186, v186
	v_add_u32_e32 v184, 0x80, v222
	v_ashrrev_i32_e32 v185, 31, v184
	v_pk_fma_f32 v[158:159], v[86:87], v[228:229], v[158:159] op_sel:[0,1,0] neg_lo:[1,0,0] neg_hi:[1,0,0]
	v_mul_f32_e32 v187, 0x45800000, v186
	v_cndmask_b32_e32 v230, v186, v187, vcc
	v_mov_b32_e32 v186, v182
	v_mov_b32_e32 v187, v178
	v_mov_b32_e32 v178, v183
	v_pk_add_f32 v[186:187], v[186:187], v[188:189]
	v_pk_add_f32 v[178:179], v[178:179], v[180:181]
	v_pk_add_f32 v[186:187], v[186:187], v[186:187] op_sel:[0,1] op_sel_hi:[1,0]
	v_pk_add_f32 v[178:179], v[178:179], v[178:179] op_sel:[0,1] op_sel_hi:[1,0]
	v_pk_fma_f32 v[160:161], v[88:89], v[228:229], v[160:161] op_sel:[0,1,0]
	v_mov_b32_e32 v179, v186
	v_mov_b32_e32 v180, v178
	s_nop 0
	v_permlane16_swap_b32_e32 v186, v179
	v_permlane16_swap_b32_e32 v178, v180
	v_add_f32_e32 v179, v186, v179
	v_add_f32_e32 v178, v178, v180
	v_mov_b32_e32 v181, v179
	v_mov_b32_e32 v180, v178
	s_nop 0
	v_permlane32_swap_b32_e32 v179, v181
	v_permlane32_swap_b32_e32 v178, v180
	v_pk_add_f32 v[178:179], v[178:179], v[180:181]
	s_waitcnt vmcnt(2)
	v_permlane32_swap_b32_e32 v166, v162
	v_permlane32_swap_b32_e32 v167, v163
	v_permlane32_swap_b32_e32 v168, v164
	v_permlane32_swap_b32_e32 v169, v165
	v_permlane16_swap_b32_e32 v166, v162
	v_permlane16_swap_b32_e32 v167, v163
	v_permlane16_swap_b32_e32 v168, v164
	v_permlane16_swap_b32_e32 v169, v165
	v_mov_b32_e32 v180, v168
	v_pk_mul_f32 v[224:225], v[178:179], s[2:3] op_sel_hi:[1,0]
	v_mov_b32_e32 v181, v164
	v_fma_f32 v178, -v225, v225, v224
	v_max_f32_e32 v178, 0, v178
	v_add_f32_e32 v178, 0x3727c5ac, v178
	v_cmp_gt_f32_e32 vcc, s1, v178
	v_mul_f32_e32 v179, 0x4b800000, v178
	v_mov_b32_e32 v164, v169
	v_cndmask_b32_e32 v178, v178, v179, vcc
	v_rsq_f32_e32 v178, v178
	v_pk_fma_f32 v[154:155], v[74:75], v[228:229], v[154:155] op_sel:[0,1,0] neg_lo:[1,0,0] neg_hi:[1,0,0]
	v_permlane32_swap_b32_e32 v82, v70
	v_permlane32_swap_b32_e32 v83, v71
	v_permlane32_swap_b32_e32 v84, v72
	v_permlane32_swap_b32_e32 v85, v73
	v_permlane16_swap_b32_e32 v82, v70
	v_permlane16_swap_b32_e32 v83, v71
	v_permlane16_swap_b32_e32 v84, v72
	v_permlane16_swap_b32_e32 v85, v73
	v_pk_fma_f32 v[160:161], v[160:161], v[230:231], v[84:85] op_sel_hi:[1,0,1]
	v_pk_fma_f32 v[158:159], v[158:159], v[230:231], v[82:83] op_sel_hi:[1,0,1]
	v_mul_f32_e32 v179, 0x45800000, v178
	v_cndmask_b32_e32 v226, v178, v179, vcc
	v_mov_b32_e32 v178, v166
	v_mov_b32_e32 v179, v162
	v_mov_b32_e32 v162, v167
	v_pk_add_f32 v[178:179], v[178:179], v[180:181]
	v_pk_add_f32 v[162:163], v[162:163], v[164:165]
	v_pk_add_f32 v[178:179], v[178:179], v[178:179] op_sel:[0,1] op_sel_hi:[1,0]
	v_pk_add_f32 v[162:163], v[162:163], v[162:163] op_sel:[0,1] op_sel_hi:[1,0]
	v_pk_fma_f32 v[156:157], v[76:77], v[228:229], v[156:157] op_sel:[0,1,0]
	v_mov_b32_e32 v163, v178
	v_mov_b32_e32 v164, v162
	s_nop 0
	v_permlane16_swap_b32_e32 v178, v163
	v_permlane16_swap_b32_e32 v162, v164
	v_add_f32_e32 v163, v178, v163
	v_add_f32_e32 v162, v162, v164
	v_mov_b32_e32 v165, v163
	v_mov_b32_e32 v164, v162
	s_nop 0
	v_permlane32_swap_b32_e32 v163, v165
	v_permlane32_swap_b32_e32 v162, v164
	v_pk_add_f32 v[162:163], v[162:163], v[164:165]
	s_waitcnt vmcnt(0)
	v_permlane32_swap_b32_e32 v170, v174
	v_permlane32_swap_b32_e32 v171, v175
	v_permlane32_swap_b32_e32 v172, v176
	v_permlane32_swap_b32_e32 v173, v177
	v_permlane16_swap_b32_e32 v170, v174
	v_permlane16_swap_b32_e32 v171, v175
	v_permlane16_swap_b32_e32 v172, v176
	v_permlane16_swap_b32_e32 v173, v177
	v_mov_b32_e32 v164, v172
	v_pk_mul_f32 v[216:217], v[162:163], s[2:3] op_sel_hi:[1,0]
	v_mov_b32_e32 v165, v176
	v_fma_f32 v162, -v217, v217, v216
	v_max_f32_e32 v162, 0, v162
	v_add_f32_e32 v162, 0x3727c5ac, v162
	v_cmp_gt_f32_e32 vcc, s1, v162
	v_mul_f32_e32 v163, 0x4b800000, v162
	v_mov_b32_e32 v176, v173
	v_cndmask_b32_e32 v162, v162, v163, vcc
	v_rsq_f32_e32 v162, v162
	v_add_u32_e32 v172, 0xa0, v222
	v_ashrrev_i32_e32 v173, 31, v172
	v_pk_fma_f32 v[154:155], v[154:155], v[230:231], v[70:71] op_sel_hi:[1,0,1]
	v_mul_f32_e32 v163, 0x45800000, v162
	v_cndmask_b32_e32 v218, v162, v163, vcc
	v_mov_b32_e32 v162, v170
	v_mov_b32_e32 v163, v174
	v_pk_add_f32 v[162:163], v[162:163], v[164:165]
	v_mov_b32_e32 v174, v171
	v_pk_add_f32 v[162:163], v[162:163], v[162:163] op_sel:[0,1] op_sel_hi:[1,0]
	v_pk_add_f32 v[164:165], v[174:175], v[176:177]
	v_mov_b32_e32 v163, v162
	v_pk_add_f32 v[164:165], v[164:165], v[164:165] op_sel:[0,1] op_sel_hi:[1,0]
	s_nop 0
	v_permlane16_swap_b32_e32 v162, v163
	v_add_f32_e32 v163, v162, v163
	v_mov_b32_e32 v162, v164
	s_nop 1
	v_permlane16_swap_b32_e32 v164, v162
	v_add_f32_e32 v162, v164, v162
	v_mov_b32_e32 v165, v163
	v_mov_b32_e32 v164, v162
	s_nop 0
	v_permlane32_swap_b32_e32 v163, v165
	v_permlane32_swap_b32_e32 v162, v164
	v_pk_add_f32 v[162:163], v[162:163], v[164:165]
	v_add_u32_e32 v174, 0x90, v222
	v_pk_mul_f32 v[180:181], v[162:163], s[2:3] op_sel_hi:[1,0]
	v_ashrrev_i32_e32 v175, 31, v174
; __device__ __forceinline__ float xsum16(float v) { const auto r = __builtin_amdgcn_permlane16_swap(__float_as_uint(v), __float_as_uint(v), false, false); return __uint_as_float(r[0]) + __uint_as_float(r[1]); }
; __device__ __forceinline__ float xsum32(float v) { const auto r = __builtin_amdgcn_permlane32_swap(__float_as_uint(v), __float_as_uint(v), false, false); return __uint_as_float(r[0]) + __uint_as_float(r[1]); }
; __device__ __forceinline__ float sigmoid_f(float x) { return fast_rcp(1.0f + fast_exp2(-1.4426950408889634f * x)); }
; __device__ __forceinline__ u32x4 pack8(const f32x4 a, const f32x4 b) { u32x4 w; w.x = cvt_pk_bf16(a[0], a[1]); w.y = cvt_pk_bf16(a[2], a[3]); w.z = cvt_pk_bf16(b[0], b[1]); w.w = cvt_pk_bf16(b[2], b[3]); return w; }
; __device__ __forceinline__ void row_stats4(const float* st, int rowb, int fq, float (&mu)[4], float (&rs)[4]) {
;     f32x4 a[4], b[4];
; #pragma unroll
;     for (int m = 0; m < 4; ++m) { const f32x4* p = (const f32x4*)(st + (size_t)(rowb + m * 16) * 32 + fq * 8); a[m] = p[0]; b[m] = p[1]; }
; #pragma unroll
;     for (int m = 0; m < 4; ++m) { float s1 = (a[m][0] + a[m][2]) + (b[m][0] + b[m][2]), s2 = (a[m][1] + a[m][3]) + (b[m][1] + b[m][3]);
;         s1 = xsum32(xsum16(s1)); s2 = xsum32(xsum16(s2));
;         const float mm = s1 * (1.0f / 1024.0f); mu[m] = mm; rs[m] = rsqrtf(fmaxf(s2 * (1.0f / 1024.0f) - mm * mm, 0.f) + LN_EPS_); }
;     __device__ __forceinline__ void operator()(const f32x4 (&acc)[2][2][4][2], const pg8::Unit& u, int wr, int wc, int fr, int fq) const {
;     ...
;         float muA[4], rsA[4], muB[4], rsB[4]; row_stats4(st, row0, fq, muA, rsA); row_stats4(st, row0 + 128, fq, muB, rsB);
; #pragma unroll
;         for (int ai = 0; ai < 2; ++ai)
; #pragma unroll
;             for (int m = 0; m < 4; ++m) { const float mu = ai ? muB[m] : muA[m], rs = ai ? rsB[m] : rsA[m];
; #pragma unroll
;                 for (int bj = 0; bj < 2; ++bj) { f32x4 z[2];
; #pragma unroll
;                     for (int n = 0; n < 2; ++n) { z[n] = (acc[ai][bj][m][n] - gg[bj][n] * mu) * rs + bb[bj][n];
; #pragma unroll
;                         for (int e = 0; e < 4; ++e) z[n][e] = sigmoid_f(z[n][e]); }
;                     *(u32x4*)(G + (size_t)(row0 + ai * 128 + m * 16) * NG_ + cB0 + bj * 128) = pack8(z[0], z[1]); }
	v_fma_f32 v162, -v181, v181, v180
	v_max_f32_e32 v162, 0, v162
	v_add_f32_e32 v162, 0x3727c5ac, v162
	v_cmp_gt_f32_e32 vcc, s1, v162
	v_mul_f32_e32 v163, 0x4b800000, v162
	v_lshlrev_b64 v[170:171], 7, v[174:175]
	v_cndmask_b32_e32 v162, v162, v163, vcc
	v_rsq_f32_e32 v162, v162
	v_lshl_add_u64 v[170:171], v[200:201], 0, v[170:171]
	v_mul_f32_e32 v158, 0xbfb8aa3b, v158
	v_mul_f32_e32 v159, 0xbfb8aa3b, v159
	v_mul_f32_e32 v163, 0x45800000, v162
	v_cndmask_b32_e32 v182, v162, v163, vcc
	v_lshlrev_b64 v[162:163], 7, v[184:185]
	v_lshl_add_u64 v[162:163], v[200:201], 0, v[162:163]
	s_nop 1
	v_bfe_u32 v177, v227, 4, 2
	v_sub_u32_e32 v176, 0, v177
	v_lshlrev_b32_e32 v176, 4, v176
	v_ashrrev_i32_e32 v177, 31, v176
	v_lshl_add_u64 v[176:177], v[162:163], 0, v[176:177]
	global_load_dwordx4 v[166:169], v[176:177], off
	s_nop 0
	global_load_dwordx4 v[162:165], v[176:177], off offset:64
	s_nop 0
	s_nop 1
	v_bfe_u32 v191, v227, 4, 2
	v_sub_u32_e32 v190, 0, v191
	v_lshlrev_b32_e32 v190, 4, v190
	v_ashrrev_i32_e32 v191, 31, v190
	v_lshl_add_u64 v[190:191], v[170:171], 0, v[190:191]
	global_load_dwordx4 v[176:179], v[190:191], off
	global_load_dwordx4 v[186:189], v[190:191], off offset:64
	v_lshlrev_b64 v[170:171], 7, v[172:173]
	v_lshl_add_u64 v[170:171], v[200:201], 0, v[170:171]
	s_nop 1
	v_bfe_u32 v213, v227, 4, 2
	v_sub_u32_e32 v212, 0, v213
	v_lshlrev_b32_e32 v212, 4, v212
	v_ashrrev_i32_e32 v213, 31, v212
	v_lshl_add_u64 v[212:213], v[170:171], 0, v[212:213]
	global_load_dwordx4 v[190:193], v[212:213], off
	global_load_dwordx4 v[236:239], v[212:213], off offset:64
	v_add_u32_e32 v170, 0xb0, v222
	v_ashrrev_i32_e32 v171, 31, v170
	v_lshlrev_b64 v[212:213], 7, v[170:171]
	v_lshl_add_u64 v[212:213], v[200:201], 0, v[212:213]
	s_nop 1
	v_bfe_u32 v249, v227, 4, 2
	v_sub_u32_e32 v248, 0, v249
	v_lshlrev_b32_e32 v248, 4, v248
	v_ashrrev_i32_e32 v249, 31, v248
	v_lshl_add_u64 v[248:249], v[212:213], 0, v[248:249]
	global_load_dwordx4 v[240:243], v[248:249], off
	global_load_dwordx4 v[244:247], v[248:249], off offset:64
	v_mul_f32_e32 v160, 0xbfb8aa3b, v160
	v_mul_f32_e32 v161, 0xbfb8aa3b, v161
	v_pk_fma_f32 v[156:157], v[156:157], v[230:231], v[72:73] op_sel_hi:[1,0,1]
	v_mul_f32_e32 v154, 0xbfb8aa3b, v154
	v_mul_f32_e32 v155, 0xbfb8aa3b, v155
	v_exp_f32_e32 v158, v158
	v_exp_f32_e32 v159, v159
	v_exp_f32_e32 v160, v160
	v_exp_f32_e32 v161, v161
	v_exp_f32_e32 v154, v154
	v_exp_f32_e32 v155, v155
	v_mul_f32_e32 v156, 0xbfb8aa3b, v156
	v_mul_f32_e32 v157, 0xbfb8aa3b, v157
	v_exp_f32_e32 v156, v156
	v_exp_f32_e32 v157, v157
	v_add_f32_e32 v158, 1.0, v158
	v_add_f32_e32 v159, 1.0, v159
	v_add_f32_e32 v160, 1.0, v160
	v_add_f32_e32 v161, 1.0, v161
	v_add_f32_e32 v154, 1.0, v154
	v_add_f32_e32 v155, 1.0, v155
	v_pk_fma_f32 v[146:147], v[50:51], v[228:229], v[146:147] op_sel:[0,1,0] neg_lo:[1,0,0] neg_hi:[1,0,0]
	v_rcp_f32_e32 v158, v158
	v_rcp_f32_e32 v159, v159
	v_rcp_f32_e32 v160, v160
	v_rcp_f32_e32 v161, v161
	v_rcp_f32_e32 v154, v154
	v_rcp_f32_e32 v155, v155
	v_add_f32_e32 v156, 1.0, v156
	v_add_f32_e32 v157, 1.0, v157
	v_permlane32_swap_b32_e32 v58, v46
	v_permlane32_swap_b32_e32 v59, v47
	v_permlane32_swap_b32_e32 v60, v48
	v_permlane32_swap_b32_e32 v61, v49
	v_permlane16_swap_b32_e32 v58, v46
	v_permlane16_swap_b32_e32 v59, v47
	v_permlane16_swap_b32_e32 v60, v48
	v_permlane16_swap_b32_e32 v61, v49
	v_pk_fma_f32 v[146:147], v[146:147], v[230:231], v[46:47] op_sel_hi:[1,0,1]
	v_rcp_f32_e32 v156, v156
	v_rcp_f32_e32 v157, v157
	v_mul_f32_e32 v146, 0xbfb8aa3b, v146
	v_exp_f32_e32 v146, v146
	v_cvt_pk_bf16_f32 v158, v158, v159
	v_cvt_pk_bf16_f32 v159, v160, v161
	v_cvt_pk_bf16_f32 v160, v154, v155
	v_mov_b64_e32 v[154:155], s[16:17]
	v_cvt_pk_bf16_f32 v161, v156, v157
	v_lshlrev_b64 v[156:157], 1, v[220:221]
	v_add_f32_e32 v146, 1.0, v146
	v_pk_fma_f32 v[148:149], v[52:53], v[228:229], v[148:149] op_sel:[0,1,0]
	v_pk_fma_f32 v[150:151], v[62:63], v[228:229], v[150:151] op_sel:[0,1,0] neg_lo:[1,0,0] neg_hi:[1,0,0]
	v_pk_fma_f32 v[148:149], v[148:149], v[230:231], v[48:49] op_sel_hi:[1,0,1]
	v_pk_fma_f32 v[152:153], v[64:65], v[228:229], v[152:153] op_sel:[0,1,0]
	v_pk_fma_f32 v[150:151], v[150:151], v[230:231], v[58:59] op_sel_hi:[1,0,1]
	v_pk_fma_f32 v[152:153], v[152:153], v[230:231], v[60:61] op_sel_hi:[1,0,1]
	v_mul_f32_e32 v150, 0xbfb8aa3b, v150
	v_mul_f32_e32 v151, 0xbfb8aa3b, v151
	v_mul_f32_e32 v152, 0xbfb8aa3b, v152
	v_mul_f32_e32 v153, 0xbfb8aa3b, v153
	v_exp_f32_e32 v150, v150
	v_exp_f32_e32 v151, v151
	v_exp_f32_e32 v152, v152
	v_exp_f32_e32 v153, v153
	v_pk_fma_f32 v[138:139], v[74:75], v[224:225], v[138:139] op_sel:[0,1,0] neg_lo:[1,0,0] neg_hi:[1,0,0]
	v_add_f32_e32 v150, 1.0, v150
	v_pk_fma_f32 v[138:139], v[138:139], v[226:227], v[70:71] op_sel_hi:[1,0,1]
	v_add_f32_e32 v151, 1.0, v151
	v_add_f32_e32 v152, 1.0, v152
	v_add_f32_e32 v153, 1.0, v153
	v_mul_f32_e32 v138, 0xbfb8aa3b, v138
	v_rcp_f32_e32 v150, v150
	v_rcp_f32_e32 v151, v151
	v_rcp_f32_e32 v152, v152
	v_rcp_f32_e32 v153, v153
	v_exp_f32_e32 v138, v138
	s_waitcnt vmcnt(6)
	v_permlane32_swap_b32_e32 v166, v162
	v_permlane32_swap_b32_e32 v167, v163
	v_permlane32_swap_b32_e32 v168, v164
	v_permlane32_swap_b32_e32 v169, v165
	v_permlane16_swap_b32_e32 v166, v162
	v_permlane16_swap_b32_e32 v167, v163
	v_permlane16_swap_b32_e32 v168, v164
	v_permlane16_swap_b32_e32 v169, v165
	v_mov_b32_e32 v212, v166
	v_mov_b32_e32 v213, v162
	v_mov_b32_e32 v248, v168
	v_mov_b32_e32 v249, v164
	v_mov_b32_e32 v162, v167
	v_mov_b32_e32 v164, v169
	v_pk_add_f32 v[212:213], v[212:213], v[248:249]
	v_pk_add_f32 v[162:163], v[162:163], v[164:165]
	v_pk_add_f32 v[212:213], v[212:213], v[212:213] op_sel:[0,1] op_sel_hi:[1,0]
	v_pk_add_f32 v[162:163], v[162:163], v[162:163] op_sel:[0,1] op_sel_hi:[1,0]
	v_add_f32_e32 v138, 1.0, v138
	v_mov_b32_e32 v163, v212
	v_mov_b32_e32 v164, v162
	s_nop 0
	v_permlane16_swap_b32_e32 v212, v163
	v_permlane16_swap_b32_e32 v162, v164
	v_add_f32_e32 v163, v212, v163
	v_add_f32_e32 v162, v162, v164
	v_mov_b32_e32 v165, v163
	v_mov_b32_e32 v164, v162
	s_nop 0
	v_permlane32_swap_b32_e32 v163, v165
	v_permlane32_swap_b32_e32 v162, v164
	v_pk_add_f32 v[162:163], v[162:163], v[164:165]
	s_waitcnt vmcnt(4)
; __device__ __forceinline__ float xsum16(float v) { const auto r = __builtin_amdgcn_permlane16_swap(__float_as_uint(v), __float_as_uint(v), false, false); return __uint_as_float(r[0]) + __uint_as_float(r[1]); }
; __device__ __forceinline__ float xsum32(float v) { const auto r = __builtin_amdgcn_permlane32_swap(__float_as_uint(v), __float_as_uint(v), false, false); return __uint_as_float(r[0]) + __uint_as_float(r[1]); }
; __device__ __forceinline__ float sigmoid_f(float x) { return fast_rcp(1.0f + fast_exp2(-1.4426950408889634f * x)); }
; __device__ __forceinline__ u32x4 pack8(const f32x4 a, const f32x4 b) { u32x4 w; w.x = cvt_pk_bf16(a[0], a[1]); w.y = cvt_pk_bf16(a[2], a[3]); w.z = cvt_pk_bf16(b[0], b[1]); w.w = cvt_pk_bf16(b[2], b[3]); return w; }
; __device__ __forceinline__ void row_stats4(const float* st, int rowb, int fq, float (&mu)[4], float (&rs)[4]) {
;     f32x4 a[4], b[4];
; #pragma unroll
;     for (int m = 0; m < 4; ++m) { const f32x4* p = (const f32x4*)(st + (size_t)(rowb + m * 16) * 32 + fq * 8); a[m] = p[0]; b[m] = p[1]; }
; #pragma unroll
;     for (int m = 0; m < 4; ++m) { float s1 = (a[m][0] + a[m][2]) + (b[m][0] + b[m][2]), s2 = (a[m][1] + a[m][3]) + (b[m][1] + b[m][3]);
;         s1 = xsum32(xsum16(s1)); s2 = xsum32(xsum16(s2));
;         const float mm = s1 * (1.0f / 1024.0f); mu[m] = mm; rs[m] = rsqrtf(fmaxf(s2 * (1.0f / 1024.0f) - mm * mm, 0.f) + LN_EPS_); }
;     __device__ __forceinline__ void operator()(const f32x4 (&acc)[2][2][4][2], const pg8::Unit& u, int wr, int wc, int fr, int fq) const {
;     ...
;         float muA[4], rsA[4], muB[4], rsB[4]; row_stats4(st, row0, fq, muA, rsA); row_stats4(st, row0 + 128, fq, muB, rsB);
; #pragma unroll
;         for (int ai = 0; ai < 2; ++ai)
; #pragma unroll
;             for (int m = 0; m < 4; ++m) { const float mu = ai ? muB[m] : muA[m], rs = ai ? rsB[m] : rsA[m];
; #pragma unroll
;                 for (int bj = 0; bj < 2; ++bj) { f32x4 z[2];
; #pragma unroll
;                     for (int n = 0; n < 2; ++n) { z[n] = (acc[ai][bj][m][n] - gg[bj][n] * mu) * rs + bb[bj][n];
; #pragma unroll
;                         for (int e = 0; e < 4; ++e) z[n][e] = sigmoid_f(z[n][e]); }
;                     *(u32x4*)(G + (size_t)(row0 + ai * 128 + m * 16) * NG_ + cB0 + bj * 128) = pack8(z[0], z[1]); }
	v_permlane32_swap_b32_e32 v176, v186
	v_permlane32_swap_b32_e32 v177, v187
	v_permlane32_swap_b32_e32 v178, v188
	v_permlane32_swap_b32_e32 v179, v189
	v_permlane16_swap_b32_e32 v176, v186
	v_permlane16_swap_b32_e32 v177, v187
	v_permlane16_swap_b32_e32 v178, v188
	v_permlane16_swap_b32_e32 v179, v189
	v_mov_b32_e32 v164, v178
	v_pk_mul_f32 v[212:213], v[162:163], s[2:3] op_sel_hi:[1,0]
	v_mov_b32_e32 v165, v188
	v_fma_f32 v162, -v213, v213, v212
	v_max_f32_e32 v162, 0, v162
	v_add_f32_e32 v162, 0x3727c5ac, v162
	v_cmp_gt_f32_e32 vcc, s1, v162
	v_mul_f32_e32 v163, 0x4b800000, v162
	v_mov_b32_e32 v188, v179
	v_cndmask_b32_e32 v162, v162, v163, vcc
	v_rsq_f32_e32 v162, v162
	v_pk_fma_f32 v[140:141], v[76:77], v[224:225], v[140:141] op_sel:[0,1,0]
	v_pk_fma_f32 v[142:143], v[86:87], v[224:225], v[142:143] op_sel:[0,1,0] neg_lo:[1,0,0] neg_hi:[1,0,0]
	v_pk_fma_f32 v[140:141], v[140:141], v[226:227], v[72:73] op_sel_hi:[1,0,1]
	v_mul_f32_e32 v163, 0x45800000, v162
	v_cndmask_b32_e32 v214, v162, v163, vcc
	v_mov_b32_e32 v162, v176
	v_mov_b32_e32 v163, v186
	v_pk_add_f32 v[162:163], v[162:163], v[164:165]
	v_mov_b32_e32 v186, v177
	v_pk_add_f32 v[162:163], v[162:163], v[162:163] op_sel:[0,1] op_sel_hi:[1,0]
	v_pk_add_f32 v[164:165], v[186:187], v[188:189]
	v_mov_b32_e32 v163, v162
	v_pk_add_f32 v[164:165], v[164:165], v[164:165] op_sel:[0,1] op_sel_hi:[1,0]
	s_nop 0
	v_permlane16_swap_b32_e32 v162, v163
	v_add_f32_e32 v163, v162, v163
	v_mov_b32_e32 v162, v164
	s_nop 1
	v_permlane16_swap_b32_e32 v164, v162
	v_add_f32_e32 v162, v164, v162
	v_mov_b32_e32 v165, v163
	v_mov_b32_e32 v164, v162
	s_nop 0
	v_permlane32_swap_b32_e32 v163, v165
	v_permlane32_swap_b32_e32 v162, v164
	v_pk_add_f32 v[162:163], v[162:163], v[164:165]
	s_waitcnt vmcnt(2)
	v_permlane32_swap_b32_e32 v190, v236
	v_permlane32_swap_b32_e32 v191, v237
	v_permlane32_swap_b32_e32 v192, v238
	v_permlane32_swap_b32_e32 v193, v239
	v_permlane16_swap_b32_e32 v190, v236
	v_permlane16_swap_b32_e32 v191, v237
	v_permlane16_swap_b32_e32 v192, v238
	v_permlane16_swap_b32_e32 v193, v239
	v_mov_b32_e32 v164, v192
	v_pk_mul_f32 v[176:177], v[162:163], s[2:3] op_sel_hi:[1,0]
	v_mov_b32_e32 v165, v238
	v_fma_f32 v162, -v177, v177, v176
	v_max_f32_e32 v162, 0, v162
	v_add_f32_e32 v162, 0x3727c5ac, v162
	v_cmp_gt_f32_e32 vcc, s1, v162
	v_mul_f32_e32 v163, 0x4b800000, v162
	v_mov_b32_e32 v238, v193
	v_cndmask_b32_e32 v162, v162, v163, vcc
	v_rsq_f32_e32 v162, v162
	v_pk_fma_f32 v[144:145], v[88:89], v[224:225], v[144:145] op_sel:[0,1,0]
	v_pk_fma_f32 v[142:143], v[142:143], v[226:227], v[82:83] op_sel_hi:[1,0,1]
	v_pk_fma_f32 v[144:145], v[144:145], v[226:227], v[84:85] op_sel_hi:[1,0,1]
	v_mul_f32_e32 v163, 0x45800000, v162
	v_cndmask_b32_e32 v178, v162, v163, vcc
	v_mov_b32_e32 v162, v190
	v_mov_b32_e32 v163, v236
	v_pk_add_f32 v[162:163], v[162:163], v[164:165]
	v_mov_b32_e32 v236, v191
	v_pk_add_f32 v[162:163], v[162:163], v[162:163] op_sel:[0,1] op_sel_hi:[1,0]
	v_pk_add_f32 v[164:165], v[236:237], v[238:239]
	v_mov_b32_e32 v163, v162
	v_pk_add_f32 v[164:165], v[164:165], v[164:165] op_sel:[0,1] op_sel_hi:[1,0]
	s_nop 0
	v_permlane16_swap_b32_e32 v162, v163
	v_add_f32_e32 v163, v162, v163
	v_mov_b32_e32 v162, v164
	s_nop 1
	v_permlane16_swap_b32_e32 v164, v162
	v_add_f32_e32 v162, v164, v162
	v_mov_b32_e32 v165, v163
	v_mov_b32_e32 v164, v162
	s_nop 0
	v_permlane32_swap_b32_e32 v163, v165
	v_permlane32_swap_b32_e32 v162, v164
	v_pk_add_f32 v[162:163], v[162:163], v[164:165]
	s_waitcnt vmcnt(0)
	v_permlane32_swap_b32_e32 v240, v244
	v_permlane32_swap_b32_e32 v241, v245
	v_permlane32_swap_b32_e32 v242, v246
	v_permlane32_swap_b32_e32 v243, v247
	v_permlane16_swap_b32_e32 v240, v244
	v_permlane16_swap_b32_e32 v241, v245
	v_permlane16_swap_b32_e32 v242, v246
	v_permlane16_swap_b32_e32 v243, v247
	v_mov_b32_e32 v164, v242
	v_pk_mul_f32 v[166:167], v[162:163], s[2:3] op_sel_hi:[1,0]
	v_mov_b32_e32 v165, v246
	v_fma_f32 v162, -v167, v167, v166
	v_max_f32_e32 v162, 0, v162
	v_add_f32_e32 v162, 0x3727c5ac, v162
	v_cmp_gt_f32_e32 vcc, s1, v162
	v_mul_f32_e32 v163, 0x4b800000, v162
	v_mov_b32_e32 v246, v243
	v_cndmask_b32_e32 v162, v162, v163, vcc
	v_rsq_f32_e32 v162, v162
	v_mul_f32_e32 v142, 0xbfb8aa3b, v142
	v_mul_f32_e32 v143, 0xbfb8aa3b, v143
	v_exp_f32_e32 v142, v142
	v_mul_f32_e32 v163, 0x45800000, v162
	v_cndmask_b32_e32 v168, v162, v163, vcc
	v_mov_b32_e32 v162, v240
	v_mov_b32_e32 v163, v244
	v_pk_add_f32 v[162:163], v[162:163], v[164:165]
	v_mov_b32_e32 v244, v241
	v_pk_add_f32 v[162:163], v[162:163], v[162:163] op_sel:[0,1] op_sel_hi:[1,0]
	v_pk_add_f32 v[164:165], v[244:245], v[246:247]
	v_mov_b32_e32 v163, v162
	v_pk_add_f32 v[164:165], v[164:165], v[164:165] op_sel:[0,1] op_sel_hi:[1,0]
	s_nop 0
	v_permlane16_swap_b32_e32 v162, v163
	v_add_f32_e32 v163, v162, v163
	v_mov_b32_e32 v162, v164
	s_nop 1
	v_permlane16_swap_b32_e32 v164, v162
	v_add_f32_e32 v162, v164, v162
	v_mov_b32_e32 v165, v163
	v_mov_b32_e32 v164, v162
	s_nop 0
	v_permlane32_swap_b32_e32 v163, v165
	v_permlane32_swap_b32_e32 v162, v164
	v_pk_add_f32 v[162:163], v[162:163], v[164:165]
	v_exp_f32_e32 v143, v143
	v_pk_mul_f32 v[162:163], v[162:163], s[2:3] op_sel_hi:[1,0]
	v_mul_f32_e32 v144, 0xbfb8aa3b, v144
	v_fma_f32 v164, -v163, v163, v162
	v_max_f32_e32 v164, 0, v164
	v_add_f32_e32 v164, 0x3727c5ac, v164
	v_cmp_gt_f32_e32 vcc, s1, v164
	s_movk_i32 s1, 0x1800
	v_mad_i64_i32 v[186:187], s[16:17], v222, s1, v[154:155]
	v_lshl_add_u64 v[186:187], v[186:187], 0, v[156:157]
	global_store_dwordx4 v[186:187], v[158:161], off
	v_mul_f32_e32 v145, 0xbfb8aa3b, v145
	v_exp_f32_e32 v144, v144
	v_rcp_f32_e32 v158, v146
; __device__ __forceinline__ float fast_exp2(float x) { return __builtin_amdgcn_exp2f(x); }
; __device__ __forceinline__ float fast_rcp(float x) { return __builtin_amdgcn_rcpf(x); }
; __device__ __forceinline__ u32x4 pack8(const f32x4 a, const f32x4 b) { u32x4 w; w.x = cvt_pk_bf16(a[0], a[1]); w.y = cvt_pk_bf16(a[2], a[3]); w.z = cvt_pk_bf16(b[0], b[1]); w.w = cvt_pk_bf16(b[2], b[3]); return w; }
; __device__ __forceinline__ float sigmoid_f(float x) { return fast_rcp(1.0f + fast_exp2(-1.4426950408889634f * x)); }
;     __device__ __forceinline__ void operator()(const f32x4 (&acc)[2][2][4][2], const pg8::Unit& u, int wr, int wc, int fr, int fq) const {
;     ...
;         for (int ai = 0; ai < 2; ++ai)
; #pragma unroll
;             for (int m = 0; m < 4; ++m) { const float mu = ai ? muB[m] : muA[m], rs = ai ? rsB[m] : rsA[m];
; #pragma unroll
;                 for (int bj = 0; bj < 2; ++bj) { f32x4 z[2];
; #pragma unroll
;                     for (int n = 0; n < 2; ++n) { z[n] = (acc[ai][bj][m][n] - gg[bj][n] * mu) * rs + bb[bj][n];
; #pragma unroll
;                         for (int e = 0; e < 4; ++e) z[n][e] = sigmoid_f(z[n][e]); }
;                     *(u32x4*)(G + (size_t)(row0 + ai * 128 + m * 16) * NG_ + cB0 + bj * 128) = pack8(z[0], z[1]); }
;                 asm volatile("" ::: "memory"); }
	v_mul_f32_e32 v146, 0xbfb8aa3b, v147
	v_exp_f32_e32 v146, v146
	v_cvt_pk_bf16_f32 v147, v152, v153
	v_exp_f32_e32 v145, v145
	v_pk_fma_f32 v[130:131], v[50:51], v[224:225], v[130:131] op_sel:[0,1,0] neg_lo:[1,0,0] neg_hi:[1,0,0]
	v_add_f32_e32 v146, 1.0, v146
	v_rcp_f32_e32 v159, v146
	v_mul_f32_e32 v146, 0xbfb8aa3b, v148
	v_exp_f32_e32 v146, v146
	v_add_f32_e32 v142, 1.0, v142
	v_cvt_pk_bf16_f32 v148, v158, v159
	v_add_f32_e32 v143, 1.0, v143
	v_add_f32_e32 v146, 1.0, v146
	v_rcp_f32_e32 v160, v146
	v_mul_f32_e32 v146, 0xbfb8aa3b, v149
	v_exp_f32_e32 v146, v146
	v_pk_fma_f32 v[130:131], v[130:131], v[226:227], v[46:47] op_sel_hi:[1,0,1]
	v_rcp_f32_e32 v142, v142
	v_rcp_f32_e32 v143, v143
	v_add_f32_e32 v146, 1.0, v146
	v_rcp_f32_e32 v149, v146
	v_cvt_pk_bf16_f32 v146, v150, v151
	v_add_f32_e32 v144, 1.0, v144
	v_add_f32_e32 v145, 1.0, v145
	v_cvt_pk_bf16_f32 v149, v160, v149
	global_store_dwordx4 v[186:187], v[146:149], off offset:256
	v_mul_f32_e32 v130, 0xbfb8aa3b, v130
	v_rcp_f32_e32 v144, v144
	v_rcp_f32_e32 v146, v138
	v_mul_f32_e32 v138, 0xbfb8aa3b, v139
	v_exp_f32_e32 v138, v138
	v_rcp_f32_e32 v145, v145
	v_exp_f32_e32 v130, v130
	v_add_f32_e32 v138, 1.0, v138
	v_rcp_f32_e32 v147, v138
	v_mul_f32_e32 v138, 0xbfb8aa3b, v140
	v_exp_f32_e32 v138, v138
	v_cvt_pk_bf16_f32 v139, v144, v145
	v_cvt_pk_bf16_f32 v140, v146, v147
	v_add_f32_e32 v130, 1.0, v130
	v_add_f32_e32 v138, 1.0, v138
	v_rcp_f32_e32 v148, v138
	v_mul_f32_e32 v138, 0xbfb8aa3b, v141
	v_exp_f32_e32 v138, v138
	v_pk_fma_f32 v[132:133], v[52:53], v[224:225], v[132:133] op_sel:[0,1,0]
	v_pk_fma_f32 v[134:135], v[62:63], v[224:225], v[134:135] op_sel:[0,1,0] neg_lo:[1,0,0] neg_hi:[1,0,0]
	v_pk_fma_f32 v[132:133], v[132:133], v[226:227], v[48:49] op_sel_hi:[1,0,1]
	v_add_f32_e32 v138, 1.0, v138
	v_rcp_f32_e32 v141, v138
	v_cvt_pk_bf16_f32 v138, v142, v143
	v_mad_i64_i32 v[142:143], s[16:17], v210, s1, v[154:155]
	v_cvt_pk_bf16_f32 v141, v148, v141
	v_lshl_add_u64 v[142:143], v[142:143], 0, v[156:157]
	global_store_dwordx4 v[142:143], v[138:141], off
	v_pk_fma_f32 v[136:137], v[64:65], v[224:225], v[136:137] op_sel:[0,1,0]
	v_pk_fma_f32 v[134:135], v[134:135], v[226:227], v[58:59] op_sel_hi:[1,0,1]
	v_rcp_f32_e32 v138, v130
	v_mul_f32_e32 v130, 0xbfb8aa3b, v131
	v_exp_f32_e32 v130, v130
	v_pk_fma_f32 v[136:137], v[136:137], v[226:227], v[60:61] op_sel_hi:[1,0,1]
	v_mul_f32_e32 v134, 0xbfb8aa3b, v134
	v_mul_f32_e32 v135, 0xbfb8aa3b, v135
	v_add_f32_e32 v130, 1.0, v130
	v_rcp_f32_e32 v139, v130
	v_mul_f32_e32 v130, 0xbfb8aa3b, v132
	v_exp_f32_e32 v130, v130
	v_mul_f32_e32 v136, 0xbfb8aa3b, v136
	v_mul_f32_e32 v137, 0xbfb8aa3b, v137
	v_exp_f32_e32 v134, v134
	v_add_f32_e32 v130, 1.0, v130
	v_rcp_f32_e32 v140, v130
	v_mul_f32_e32 v130, 0xbfb8aa3b, v133
	v_exp_f32_e32 v135, v135
	v_exp_f32_e32 v136, v136
	v_exp_f32_e32 v137, v137
	v_exp_f32_e32 v130, v130
	v_pk_fma_f32 v[122:123], v[74:75], v[216:217], v[122:123] op_sel:[0,1,0] neg_lo:[1,0,0] neg_hi:[1,0,0]
	v_add_f32_e32 v134, 1.0, v134
	v_pk_fma_f32 v[122:123], v[122:123], v[218:219], v[70:71] op_sel_hi:[1,0,1]
	v_add_f32_e32 v135, 1.0, v135
	v_add_f32_e32 v136, 1.0, v136
	v_add_f32_e32 v137, 1.0, v137
	v_add_f32_e32 v130, 1.0, v130
	v_mul_f32_e32 v122, 0xbfb8aa3b, v122
	v_rcp_f32_e32 v134, v134
	v_rcp_f32_e32 v135, v135
	v_rcp_f32_e32 v136, v136
	v_rcp_f32_e32 v137, v137
	v_rcp_f32_e32 v133, v130
	v_exp_f32_e32 v122, v122
	v_cvt_pk_bf16_f32 v130, v134, v135
	v_cvt_pk_bf16_f32 v131, v136, v137
	v_cvt_pk_bf16_f32 v132, v138, v139
	v_cvt_pk_bf16_f32 v133, v140, v133
	v_add_f32_e32 v122, 1.0, v122
	global_store_dwordx4 v[142:143], v[130:133], off offset:256
	v_pk_fma_f32 v[124:125], v[76:77], v[216:217], v[124:125] op_sel:[0,1,0]
	v_pk_fma_f32 v[126:127], v[86:87], v[216:217], v[126:127] op_sel:[0,1,0] neg_lo:[1,0,0] neg_hi:[1,0,0]
	v_rcp_f32_e32 v130, v122
	v_mul_f32_e32 v122, 0xbfb8aa3b, v123
	v_exp_f32_e32 v122, v122
	v_pk_fma_f32 v[124:125], v[124:125], v[218:219], v[72:73] op_sel_hi:[1,0,1]
	v_pk_fma_f32 v[128:129], v[88:89], v[216:217], v[128:129] op_sel:[0,1,0]
	v_pk_fma_f32 v[126:127], v[126:127], v[218:219], v[82:83] op_sel_hi:[1,0,1]
	v_add_f32_e32 v122, 1.0, v122
	v_rcp_f32_e32 v131, v122
	v_mul_f32_e32 v122, 0xbfb8aa3b, v124
	v_exp_f32_e32 v122, v122
	v_pk_fma_f32 v[128:129], v[128:129], v[218:219], v[84:85] op_sel_hi:[1,0,1]
	v_mul_f32_e32 v126, 0xbfb8aa3b, v126
	v_mul_f32_e32 v127, 0xbfb8aa3b, v127
	v_add_f32_e32 v122, 1.0, v122
	v_exp_f32_e32 v126, v126
	v_exp_f32_e32 v127, v127
	v_mul_f32_e32 v128, 0xbfb8aa3b, v128
	v_mul_f32_e32 v129, 0xbfb8aa3b, v129
	v_rcp_f32_e32 v132, v122
	v_mul_f32_e32 v122, 0xbfb8aa3b, v125
	v_exp_f32_e32 v128, v128
	v_exp_f32_e32 v129, v129
	v_exp_f32_e32 v122, v122
	v_pk_fma_f32 v[114:115], v[50:51], v[216:217], v[114:115] op_sel:[0,1,0] neg_lo:[1,0,0] neg_hi:[1,0,0]
	v_add_f32_e32 v126, 1.0, v126
	v_add_f32_e32 v127, 1.0, v127
	v_pk_fma_f32 v[114:115], v[114:115], v[218:219], v[46:47] op_sel_hi:[1,0,1]
	v_rcp_f32_e32 v126, v126
	v_rcp_f32_e32 v127, v127
	v_add_f32_e32 v128, 1.0, v128
	v_add_f32_e32 v129, 1.0, v129
	v_add_f32_e32 v122, 1.0, v122
	v_mul_f32_e32 v114, 0xbfb8aa3b, v114
	v_rcp_f32_e32 v128, v128
	v_rcp_f32_e32 v129, v129
	v_rcp_f32_e32 v125, v122
	v_exp_f32_e32 v114, v114
	v_cvt_pk_bf16_f32 v122, v126, v127
	v_mad_i64_i32 v[126:127], s[16:17], v208, s1, v[154:155]
	v_cvt_pk_bf16_f32 v123, v128, v129
	v_cvt_pk_bf16_f32 v124, v130, v131
	v_cvt_pk_bf16_f32 v125, v132, v125
	v_lshl_add_u64 v[126:127], v[126:127], 0, v[156:157]
	v_add_f32_e32 v114, 1.0, v114
	global_store_dwordx4 v[126:127], v[122:125], off
	v_pk_fma_f32 v[116:117], v[52:53], v[216:217], v[116:117] op_sel:[0,1,0]
; __device__ __forceinline__ float fast_exp2(float x) { return __builtin_amdgcn_exp2f(x); }
; __device__ __forceinline__ float fast_rcp(float x) { return __builtin_amdgcn_rcpf(x); }
; __device__ __forceinline__ u32x4 pack8(const f32x4 a, const f32x4 b) { u32x4 w; w.x = cvt_pk_bf16(a[0], a[1]); w.y = cvt_pk_bf16(a[2], a[3]); w.z = cvt_pk_bf16(b[0], b[1]); w.w = cvt_pk_bf16(b[2], b[3]); return w; }
; __device__ __forceinline__ float sigmoid_f(float x) { return fast_rcp(1.0f + fast_exp2(-1.4426950408889634f * x)); }
;     __device__ __forceinline__ void operator()(const f32x4 (&acc)[2][2][4][2], const pg8::Unit& u, int wr, int wc, int fr, int fq) const {
;     ...
;         for (int ai = 0; ai < 2; ++ai)
; #pragma unroll
;             for (int m = 0; m < 4; ++m) { const float mu = ai ? muB[m] : muA[m], rs = ai ? rsB[m] : rsA[m];
; #pragma unroll
;                 for (int bj = 0; bj < 2; ++bj) { f32x4 z[2];
; #pragma unroll
;                     for (int n = 0; n < 2; ++n) { z[n] = (acc[ai][bj][m][n] - gg[bj][n] * mu) * rs + bb[bj][n];
; #pragma unroll
;                         for (int e = 0; e < 4; ++e) z[n][e] = sigmoid_f(z[n][e]); }
;                     *(u32x4*)(G + (size_t)(row0 + ai * 128 + m * 16) * NG_ + cB0 + bj * 128) = pack8(z[0], z[1]); }
;                 asm volatile("" ::: "memory"); }
	v_pk_fma_f32 v[118:119], v[62:63], v[216:217], v[118:119] op_sel:[0,1,0] neg_lo:[1,0,0] neg_hi:[1,0,0]
	v_rcp_f32_e32 v122, v114
	v_mul_f32_e32 v114, 0xbfb8aa3b, v115
	v_exp_f32_e32 v114, v114
	v_pk_fma_f32 v[116:117], v[116:117], v[218:219], v[48:49] op_sel_hi:[1,0,1]
	v_pk_fma_f32 v[120:121], v[64:65], v[216:217], v[120:121] op_sel:[0,1,0]
	v_pk_fma_f32 v[118:119], v[118:119], v[218:219], v[58:59] op_sel_hi:[1,0,1]
	v_add_f32_e32 v114, 1.0, v114
	v_rcp_f32_e32 v123, v114
	v_mul_f32_e32 v114, 0xbfb8aa3b, v116
	v_exp_f32_e32 v114, v114
	v_pk_fma_f32 v[120:121], v[120:121], v[218:219], v[60:61] op_sel_hi:[1,0,1]
	v_mul_f32_e32 v118, 0xbfb8aa3b, v118
	v_mul_f32_e32 v119, 0xbfb8aa3b, v119
	v_add_f32_e32 v114, 1.0, v114
	v_mul_f32_e32 v120, 0xbfb8aa3b, v120
	v_mul_f32_e32 v121, 0xbfb8aa3b, v121
	v_rcp_f32_e32 v124, v114
	v_mul_f32_e32 v114, 0xbfb8aa3b, v117
	v_exp_f32_e32 v118, v118
	v_exp_f32_e32 v119, v119
	v_exp_f32_e32 v120, v120
	v_exp_f32_e32 v121, v121
	v_exp_f32_e32 v114, v114
	v_pk_fma_f32 v[106:107], v[74:75], v[180:181], v[106:107] op_sel:[0,1,0] neg_lo:[1,0,0] neg_hi:[1,0,0]
	v_add_f32_e32 v118, 1.0, v118
	v_pk_fma_f32 v[106:107], v[106:107], v[182:183], v[70:71] op_sel_hi:[1,0,1]
	v_add_f32_e32 v119, 1.0, v119
	v_add_f32_e32 v120, 1.0, v120
	v_add_f32_e32 v121, 1.0, v121
	v_add_f32_e32 v114, 1.0, v114
	v_mul_f32_e32 v106, 0xbfb8aa3b, v106
	v_rcp_f32_e32 v118, v118
	v_rcp_f32_e32 v119, v119
	v_rcp_f32_e32 v120, v120
	v_rcp_f32_e32 v121, v121
	v_rcp_f32_e32 v117, v114
	v_exp_f32_e32 v106, v106
	v_cvt_pk_bf16_f32 v114, v118, v119
	v_cvt_pk_bf16_f32 v115, v120, v121
	v_cvt_pk_bf16_f32 v116, v122, v123
	v_cvt_pk_bf16_f32 v117, v124, v117
	v_add_f32_e32 v106, 1.0, v106
	global_store_dwordx4 v[126:127], v[114:117], off offset:256
	v_pk_fma_f32 v[108:109], v[76:77], v[180:181], v[108:109] op_sel:[0,1,0]
	v_pk_fma_f32 v[110:111], v[86:87], v[180:181], v[110:111] op_sel:[0,1,0] neg_lo:[1,0,0] neg_hi:[1,0,0]
	v_rcp_f32_e32 v114, v106
	v_mul_f32_e32 v106, 0xbfb8aa3b, v107
	v_exp_f32_e32 v106, v106
	v_pk_fma_f32 v[108:109], v[108:109], v[182:183], v[72:73] op_sel_hi:[1,0,1]
	v_pk_fma_f32 v[112:113], v[88:89], v[180:181], v[112:113] op_sel:[0,1,0]
	v_pk_fma_f32 v[110:111], v[110:111], v[182:183], v[82:83] op_sel_hi:[1,0,1]
	v_add_f32_e32 v106, 1.0, v106
	v_rcp_f32_e32 v115, v106
	v_mul_f32_e32 v106, 0xbfb8aa3b, v108
	v_exp_f32_e32 v106, v106
	v_pk_fma_f32 v[112:113], v[112:113], v[182:183], v[84:85] op_sel_hi:[1,0,1]
	v_mul_f32_e32 v110, 0xbfb8aa3b, v110
	v_mul_f32_e32 v111, 0xbfb8aa3b, v111
	v_add_f32_e32 v106, 1.0, v106
	v_exp_f32_e32 v110, v110
	v_exp_f32_e32 v111, v111
	v_mul_f32_e32 v112, 0xbfb8aa3b, v112
	v_mul_f32_e32 v113, 0xbfb8aa3b, v113
	v_rcp_f32_e32 v116, v106
	v_mul_f32_e32 v106, 0xbfb8aa3b, v109
	v_exp_f32_e32 v112, v112
	v_exp_f32_e32 v113, v113
	v_exp_f32_e32 v106, v106
	v_pk_fma_f32 v[98:99], v[50:51], v[180:181], v[98:99] op_sel:[0,1,0] neg_lo:[1,0,0] neg_hi:[1,0,0]
	v_add_f32_e32 v110, 1.0, v110
	v_add_f32_e32 v111, 1.0, v111
	v_pk_fma_f32 v[98:99], v[98:99], v[182:183], v[46:47] op_sel_hi:[1,0,1]
	v_rcp_f32_e32 v110, v110
	v_rcp_f32_e32 v111, v111
	v_add_f32_e32 v112, 1.0, v112
	v_add_f32_e32 v113, 1.0, v113
	v_add_f32_e32 v106, 1.0, v106
	v_mul_f32_e32 v98, 0xbfb8aa3b, v98
	v_rcp_f32_e32 v112, v112
	v_rcp_f32_e32 v113, v113
	v_rcp_f32_e32 v109, v106
	v_exp_f32_e32 v98, v98
	v_cvt_pk_bf16_f32 v106, v110, v111
	v_mad_i64_i32 v[110:111], s[16:17], v206, s1, v[154:155]
	v_cvt_pk_bf16_f32 v107, v112, v113
	v_cvt_pk_bf16_f32 v108, v114, v115
	v_cvt_pk_bf16_f32 v109, v116, v109
	v_lshl_add_u64 v[110:111], v[110:111], 0, v[156:157]
	v_add_f32_e32 v98, 1.0, v98
	global_store_dwordx4 v[110:111], v[106:109], off
	v_pk_fma_f32 v[100:101], v[52:53], v[180:181], v[100:101] op_sel:[0,1,0]
	v_pk_fma_f32 v[102:103], v[62:63], v[180:181], v[102:103] op_sel:[0,1,0] neg_lo:[1,0,0] neg_hi:[1,0,0]
	v_rcp_f32_e32 v106, v98
	v_mul_f32_e32 v98, 0xbfb8aa3b, v99
	v_exp_f32_e32 v98, v98
	v_pk_fma_f32 v[100:101], v[100:101], v[182:183], v[48:49] op_sel_hi:[1,0,1]
	v_pk_fma_f32 v[104:105], v[64:65], v[180:181], v[104:105] op_sel:[0,1,0]
	v_pk_fma_f32 v[102:103], v[102:103], v[182:183], v[58:59] op_sel_hi:[1,0,1]
	v_add_f32_e32 v98, 1.0, v98
	v_rcp_f32_e32 v107, v98
	v_mul_f32_e32 v98, 0xbfb8aa3b, v100
	v_exp_f32_e32 v98, v98
	v_pk_fma_f32 v[104:105], v[104:105], v[182:183], v[60:61] op_sel_hi:[1,0,1]
	v_mul_f32_e32 v102, 0xbfb8aa3b, v102
	v_mul_f32_e32 v103, 0xbfb8aa3b, v103
	v_add_f32_e32 v98, 1.0, v98
	v_mul_f32_e32 v104, 0xbfb8aa3b, v104
	v_mul_f32_e32 v105, 0xbfb8aa3b, v105
	v_rcp_f32_e32 v108, v98
	v_mul_f32_e32 v98, 0xbfb8aa3b, v101
	v_exp_f32_e32 v102, v102
	v_exp_f32_e32 v103, v103
	v_exp_f32_e32 v104, v104
	v_exp_f32_e32 v105, v105
	v_exp_f32_e32 v98, v98
	v_pk_fma_f32 v[90:91], v[74:75], v[212:213], v[90:91] op_sel:[0,1,0] neg_lo:[1,0,0] neg_hi:[1,0,0]
	v_add_f32_e32 v102, 1.0, v102
	v_pk_fma_f32 v[90:91], v[90:91], v[214:215], v[70:71] op_sel_hi:[1,0,1]
	v_add_f32_e32 v103, 1.0, v103
	v_add_f32_e32 v104, 1.0, v104
	v_add_f32_e32 v105, 1.0, v105
	v_add_f32_e32 v98, 1.0, v98
	v_mul_f32_e32 v90, 0xbfb8aa3b, v90
	v_rcp_f32_e32 v102, v102
	v_rcp_f32_e32 v103, v103
	v_rcp_f32_e32 v104, v104
	v_rcp_f32_e32 v105, v105
	v_rcp_f32_e32 v101, v98
	v_exp_f32_e32 v90, v90
	v_cvt_pk_bf16_f32 v98, v102, v103
	v_cvt_pk_bf16_f32 v99, v104, v105
	v_cvt_pk_bf16_f32 v100, v106, v107
	v_cvt_pk_bf16_f32 v101, v108, v101
	v_add_f32_e32 v90, 1.0, v90
	global_store_dwordx4 v[110:111], v[98:101], off offset:256
	v_pk_fma_f32 v[92:93], v[76:77], v[212:213], v[92:93] op_sel:[0,1,0]
	v_pk_fma_f32 v[94:95], v[86:87], v[212:213], v[94:95] op_sel:[0,1,0] neg_lo:[1,0,0] neg_hi:[1,0,0]
; __device__ __forceinline__ float fast_exp2(float x) { return __builtin_amdgcn_exp2f(x); }
; __device__ __forceinline__ float fast_rcp(float x) { return __builtin_amdgcn_rcpf(x); }
; __device__ __forceinline__ u32x4 pack8(const f32x4 a, const f32x4 b) { u32x4 w; w.x = cvt_pk_bf16(a[0], a[1]); w.y = cvt_pk_bf16(a[2], a[3]); w.z = cvt_pk_bf16(b[0], b[1]); w.w = cvt_pk_bf16(b[2], b[3]); return w; }
; __device__ __forceinline__ float sigmoid_f(float x) { return fast_rcp(1.0f + fast_exp2(-1.4426950408889634f * x)); }
;     __device__ __forceinline__ void operator()(const f32x4 (&acc)[2][2][4][2], const pg8::Unit& u, int wr, int wc, int fr, int fq) const {
;     ...
;         for (int ai = 0; ai < 2; ++ai)
; #pragma unroll
;             for (int m = 0; m < 4; ++m) { const float mu = ai ? muB[m] : muA[m], rs = ai ? rsB[m] : rsA[m];
; #pragma unroll
;                 for (int bj = 0; bj < 2; ++bj) { f32x4 z[2];
; #pragma unroll
;                     for (int n = 0; n < 2; ++n) { z[n] = (acc[ai][bj][m][n] - gg[bj][n] * mu) * rs + bb[bj][n];
; #pragma unroll
;                         for (int e = 0; e < 4; ++e) z[n][e] = sigmoid_f(z[n][e]); }
;                     *(u32x4*)(G + (size_t)(row0 + ai * 128 + m * 16) * NG_ + cB0 + bj * 128) = pack8(z[0], z[1]); }
;                 asm volatile("" ::: "memory"); }
	v_rcp_f32_e32 v98, v90
	v_mul_f32_e32 v90, 0xbfb8aa3b, v91
	v_exp_f32_e32 v90, v90
	v_pk_fma_f32 v[92:93], v[92:93], v[214:215], v[72:73] op_sel_hi:[1,0,1]
	v_pk_fma_f32 v[96:97], v[88:89], v[212:213], v[96:97] op_sel:[0,1,0]
	v_pk_fma_f32 v[94:95], v[94:95], v[214:215], v[82:83] op_sel_hi:[1,0,1]
	v_add_f32_e32 v90, 1.0, v90
	v_rcp_f32_e32 v99, v90
	v_mul_f32_e32 v90, 0xbfb8aa3b, v92
	v_exp_f32_e32 v90, v90
	v_pk_fma_f32 v[96:97], v[96:97], v[214:215], v[84:85] op_sel_hi:[1,0,1]
	v_mul_f32_e32 v94, 0xbfb8aa3b, v94
	v_mul_f32_e32 v95, 0xbfb8aa3b, v95
	v_add_f32_e32 v90, 1.0, v90
	v_exp_f32_e32 v94, v94
	v_exp_f32_e32 v95, v95
	v_mul_f32_e32 v96, 0xbfb8aa3b, v96
	v_mul_f32_e32 v97, 0xbfb8aa3b, v97
	v_rcp_f32_e32 v100, v90
	v_mul_f32_e32 v90, 0xbfb8aa3b, v93
	v_exp_f32_e32 v96, v96
	v_exp_f32_e32 v97, v97
	v_exp_f32_e32 v90, v90
	v_pk_fma_f32 v[66:67], v[50:51], v[212:213], v[66:67] op_sel:[0,1,0] neg_lo:[1,0,0] neg_hi:[1,0,0]
	v_add_f32_e32 v94, 1.0, v94
	v_add_f32_e32 v95, 1.0, v95
	v_pk_fma_f32 v[66:67], v[66:67], v[214:215], v[46:47] op_sel_hi:[1,0,1]
	v_rcp_f32_e32 v94, v94
	v_rcp_f32_e32 v95, v95
	v_add_f32_e32 v96, 1.0, v96
	v_add_f32_e32 v97, 1.0, v97
	v_add_f32_e32 v90, 1.0, v90
	v_mul_f32_e32 v66, 0xbfb8aa3b, v66
	v_rcp_f32_e32 v96, v96
	v_rcp_f32_e32 v97, v97
	v_rcp_f32_e32 v93, v90
	v_exp_f32_e32 v66, v66
	v_cvt_pk_bf16_f32 v90, v94, v95
	v_mad_i64_i32 v[94:95], s[16:17], v184, s1, v[154:155]
	v_cvt_pk_bf16_f32 v91, v96, v97
	v_cvt_pk_bf16_f32 v92, v98, v99
	v_cvt_pk_bf16_f32 v93, v100, v93
	v_lshl_add_u64 v[94:95], v[94:95], 0, v[156:157]
	v_add_f32_e32 v66, 1.0, v66
	global_store_dwordx4 v[94:95], v[90:93], off
	v_pk_fma_f32 v[68:69], v[52:53], v[212:213], v[68:69] op_sel:[0,1,0]
	v_pk_fma_f32 v[78:79], v[62:63], v[212:213], v[78:79] op_sel:[0,1,0] neg_lo:[1,0,0] neg_hi:[1,0,0]
	v_rcp_f32_e32 v90, v66
	v_mul_f32_e32 v66, 0xbfb8aa3b, v67
	v_exp_f32_e32 v66, v66
	v_pk_fma_f32 v[68:69], v[68:69], v[214:215], v[48:49] op_sel_hi:[1,0,1]
	v_pk_fma_f32 v[80:81], v[64:65], v[212:213], v[80:81] op_sel:[0,1,0]
	v_pk_fma_f32 v[78:79], v[78:79], v[214:215], v[58:59] op_sel_hi:[1,0,1]
	v_add_f32_e32 v66, 1.0, v66
	v_rcp_f32_e32 v91, v66
	v_mul_f32_e32 v66, 0xbfb8aa3b, v68
	v_exp_f32_e32 v66, v66
	v_pk_fma_f32 v[80:81], v[80:81], v[214:215], v[60:61] op_sel_hi:[1,0,1]
	v_mul_f32_e32 v78, 0xbfb8aa3b, v78
	v_mul_f32_e32 v79, 0xbfb8aa3b, v79
	v_add_f32_e32 v66, 1.0, v66
	v_mul_f32_e32 v80, 0xbfb8aa3b, v80
	v_mul_f32_e32 v81, 0xbfb8aa3b, v81
	v_rcp_f32_e32 v92, v66
	v_mul_f32_e32 v66, 0xbfb8aa3b, v69
	v_exp_f32_e32 v78, v78
	v_exp_f32_e32 v79, v79
	v_exp_f32_e32 v80, v80
	v_exp_f32_e32 v81, v81
	v_exp_f32_e32 v66, v66
	v_pk_fma_f32 v[42:43], v[74:75], v[176:177], v[42:43] op_sel:[0,1,0] neg_lo:[1,0,0] neg_hi:[1,0,0]
	v_add_f32_e32 v78, 1.0, v78
	v_pk_fma_f32 v[42:43], v[42:43], v[178:179], v[70:71] op_sel_hi:[1,0,1]
	v_add_f32_e32 v79, 1.0, v79
	v_add_f32_e32 v80, 1.0, v80
	v_add_f32_e32 v81, 1.0, v81
	v_add_f32_e32 v66, 1.0, v66
	v_mul_f32_e32 v42, 0xbfb8aa3b, v42
	v_rcp_f32_e32 v78, v78
	v_rcp_f32_e32 v79, v79
	v_rcp_f32_e32 v80, v80
	v_rcp_f32_e32 v81, v81
	v_rcp_f32_e32 v69, v66
	v_exp_f32_e32 v42, v42
	v_cvt_pk_bf16_f32 v66, v78, v79
	v_cvt_pk_bf16_f32 v67, v80, v81
	v_cvt_pk_bf16_f32 v68, v90, v91
	v_cvt_pk_bf16_f32 v69, v92, v69
	v_add_f32_e32 v42, 1.0, v42
	global_store_dwordx4 v[94:95], v[66:69], off offset:256
	v_pk_fma_f32 v[44:45], v[76:77], v[176:177], v[44:45] op_sel:[0,1,0]
	v_pk_fma_f32 v[54:55], v[86:87], v[176:177], v[54:55] op_sel:[0,1,0] neg_lo:[1,0,0] neg_hi:[1,0,0]
	v_rcp_f32_e32 v66, v42
	v_mul_f32_e32 v42, 0xbfb8aa3b, v43
	v_exp_f32_e32 v42, v42
	v_pk_fma_f32 v[44:45], v[44:45], v[178:179], v[72:73] op_sel_hi:[1,0,1]
	v_pk_fma_f32 v[56:57], v[88:89], v[176:177], v[56:57] op_sel:[0,1,0]
	v_pk_fma_f32 v[54:55], v[54:55], v[178:179], v[82:83] op_sel_hi:[1,0,1]
	v_add_f32_e32 v42, 1.0, v42
	v_rcp_f32_e32 v67, v42
	v_mul_f32_e32 v42, 0xbfb8aa3b, v44
	v_exp_f32_e32 v42, v42
	v_pk_fma_f32 v[56:57], v[56:57], v[178:179], v[84:85] op_sel_hi:[1,0,1]
	v_mul_f32_e32 v54, 0xbfb8aa3b, v54
	v_mul_f32_e32 v55, 0xbfb8aa3b, v55
	v_add_f32_e32 v42, 1.0, v42
	v_exp_f32_e32 v54, v54
	v_exp_f32_e32 v55, v55
	v_mul_f32_e32 v56, 0xbfb8aa3b, v56
	v_mul_f32_e32 v57, 0xbfb8aa3b, v57
	v_rcp_f32_e32 v68, v42
	v_mul_f32_e32 v42, 0xbfb8aa3b, v45
	v_exp_f32_e32 v56, v56
	v_exp_f32_e32 v57, v57
	v_exp_f32_e32 v42, v42
	v_pk_fma_f32 v[34:35], v[50:51], v[176:177], v[34:35] op_sel:[0,1,0] neg_lo:[1,0,0] neg_hi:[1,0,0]
	v_add_f32_e32 v54, 1.0, v54
	v_add_f32_e32 v55, 1.0, v55
	v_pk_fma_f32 v[34:35], v[34:35], v[178:179], v[46:47] op_sel_hi:[1,0,1]
	v_rcp_f32_e32 v54, v54
	v_rcp_f32_e32 v55, v55
	v_add_f32_e32 v56, 1.0, v56
	v_add_f32_e32 v57, 1.0, v57
	v_add_f32_e32 v42, 1.0, v42
	v_mul_f32_e32 v34, 0xbfb8aa3b, v34
	v_rcp_f32_e32 v56, v56
	v_rcp_f32_e32 v57, v57
	v_rcp_f32_e32 v45, v42
	v_exp_f32_e32 v34, v34
	v_cvt_pk_bf16_f32 v42, v54, v55
	v_mad_i64_i32 v[54:55], s[16:17], v174, s1, v[154:155]
	v_cvt_pk_bf16_f32 v43, v56, v57
	v_cvt_pk_bf16_f32 v44, v66, v67
	v_cvt_pk_bf16_f32 v45, v68, v45
	v_lshl_add_u64 v[54:55], v[54:55], 0, v[156:157]
	v_add_f32_e32 v34, 1.0, v34
	global_store_dwordx4 v[54:55], v[42:45], off
	v_pk_fma_f32 v[36:37], v[52:53], v[176:177], v[36:37] op_sel:[0,1,0]
	v_pk_fma_f32 v[38:39], v[62:63], v[176:177], v[38:39] op_sel:[0,1,0] neg_lo:[1,0,0] neg_hi:[1,0,0]
	v_rcp_f32_e32 v42, v34
	v_mul_f32_e32 v34, 0xbfb8aa3b, v35
	v_exp_f32_e32 v34, v34
	v_pk_fma_f32 v[36:37], v[36:37], v[178:179], v[48:49] op_sel_hi:[1,0,1]
	v_pk_fma_f32 v[40:41], v[64:65], v[176:177], v[40:41] op_sel:[0,1,0]
	v_pk_fma_f32 v[38:39], v[38:39], v[178:179], v[58:59] op_sel_hi:[1,0,1]
; __device__ __forceinline__ float fast_exp2(float x) { return __builtin_amdgcn_exp2f(x); }
; __device__ __forceinline__ float fast_rcp(float x) { return __builtin_amdgcn_rcpf(x); }
; __device__ __forceinline__ u32x4 pack8(const f32x4 a, const f32x4 b) { u32x4 w; w.x = cvt_pk_bf16(a[0], a[1]); w.y = cvt_pk_bf16(a[2], a[3]); w.z = cvt_pk_bf16(b[0], b[1]); w.w = cvt_pk_bf16(b[2], b[3]); return w; }
; __device__ __forceinline__ float sigmoid_f(float x) { return fast_rcp(1.0f + fast_exp2(-1.4426950408889634f * x)); }
;     __device__ __forceinline__ void operator()(const f32x4 (&acc)[2][2][4][2], const pg8::Unit& u, int wr, int wc, int fr, int fq) const {
;     ...
;         for (int ai = 0; ai < 2; ++ai)
; #pragma unroll
;             for (int m = 0; m < 4; ++m) { const float mu = ai ? muB[m] : muA[m], rs = ai ? rsB[m] : rsA[m];
; #pragma unroll
;                 for (int bj = 0; bj < 2; ++bj) { f32x4 z[2];
; #pragma unroll
;                     for (int n = 0; n < 2; ++n) { z[n] = (acc[ai][bj][m][n] - gg[bj][n] * mu) * rs + bb[bj][n];
; #pragma unroll
;                         for (int e = 0; e < 4; ++e) z[n][e] = sigmoid_f(z[n][e]); }
;                     *(u32x4*)(G + (size_t)(row0 + ai * 128 + m * 16) * NG_ + cB0 + bj * 128) = pack8(z[0], z[1]); }
;                 asm volatile("" ::: "memory"); }
	v_add_f32_e32 v34, 1.0, v34
	v_rcp_f32_e32 v43, v34
	v_mul_f32_e32 v34, 0xbfb8aa3b, v36
	v_exp_f32_e32 v34, v34
	v_pk_fma_f32 v[40:41], v[40:41], v[178:179], v[60:61] op_sel_hi:[1,0,1]
	v_mul_f32_e32 v38, 0xbfb8aa3b, v38
	v_mul_f32_e32 v39, 0xbfb8aa3b, v39
	v_add_f32_e32 v34, 1.0, v34
	v_mul_f32_e32 v40, 0xbfb8aa3b, v40
	v_mul_f32_e32 v41, 0xbfb8aa3b, v41
	v_rcp_f32_e32 v44, v34
	v_mul_f32_e32 v34, 0xbfb8aa3b, v37
	v_exp_f32_e32 v38, v38
	v_exp_f32_e32 v39, v39
	v_exp_f32_e32 v40, v40
	v_exp_f32_e32 v41, v41
	v_exp_f32_e32 v34, v34
	v_pk_fma_f32 v[26:27], v[74:75], v[166:167], v[26:27] op_sel:[0,1,0] neg_lo:[1,0,0] neg_hi:[1,0,0]
	v_add_f32_e32 v38, 1.0, v38
	v_pk_fma_f32 v[26:27], v[26:27], v[168:169], v[70:71] op_sel_hi:[1,0,1]
	v_add_f32_e32 v39, 1.0, v39
	v_add_f32_e32 v40, 1.0, v40
	v_add_f32_e32 v41, 1.0, v41
	v_add_f32_e32 v34, 1.0, v34
	v_mul_f32_e32 v26, 0xbfb8aa3b, v26
	v_rcp_f32_e32 v38, v38
	v_rcp_f32_e32 v39, v39
	v_rcp_f32_e32 v40, v40
	v_rcp_f32_e32 v41, v41
	v_rcp_f32_e32 v37, v34
	v_exp_f32_e32 v26, v26
	v_cvt_pk_bf16_f32 v34, v38, v39
	v_cvt_pk_bf16_f32 v35, v40, v41
	v_cvt_pk_bf16_f32 v36, v42, v43
	v_cvt_pk_bf16_f32 v37, v44, v37
	v_add_f32_e32 v26, 1.0, v26
	global_store_dwordx4 v[54:55], v[34:37], off offset:256
	v_pk_fma_f32 v[28:29], v[76:77], v[166:167], v[28:29] op_sel:[0,1,0]
	v_pk_fma_f32 v[30:31], v[86:87], v[166:167], v[30:31] op_sel:[0,1,0] neg_lo:[1,0,0] neg_hi:[1,0,0]
	v_rcp_f32_e32 v34, v26
	v_mul_f32_e32 v26, 0xbfb8aa3b, v27
	v_exp_f32_e32 v26, v26
	v_pk_fma_f32 v[28:29], v[28:29], v[168:169], v[72:73] op_sel_hi:[1,0,1]
	v_pk_fma_f32 v[32:33], v[88:89], v[166:167], v[32:33] op_sel:[0,1,0]
	v_pk_fma_f32 v[30:31], v[30:31], v[168:169], v[82:83] op_sel_hi:[1,0,1]
	v_add_f32_e32 v26, 1.0, v26
	v_rcp_f32_e32 v35, v26
	v_mul_f32_e32 v26, 0xbfb8aa3b, v28
	v_exp_f32_e32 v26, v26
	v_pk_fma_f32 v[32:33], v[32:33], v[168:169], v[84:85] op_sel_hi:[1,0,1]
	v_mul_f32_e32 v30, 0xbfb8aa3b, v30
	v_mul_f32_e32 v31, 0xbfb8aa3b, v31
	v_add_f32_e32 v26, 1.0, v26
	v_exp_f32_e32 v30, v30
	v_exp_f32_e32 v31, v31
	v_mul_f32_e32 v32, 0xbfb8aa3b, v32
	v_mul_f32_e32 v33, 0xbfb8aa3b, v33
	v_rcp_f32_e32 v36, v26
	v_mul_f32_e32 v26, 0xbfb8aa3b, v29
	v_exp_f32_e32 v32, v32
	v_exp_f32_e32 v33, v33
	v_exp_f32_e32 v26, v26
	v_pk_fma_f32 v[18:19], v[50:51], v[166:167], v[18:19] op_sel:[0,1,0] neg_lo:[1,0,0] neg_hi:[1,0,0]
	v_add_f32_e32 v30, 1.0, v30
	v_add_f32_e32 v31, 1.0, v31
	v_pk_fma_f32 v[18:19], v[18:19], v[168:169], v[46:47] op_sel_hi:[1,0,1]
	v_rcp_f32_e32 v30, v30
	v_rcp_f32_e32 v31, v31
	v_add_f32_e32 v32, 1.0, v32
	v_add_f32_e32 v33, 1.0, v33
	v_add_f32_e32 v26, 1.0, v26
	v_mul_f32_e32 v18, 0xbfb8aa3b, v18
	v_rcp_f32_e32 v32, v32
	v_rcp_f32_e32 v33, v33
	v_rcp_f32_e32 v29, v26
	v_exp_f32_e32 v18, v18
	v_cvt_pk_bf16_f32 v26, v30, v31
	v_mad_i64_i32 v[30:31], s[16:17], v172, s1, v[154:155]
	v_cvt_pk_bf16_f32 v27, v32, v33
	v_cvt_pk_bf16_f32 v28, v34, v35
	v_cvt_pk_bf16_f32 v29, v36, v29
	v_lshl_add_u64 v[30:31], v[30:31], 0, v[156:157]
	v_add_f32_e32 v18, 1.0, v18
	global_store_dwordx4 v[30:31], v[26:29], off
	v_pk_fma_f32 v[20:21], v[52:53], v[166:167], v[20:21] op_sel:[0,1,0]
	v_mul_f32_e32 v165, 0x4b800000, v164
	v_rcp_f32_e32 v26, v18
	v_mul_f32_e32 v18, 0xbfb8aa3b, v19
	v_exp_f32_e32 v18, v18
	v_pk_fma_f32 v[20:21], v[20:21], v[168:169], v[48:49] op_sel_hi:[1,0,1]
	v_cndmask_b32_e32 v164, v164, v165, vcc
	v_rsq_f32_e32 v164, v164
	v_add_f32_e32 v18, 1.0, v18
	v_rcp_f32_e32 v27, v18
	v_mul_f32_e32 v18, 0xbfb8aa3b, v20
	v_exp_f32_e32 v18, v18
	v_pk_fma_f32 v[22:23], v[62:63], v[166:167], v[22:23] op_sel:[0,1,0] neg_lo:[1,0,0] neg_hi:[1,0,0]
	v_pk_fma_f32 v[24:25], v[64:65], v[166:167], v[24:25] op_sel:[0,1,0]
	v_pk_fma_f32 v[22:23], v[22:23], v[168:169], v[58:59] op_sel_hi:[1,0,1]
	v_pk_fma_f32 v[24:25], v[24:25], v[168:169], v[60:61] op_sel_hi:[1,0,1]
	v_add_f32_e32 v18, 1.0, v18
	v_mul_f32_e32 v22, 0xbfb8aa3b, v22
	v_mul_f32_e32 v23, 0xbfb8aa3b, v23
	v_mul_f32_e32 v24, 0xbfb8aa3b, v24
	v_mul_f32_e32 v25, 0xbfb8aa3b, v25
	v_rcp_f32_e32 v28, v18
	v_mul_f32_e32 v18, 0xbfb8aa3b, v21
	v_exp_f32_e32 v22, v22
	v_exp_f32_e32 v23, v23
	v_exp_f32_e32 v24, v24
	v_exp_f32_e32 v25, v25
; __device__ __forceinline__ float sigmoid_f(float x) { return fast_rcp(1.0f + fast_exp2(-1.4426950408889634f * x)); }
; __device__ __forceinline__ u32x4 pack8(const f32x4 a, const f32x4 b) { u32x4 w; w.x = cvt_pk_bf16(a[0], a[1]); w.y = cvt_pk_bf16(a[2], a[3]); w.z = cvt_pk_bf16(b[0], b[1]); w.w = cvt_pk_bf16(b[2], b[3]); return w; }
;     __device__ __forceinline__ void operator()(const f32x4 (&acc)[2][2][4][2], const pg8::Unit& u, int wr, int wc, int fr, int fq) const {
;     ...
;         for (int ai = 0; ai < 2; ++ai)
; #pragma unroll
;             for (int m = 0; m < 4; ++m) { const float mu = ai ? muB[m] : muA[m], rs = ai ? rsB[m] : rsA[m];
; #pragma unroll
;                 for (int bj = 0; bj < 2; ++bj) { f32x4 z[2];
; #pragma unroll
;                     for (int n = 0; n < 2; ++n) { z[n] = (acc[ai][bj][m][n] - gg[bj][n] * mu) * rs + bb[bj][n];
; #pragma unroll
;                         for (int e = 0; e < 4; ++e) z[n][e] = sigmoid_f(z[n][e]); }
;                     *(u32x4*)(G + (size_t)(row0 + ai * 128 + m * 16) * NG_ + cB0 + bj * 128) = pack8(z[0], z[1]); }
;                 asm volatile("" ::: "memory"); }
;     }
	v_exp_f32_e32 v18, v18
	v_mul_f32_e32 v165, 0x45800000, v164
	v_cndmask_b32_e32 v164, v164, v165, vcc
	v_pk_fma_f32 v[10:11], v[74:75], v[162:163], v[10:11] op_sel:[0,1,0] neg_lo:[1,0,0] neg_hi:[1,0,0]
	v_add_f32_e32 v22, 1.0, v22
	v_pk_fma_f32 v[10:11], v[10:11], v[164:165], v[70:71] op_sel_hi:[1,0,1]
	v_add_f32_e32 v23, 1.0, v23
	v_add_f32_e32 v24, 1.0, v24
	v_add_f32_e32 v25, 1.0, v25
	v_add_f32_e32 v18, 1.0, v18
	v_mul_f32_e32 v10, 0xbfb8aa3b, v10
	v_rcp_f32_e32 v22, v22
	v_rcp_f32_e32 v23, v23
	v_rcp_f32_e32 v24, v24
	v_rcp_f32_e32 v25, v25
	v_rcp_f32_e32 v21, v18
	v_exp_f32_e32 v10, v10
	v_cvt_pk_bf16_f32 v18, v22, v23
	v_cvt_pk_bf16_f32 v19, v24, v25
	v_cvt_pk_bf16_f32 v20, v26, v27
	v_cvt_pk_bf16_f32 v21, v28, v21
	v_add_f32_e32 v10, 1.0, v10
	global_store_dwordx4 v[30:31], v[18:21], off offset:256
	v_pk_fma_f32 v[12:13], v[76:77], v[162:163], v[12:13] op_sel:[0,1,0]
	v_pk_fma_f32 v[14:15], v[86:87], v[162:163], v[14:15] op_sel:[0,1,0] neg_lo:[1,0,0] neg_hi:[1,0,0]
	v_rcp_f32_e32 v18, v10
	v_mul_f32_e32 v10, 0xbfb8aa3b, v11
	v_exp_f32_e32 v10, v10
	v_pk_fma_f32 v[12:13], v[12:13], v[164:165], v[72:73] op_sel_hi:[1,0,1]
	v_pk_fma_f32 v[16:17], v[88:89], v[162:163], v[16:17] op_sel:[0,1,0]
	v_pk_fma_f32 v[14:15], v[14:15], v[164:165], v[82:83] op_sel_hi:[1,0,1]
	v_add_f32_e32 v10, 1.0, v10
	v_rcp_f32_e32 v19, v10
	v_mul_f32_e32 v10, 0xbfb8aa3b, v12
	v_exp_f32_e32 v10, v10
	v_pk_fma_f32 v[16:17], v[16:17], v[164:165], v[84:85] op_sel_hi:[1,0,1]
	v_mul_f32_e32 v14, 0xbfb8aa3b, v14
	v_mul_f32_e32 v15, 0xbfb8aa3b, v15
	v_add_f32_e32 v10, 1.0, v10
	v_exp_f32_e32 v14, v14
	v_exp_f32_e32 v15, v15
	v_mul_f32_e32 v16, 0xbfb8aa3b, v16
	v_mul_f32_e32 v17, 0xbfb8aa3b, v17
	v_rcp_f32_e32 v20, v10
	v_mul_f32_e32 v10, 0xbfb8aa3b, v13
	v_exp_f32_e32 v16, v16
	v_exp_f32_e32 v17, v17
	v_exp_f32_e32 v10, v10
	v_pk_fma_f32 v[2:3], v[50:51], v[162:163], v[2:3] op_sel:[0,1,0] neg_lo:[1,0,0] neg_hi:[1,0,0]
	v_add_f32_e32 v14, 1.0, v14
	v_add_f32_e32 v15, 1.0, v15
	v_pk_fma_f32 v[2:3], v[2:3], v[164:165], v[46:47] op_sel_hi:[1,0,1]
	v_rcp_f32_e32 v14, v14
	v_rcp_f32_e32 v15, v15
	v_add_f32_e32 v16, 1.0, v16
	v_add_f32_e32 v17, 1.0, v17
	v_add_f32_e32 v10, 1.0, v10
	v_mul_f32_e32 v2, 0xbfb8aa3b, v2
	v_rcp_f32_e32 v16, v16
	v_rcp_f32_e32 v17, v17
	v_rcp_f32_e32 v13, v10
	v_exp_f32_e32 v2, v2
	v_cvt_pk_bf16_f32 v10, v14, v15
	v_mad_i64_i32 v[14:15], s[16:17], v170, s1, v[154:155]
	v_cvt_pk_bf16_f32 v11, v16, v17
	v_cvt_pk_bf16_f32 v12, v18, v19
	v_cvt_pk_bf16_f32 v13, v20, v13
	v_lshl_add_u64 v[14:15], v[14:15], 0, v[156:157]
	v_add_f32_e32 v2, 1.0, v2
	global_store_dwordx4 v[14:15], v[10:13], off
	v_pk_fma_f32 v[4:5], v[52:53], v[162:163], v[4:5] op_sel:[0,1,0]
	v_pk_fma_f32 v[6:7], v[62:63], v[162:163], v[6:7] op_sel:[0,1,0] neg_lo:[1,0,0] neg_hi:[1,0,0]
	v_rcp_f32_e32 v10, v2
	v_mul_f32_e32 v2, 0xbfb8aa3b, v3
	v_exp_f32_e32 v2, v2
	v_pk_fma_f32 v[4:5], v[4:5], v[164:165], v[48:49] op_sel_hi:[1,0,1]
	v_pk_fma_f32 v[8:9], v[64:65], v[162:163], v[8:9] op_sel:[0,1,0]
	v_pk_fma_f32 v[6:7], v[6:7], v[164:165], v[58:59] op_sel_hi:[1,0,1]
	v_add_f32_e32 v2, 1.0, v2
	v_rcp_f32_e32 v11, v2
	v_mul_f32_e32 v2, 0xbfb8aa3b, v4
	v_exp_f32_e32 v2, v2
	v_pk_fma_f32 v[8:9], v[8:9], v[164:165], v[60:61] op_sel_hi:[1,0,1]
	v_mul_f32_e32 v6, 0xbfb8aa3b, v6
	v_mul_f32_e32 v7, 0xbfb8aa3b, v7
	v_add_f32_e32 v2, 1.0, v2
	v_mul_f32_e32 v8, 0xbfb8aa3b, v8
	v_mul_f32_e32 v9, 0xbfb8aa3b, v9
	v_rcp_f32_e32 v12, v2
	v_mul_f32_e32 v2, 0xbfb8aa3b, v5
	v_exp_f32_e32 v6, v6
	v_exp_f32_e32 v7, v7
	v_exp_f32_e32 v8, v8
	v_exp_f32_e32 v9, v9
	v_exp_f32_e32 v2, v2
	v_add_f32_e32 v6, 1.0, v6
	v_add_f32_e32 v7, 1.0, v7
	v_add_f32_e32 v8, 1.0, v8
	v_add_f32_e32 v9, 1.0, v9
	v_add_f32_e32 v2, 1.0, v2
	v_rcp_f32_e32 v6, v6
	v_rcp_f32_e32 v7, v7
	v_rcp_f32_e32 v8, v8
	v_rcp_f32_e32 v9, v9
	v_rcp_f32_e32 v5, v2
	v_cvt_pk_bf16_f32 v2, v6, v7
	v_cvt_pk_bf16_f32 v4, v10, v11
	v_cvt_pk_bf16_f32 v3, v8, v9
	v_cvt_pk_bf16_f32 v5, v12, v5
	global_store_dwordx4 v[14:15], v[2:5], off offset:256
	s_andn2_b64 vcc, exec, s[44:45]
	s_cbranch_vccnz .LBB0_1362
	s_andn2_b64 vcc, exec, s[4:5]
	s_cbranch_vccnz .LBB0_1361
	s_barrier
	s_branch .LBB0_1361

; __device__ __forceinline__ float xsum16(float v) { const auto r = __builtin_amdgcn_permlane16_swap(__float_as_uint(v), __float_as_uint(v), false, false); return __uint_as_float(r[0]) + __uint_as_float(r[1]); }
; __device__ __forceinline__ float xsum32(float v) { const auto r = __builtin_amdgcn_permlane32_swap(__float_as_uint(v), __float_as_uint(v), false, false); return __uint_as_float(r[0]) + __uint_as_float(r[1]); }
; __device__ __forceinline__ void row_stats4(const float* st, int rowb, int fq, float (&mu)[4], float (&rs)[4]) {
;     f32x4 a[4], b[4];
; #pragma unroll
;     for (int m = 0; m < 4; ++m) { const f32x4* p = (const f32x4*)(st + (size_t)(rowb + m * 16) * 32 + fq * 8); a[m] = p[0]; b[m] = p[1]; }
; #pragma unroll
;     for (int m = 0; m < 4; ++m) { float s1 = (a[m][0] + a[m][2]) + (b[m][0] + b[m][2]), s2 = (a[m][1] + a[m][3]) + (b[m][1] + b[m][3]);
;         s1 = xsum32(xsum16(s1)); s2 = xsum32(xsum16(s2));
;         const float mm = s1 * (1.0f / 1024.0f); mu[m] = mm; rs[m] = rsqrtf(fmaxf(s2 * (1.0f / 1024.0f) - mm * mm, 0.f) + LN_EPS_); }
;     __device__ __forceinline__ void operator()(const f32x4 (&acc)[2][2][4][2], const pg8::Unit& u, int wr, int wc, int fr, int fq) const {
;         const int row0 = u.pm * 256 + wr * 64 + fr, cl = wc * 32 + fq * 8, cB0 = u.pn * 256 + cl;
;         f32x4 g0[2], g1[2], b0[2], b1[2];
; #pragma unroll
;         for (int n = 0; n < 2; ++n) { g0[n] = *(const f32x4*)(gW + cB0 + 4 * n); g1[n] = *(const f32x4*)(gW + cB0 + 128 + 4 * n); b0[n] = *(const f32x4*)(bW + cB0 + 4 * n); b1[n] = *(const f32x4*)(bW + cB0 + 128 + 4 * n); }
;         float muA[4], rsA[4], muB[4], rsB[4]; row_stats4(st, row0, fq, muA, rsA); row_stats4(st, row0 + 128, fq, muB, rsB);
.LBB0_1624:
	s_lshl_b32 s9, s2, 8
	v_lshl_or_b32 v62, s44, 8, v220
	s_add_i32 s9, s9, s19
	v_ashrrev_i32_e32 v63, 31, v62
	v_readlane_b32 s16, v250, 48
	v_lshlrev_b64 v[62:63], 2, v[62:63]
	v_readlane_b32 s17, v250, 49
	v_or_b32_e32 v208, s9, v213
	v_ashrrev_i32_e32 v209, 31, v208
	v_lshl_add_u64 v[64:65], s[16:17], 0, v[62:63]
	v_readlane_b32 s16, v250, 50
	v_readlane_b32 s17, v250, 51
	v_lshlrev_b64 v[162:163], 7, v[208:209]
	v_lshl_add_u64 v[218:219], v[202:203], 0, v[162:163]
	v_lshl_add_u64 v[82:83], s[16:17], 0, v[62:63]
	s_nop 1
	v_bfe_u32 v67, v227, 4, 2
	v_sub_u32_e32 v66, 0, v67
	v_lshlrev_b32_e32 v66, 4, v66
	v_ashrrev_i32_e32 v67, 31, v66
	v_lshl_add_u64 v[66:67], v[64:65], 0, v[66:67]
	global_load_dwordx4 v[74:77], v[66:67], off offset:64
	global_load_dwordx4 v[94:97], v[66:67], off
	s_nop 1
	v_bfe_u32 v71, v227, 4, 2
	v_sub_u32_e32 v70, 0, v71
	v_lshlrev_b32_e32 v70, 4, v70
	v_ashrrev_i32_e32 v71, 31, v70
	v_lshl_add_u64 v[70:71], v[64:65], 0, v[70:71]
	global_load_dwordx4 v[66:69], v[70:71], off offset:576
	global_load_dwordx4 v[86:89], v[70:71], off offset:512
	s_nop 1
	v_bfe_u32 v63, v227, 4, 2
	v_sub_u32_e32 v62, 0, v63
	v_lshlrev_b32_e32 v62, 4, v62
	v_ashrrev_i32_e32 v63, 31, v62
	v_lshl_add_u64 v[62:63], v[82:83], 0, v[62:63]
	global_load_dwordx4 v[70:73], v[62:63], off offset:64
	global_load_dwordx4 v[90:93], v[62:63], off
	s_nop 0
	s_nop 1
	v_bfe_u32 v163, v227, 4, 2
	v_sub_u32_e32 v162, 0, v163
	v_lshlrev_b32_e32 v162, 4, v162
	v_ashrrev_i32_e32 v163, 31, v162
	v_lshl_add_u64 v[162:163], v[82:83], 0, v[162:163]
	global_load_dwordx4 v[62:65], v[162:163], off offset:576
	s_nop 0
	global_load_dwordx4 v[82:85], v[162:163], off offset:512
	s_nop 0
	s_nop 1
	v_bfe_u32 v163, v227, 4, 2
	v_sub_u32_e32 v162, 0, v163
	v_lshlrev_b32_e32 v162, 4, v162
	v_ashrrev_i32_e32 v163, 31, v162
	v_lshl_add_u64 v[162:163], v[218:219], 0, v[162:163]
	global_load_dwordx4 v[186:189], v[162:163], off
	global_load_dwordx4 v[190:193], v[162:163], off offset:64
	v_or_b32_e32 v162, 16, v208
	v_ashrrev_i32_e32 v163, 31, v162
	v_lshlrev_b64 v[162:163], 7, v[162:163]
	v_lshl_add_u64 v[162:163], v[202:203], 0, v[162:163]
	s_nop 1
	v_bfe_u32 v165, v227, 4, 2
	v_sub_u32_e32 v164, 0, v165
	v_lshlrev_b32_e32 v164, 4, v164
	v_ashrrev_i32_e32 v165, 31, v164
	v_lshl_add_u64 v[164:165], v[162:163], 0, v[164:165]
	global_load_dwordx4 v[182:185], v[164:165], off
	global_load_dwordx4 v[178:181], v[164:165], off offset:64
	v_or_b32_e32 v162, 32, v208
	v_ashrrev_i32_e32 v163, 31, v162
	v_lshlrev_b64 v[162:163], 7, v[162:163]
	v_lshl_add_u64 v[162:163], v[202:203], 0, v[162:163]
	s_nop 1
	v_bfe_u32 v171, v227, 4, 2
	v_sub_u32_e32 v170, 0, v171
	v_lshlrev_b32_e32 v170, 4, v170
	v_ashrrev_i32_e32 v171, 31, v170
	v_lshl_add_u64 v[170:171], v[162:163], 0, v[170:171]
	global_load_dwordx4 v[166:169], v[170:171], off
	s_nop 0
	global_load_dwordx4 v[162:165], v[170:171], off offset:64
	v_or_b32_e32 v170, 48, v208
	v_ashrrev_i32_e32 v171, 31, v170
	v_lshlrev_b64 v[170:171], 7, v[170:171]
	v_lshl_add_u64 v[174:175], v[202:203], 0, v[170:171]
	s_nop 1
	v_bfe_u32 v211, v227, 4, 2
	v_sub_u32_e32 v210, 0, v211
	v_lshlrev_b32_e32 v210, 4, v210
	v_ashrrev_i32_e32 v211, 31, v210
	v_lshl_add_u64 v[210:211], v[174:175], 0, v[210:211]
	global_load_dwordx4 v[170:173], v[210:211], off
	s_nop 0
	global_load_dwordx4 v[174:177], v[210:211], off offset:64
	s_mov_b32 s16, 0x3a800000
	s_mov_b32 s2, 0x800000
	s_movk_i32 s1, 0x4000
	s_mov_b64 s[28:29], 0x4800
	v_readlane_b32 s30, v253, 41
	v_readlane_b32 s31, v253, 42
	s_movk_i32 s11, 0x33c0
	s_waitcnt vmcnt(14)
	v_permlane32_swap_b32_e32 v94, v74
	v_permlane32_swap_b32_e32 v95, v75
	v_permlane32_swap_b32_e32 v96, v76
	v_permlane32_swap_b32_e32 v97, v77
	v_permlane16_swap_b32_e32 v94, v74
	v_permlane16_swap_b32_e32 v95, v75
	v_permlane16_swap_b32_e32 v96, v76
	v_permlane16_swap_b32_e32 v97, v77
	v_xor_b32_e32 v77, 0x80000000, v77
	v_xor_b32_e32 v76, 0x80000000, v76
	s_waitcnt vmcnt(12)
	v_permlane32_swap_b32_e32 v86, v66
	v_permlane32_swap_b32_e32 v87, v67
	v_permlane32_swap_b32_e32 v88, v68
	v_permlane32_swap_b32_e32 v89, v69
	v_permlane16_swap_b32_e32 v86, v66
	v_permlane16_swap_b32_e32 v87, v67
	v_permlane16_swap_b32_e32 v88, v68
	v_permlane16_swap_b32_e32 v89, v69
	v_xor_b32_e32 v69, 0x80000000, v69
	v_xor_b32_e32 v89, 0x80000000, v89
	v_xor_b32_e32 v88, 0x80000000, v88
	v_xor_b32_e32 v68, 0x80000000, v68
	s_waitcnt vmcnt(6)
	v_permlane32_swap_b32_e32 v186, v190
	v_permlane32_swap_b32_e32 v187, v191
	v_permlane32_swap_b32_e32 v188, v192
	v_permlane32_swap_b32_e32 v189, v193
	v_permlane16_swap_b32_e32 v186, v190
	v_permlane16_swap_b32_e32 v187, v191
	v_permlane16_swap_b32_e32 v188, v192
	v_permlane16_swap_b32_e32 v189, v193
	v_mov_b32_e32 v210, v186
	v_mov_b32_e32 v211, v190
	v_mov_b32_e32 v214, v188
	v_mov_b32_e32 v215, v192
	v_pk_add_f32 v[210:211], v[210:211], v[214:215]
	v_mov_b32_e32 v190, v187
	v_pk_add_f32 v[210:211], v[210:211], v[210:211] op_sel:[0,1] op_sel_hi:[1,0]
	v_mov_b32_e32 v192, v189
	v_pk_add_f32 v[186:187], v[190:191], v[192:193]
	v_mov_b32_e32 v0, v210
	v_pk_add_f32 v[186:187], v[186:187], v[186:187] op_sel:[0,1] op_sel_hi:[1,0]
	s_nop 0
	v_permlane16_swap_b32_e32 v210, v0
	v_add_f32_e32 v187, v210, v0
	v_mov_b32_e32 v0, v186
	s_nop 1
	v_permlane16_swap_b32_e32 v186, v0
	v_add_f32_e32 v186, v186, v0
	v_mov_b32_e32 v189, v187
	v_mov_b32_e32 v188, v186
	s_nop 0
	v_permlane32_swap_b32_e32 v187, v189
	v_permlane32_swap_b32_e32 v186, v188
	v_pk_add_f32 v[186:187], v[186:187], v[188:189]
	s_waitcnt vmcnt(4)
; __device__ __forceinline__ float xsum16(float v) { const auto r = __builtin_amdgcn_permlane16_swap(__float_as_uint(v), __float_as_uint(v), false, false); return __uint_as_float(r[0]) + __uint_as_float(r[1]); }
; __device__ __forceinline__ float xsum32(float v) { const auto r = __builtin_amdgcn_permlane32_swap(__float_as_uint(v), __float_as_uint(v), false, false); return __uint_as_float(r[0]) + __uint_as_float(r[1]); }
; __device__ __forceinline__ void row_stats4(const float* st, int rowb, int fq, float (&mu)[4], float (&rs)[4]) {
;     f32x4 a[4], b[4];
; #pragma unroll
;     for (int m = 0; m < 4; ++m) { const f32x4* p = (const f32x4*)(st + (size_t)(rowb + m * 16) * 32 + fq * 8); a[m] = p[0]; b[m] = p[1]; }
; #pragma unroll
;     for (int m = 0; m < 4; ++m) { float s1 = (a[m][0] + a[m][2]) + (b[m][0] + b[m][2]), s2 = (a[m][1] + a[m][3]) + (b[m][1] + b[m][3]);
;         s1 = xsum32(xsum16(s1)); s2 = xsum32(xsum16(s2));
;         const float mm = s1 * (1.0f / 1024.0f); mu[m] = mm; rs[m] = rsqrtf(fmaxf(s2 * (1.0f / 1024.0f) - mm * mm, 0.f) + LN_EPS_); }
;     __device__ __forceinline__ void operator()(const f32x4 (&acc)[2][2][4][2], const pg8::Unit& u, int wr, int wc, int fr, int fq) const {
;         const int row0 = u.pm * 256 + wr * 64 + fr, cl = wc * 32 + fq * 8, cB0 = u.pn * 256 + cl;
;         f32x4 g0[2], g1[2], b0[2], b1[2];
; #pragma unroll
;         for (int n = 0; n < 2; ++n) { g0[n] = *(const f32x4*)(gW + cB0 + 4 * n); g1[n] = *(const f32x4*)(gW + cB0 + 128 + 4 * n); b0[n] = *(const f32x4*)(bW + cB0 + 4 * n); b1[n] = *(const f32x4*)(bW + cB0 + 128 + 4 * n); }
;         float muA[4], rsA[4], muB[4], rsB[4]; row_stats4(st, row0, fq, muA, rsA); row_stats4(st, row0 + 128, fq, muB, rsB);
;         u32x4 ow[2][4];
; #pragma unroll
;         for (int ai = 0; ai < 2; ++ai)
; #pragma unroll
;             for (int m = 0; m < 4; ++m) { const float mu = ai ? muB[m] : muA[m], rs = ai ? rsB[m] : rsA[m]; f32x4 h[2];
; #pragma unroll
;                 for (int n = 0; n < 2; ++n) { const f32x4 zg = (acc[ai][0][m][n] - g0[n] * mu) * rs + b0[n], zu = (acc[ai][1][m][n] - g1[n] * mu) * rs + b1[n]; h[n] = silu_mul(zg, zu); }
	v_permlane32_swap_b32_e32 v182, v178
	v_permlane32_swap_b32_e32 v183, v179
	v_permlane32_swap_b32_e32 v184, v180
	v_permlane32_swap_b32_e32 v185, v181
	v_permlane16_swap_b32_e32 v182, v178
	v_permlane16_swap_b32_e32 v183, v179
	v_permlane16_swap_b32_e32 v184, v180
	v_permlane16_swap_b32_e32 v185, v181
	v_mov_b32_e32 v188, v184
	v_pk_mul_f32 v[210:211], v[186:187], s[16:17] op_sel_hi:[1,0]
	v_mov_b32_e32 v187, v178
	v_fma_f32 v0, -v211, v211, v210
	v_max_f32_e32 v0, 0, v0
	v_add_f32_e32 v0, 0x3727c5ac, v0
	v_cmp_gt_f32_e32 vcc, s2, v0
	v_mul_f32_e32 v186, 0x4b800000, v0
	v_mov_b32_e32 v189, v180
	v_cndmask_b32_e32 v0, v0, v186, vcc
	v_rsq_f32_e32 v0, v0
	v_mov_b32_e32 v178, v183
	v_mov_b32_e32 v180, v185
	v_pk_add_f32 v[178:179], v[178:179], v[180:181]
	v_mul_f32_e32 v186, 0x45800000, v0
	v_cndmask_b32_e32 v212, v0, v186, vcc
	v_mov_b32_e32 v186, v182
	v_pk_add_f32 v[186:187], v[186:187], v[188:189]
	v_pk_add_f32 v[178:179], v[178:179], v[178:179] op_sel:[0,1] op_sel_hi:[1,0]
	v_pk_add_f32 v[186:187], v[186:187], v[186:187] op_sel:[0,1] op_sel_hi:[1,0]
	v_pk_fma_f32 v[154:155], v[86:87], v[210:211], v[154:155] op_sel:[0,1,0] neg_lo:[1,0,0] neg_hi:[1,0,0]
	v_mov_b32_e32 v0, v186
	s_nop 1
	v_permlane16_swap_b32_e32 v186, v0
	v_add_f32_e32 v179, v186, v0
	v_mov_b32_e32 v0, v178
	s_nop 1
	v_permlane16_swap_b32_e32 v178, v0
	v_add_f32_e32 v178, v178, v0
	v_mov_b32_e32 v181, v179
	v_mov_b32_e32 v180, v178
	s_nop 0
	v_permlane32_swap_b32_e32 v179, v181
	v_permlane32_swap_b32_e32 v178, v180
	v_pk_add_f32 v[178:179], v[178:179], v[180:181]
	s_waitcnt vmcnt(2)
	v_permlane32_swap_b32_e32 v166, v162
	v_permlane32_swap_b32_e32 v167, v163
	v_permlane32_swap_b32_e32 v168, v164
	v_permlane32_swap_b32_e32 v169, v165
	v_permlane16_swap_b32_e32 v166, v162
	v_permlane16_swap_b32_e32 v167, v163
	v_permlane16_swap_b32_e32 v168, v164
	v_permlane16_swap_b32_e32 v169, v165
	v_mov_b32_e32 v180, v168
	v_pk_mul_f32 v[214:215], v[178:179], s[16:17] op_sel_hi:[1,0]
	v_mov_b32_e32 v179, v162
	v_fma_f32 v0, -v215, v215, v214
	v_max_f32_e32 v0, 0, v0
	v_add_f32_e32 v0, 0x3727c5ac, v0
	v_cmp_gt_f32_e32 vcc, s2, v0
	v_mul_f32_e32 v178, 0x4b800000, v0
	v_mov_b32_e32 v181, v164
	v_cndmask_b32_e32 v0, v0, v178, vcc
	v_rsq_f32_e32 v0, v0
	v_mov_b32_e32 v162, v167
	v_mov_b32_e32 v164, v169
	v_pk_add_f32 v[162:163], v[162:163], v[164:165]
	v_mul_f32_e32 v178, 0x45800000, v0
	v_cndmask_b32_e32 v216, v0, v178, vcc
	v_mov_b32_e32 v178, v166
	v_pk_add_f32 v[178:179], v[178:179], v[180:181]
	v_pk_add_f32 v[162:163], v[162:163], v[162:163] op_sel:[0,1] op_sel_hi:[1,0]
	v_pk_add_f32 v[178:179], v[178:179], v[178:179] op_sel:[0,1] op_sel_hi:[1,0]
	v_add_u32_e32 v166, 0x80, v208
	v_mov_b32_e32 v0, v178
	s_nop 1
	v_permlane16_swap_b32_e32 v178, v0
	v_add_f32_e32 v163, v178, v0
	v_mov_b32_e32 v0, v162
	s_nop 1
	v_permlane16_swap_b32_e32 v162, v0
	v_add_f32_e32 v162, v162, v0
	v_mov_b32_e32 v165, v163
	v_mov_b32_e32 v164, v162
	s_nop 0
	v_permlane32_swap_b32_e32 v163, v165
	v_permlane32_swap_b32_e32 v162, v164
	v_pk_add_f32 v[162:163], v[162:163], v[164:165]
	s_waitcnt vmcnt(0)
	v_permlane32_swap_b32_e32 v170, v174
	v_permlane32_swap_b32_e32 v171, v175
	v_permlane32_swap_b32_e32 v172, v176
	v_permlane32_swap_b32_e32 v173, v177
	v_permlane16_swap_b32_e32 v170, v174
	v_permlane16_swap_b32_e32 v171, v175
	v_permlane16_swap_b32_e32 v172, v176
	v_permlane16_swap_b32_e32 v173, v177
	v_mov_b32_e32 v164, v172
	v_pk_mul_f32 v[178:179], v[162:163], s[16:17] op_sel_hi:[1,0]
	v_mov_b32_e32 v163, v174
	v_fma_f32 v0, -v179, v179, v178
	v_max_f32_e32 v0, 0, v0
	v_add_f32_e32 v0, 0x3727c5ac, v0
	v_cmp_gt_f32_e32 vcc, s2, v0
	v_mul_f32_e32 v162, 0x4b800000, v0
	v_mov_b32_e32 v165, v176
	v_cndmask_b32_e32 v0, v0, v162, vcc
	v_rsq_f32_e32 v0, v0
	v_mov_b32_e32 v174, v171
	v_mov_b32_e32 v176, v173
	v_ashrrev_i32_e32 v167, 31, v166
	v_mul_f32_e32 v162, 0x45800000, v0
	v_cndmask_b32_e32 v180, v0, v162, vcc
	v_mov_b32_e32 v162, v170
	v_pk_add_f32 v[162:163], v[162:163], v[164:165]
	v_pk_add_f32 v[164:165], v[174:175], v[176:177]
	v_pk_add_f32 v[162:163], v[162:163], v[162:163] op_sel:[0,1] op_sel_hi:[1,0]
	v_pk_add_f32 v[164:165], v[164:165], v[164:165] op_sel:[0,1] op_sel_hi:[1,0]
	v_mov_b32_e32 v0, v162
	s_nop 1
	v_permlane16_swap_b32_e32 v162, v0
	v_add_f32_e32 v163, v162, v0
	v_mov_b32_e32 v0, v164
	s_nop 1
	v_permlane16_swap_b32_e32 v164, v0
	v_add_f32_e32 v162, v164, v0
	v_mov_b32_e32 v165, v163
	v_mov_b32_e32 v164, v162
	s_nop 0
	v_permlane32_swap_b32_e32 v163, v165
	v_permlane32_swap_b32_e32 v162, v164
	v_pk_add_f32 v[162:163], v[162:163], v[164:165]
	v_lshl_add_u64 v[168:169], v[218:219], 0, s[28:29]
	v_pk_mul_f32 v[170:171], v[162:163], s[16:17] op_sel_hi:[1,0]
	s_mov_b64 s[28:29], 0x5000
	v_fma_f32 v0, -v171, v171, v170
	v_max_f32_e32 v0, 0, v0
	v_add_f32_e32 v0, 0x3727c5ac, v0
	v_cmp_gt_f32_e32 vcc, s2, v0
	v_mul_f32_e32 v162, 0x4b800000, v0
	v_permlane32_swap_b32_e32 v82, v62
	v_permlane32_swap_b32_e32 v83, v63
	v_permlane32_swap_b32_e32 v84, v64
	v_permlane32_swap_b32_e32 v85, v65
	v_permlane16_swap_b32_e32 v82, v62
	v_permlane16_swap_b32_e32 v83, v63
	v_permlane16_swap_b32_e32 v84, v64
	v_permlane16_swap_b32_e32 v85, v65
	v_pk_fma_f32 v[154:155], v[154:155], v[212:213], v[82:83] op_sel_hi:[1,0,1]
	v_cndmask_b32_e32 v0, v0, v162, vcc
	v_rsq_f32_e32 v0, v0
	v_pk_fma_f32 v[156:157], v[88:89], v[210:211], v[156:157] op_sel:[0,1,0]
	v_pk_fma_f32 v[150:151], v[74:75], v[210:211], v[150:151] op_sel:[0,1,0] neg_lo:[1,0,0] neg_hi:[1,0,0]
	v_pk_fma_f32 v[156:157], v[156:157], v[212:213], v[84:85] op_sel_hi:[1,0,1]
	v_mul_f32_e32 v162, 0x45800000, v0
	v_cndmask_b32_e32 v172, v0, v162, vcc
; __device__ __forceinline__ float xsum16(float v) { const auto r = __builtin_amdgcn_permlane16_swap(__float_as_uint(v), __float_as_uint(v), false, false); return __uint_as_float(r[0]) + __uint_as_float(r[1]); }
; __device__ __forceinline__ float xsum32(float v) { const auto r = __builtin_amdgcn_permlane32_swap(__float_as_uint(v), __float_as_uint(v), false, false); return __uint_as_float(r[0]) + __uint_as_float(r[1]); }
; __device__ __forceinline__ u32x4 pack8(const f32x4 a, const f32x4 b) { u32x4 w; w.x = cvt_pk_bf16(a[0], a[1]); w.y = cvt_pk_bf16(a[2], a[3]); w.z = cvt_pk_bf16(b[0], b[1]); w.w = cvt_pk_bf16(b[2], b[3]); return w; }
; __device__ __forceinline__ void row_stats4(const float* st, int rowb, int fq, float (&mu)[4], float (&rs)[4]) {
;     f32x4 a[4], b[4];
; #pragma unroll
;     for (int m = 0; m < 4; ++m) { const f32x4* p = (const f32x4*)(st + (size_t)(rowb + m * 16) * 32 + fq * 8); a[m] = p[0]; b[m] = p[1]; }
; #pragma unroll
;     for (int m = 0; m < 4; ++m) { float s1 = (a[m][0] + a[m][2]) + (b[m][0] + b[m][2]), s2 = (a[m][1] + a[m][3]) + (b[m][1] + b[m][3]);
;         s1 = xsum32(xsum16(s1)); s2 = xsum32(xsum16(s2));
;         const float mm = s1 * (1.0f / 1024.0f); mu[m] = mm; rs[m] = rsqrtf(fmaxf(s2 * (1.0f / 1024.0f) - mm * mm, 0.f) + LN_EPS_); }
;     __device__ __forceinline__ void operator()(const f32x4 (&acc)[2][2][4][2], const pg8::Unit& u, int wr, int wc, int fr, int fq) const {
;     ...
;             for (int m = 0; m < 4; ++m) { const float mu = ai ? muB[m] : muA[m], rs = ai ? rsB[m] : rsA[m]; f32x4 h[2];
; #pragma unroll
;                 for (int n = 0; n < 2; ++n) { const f32x4 zg = (acc[ai][0][m][n] - g0[n] * mu) * rs + b0[n], zu = (acc[ai][1][m][n] - g1[n] * mu) * rs + b1[n]; h[n] = silu_mul(zg, zu); }
;                 ow[ai][m] = pack8(h[0], h[1]); }
	v_lshlrev_b64 v[162:163], 7, v[166:167]
	v_lshl_add_u64 v[162:163], v[202:203], 0, v[162:163]
	s_nop 1
	v_bfe_u32 v183, v227, 4, 2
	v_sub_u32_e32 v182, 0, v183
	v_lshlrev_b32_e32 v182, 4, v182
	v_ashrrev_i32_e32 v183, 31, v182
	v_lshl_add_u64 v[182:183], v[162:163], 0, v[182:183]
	global_load_dwordx4 v[174:177], v[182:183], off
	s_nop 0
	global_load_dwordx4 v[162:165], v[182:183], off offset:64
	v_add_co_u32_e32 v182, vcc, s1, v218
	s_movk_i32 s1, 0x5000
	s_nop 0
	v_addc_co_u32_e32 v183, vcc, 0, v219, vcc
	global_load_dwordx4 v[186:189], v[182:183], off offset:2048
	global_load_dwordx4 v[190:193], v[168:169], off offset:16
	v_add_co_u32_e32 v182, vcc, s1, v218
	v_lshl_add_u64 v[168:169], v[218:219], 0, s[28:29]
	s_nop 0
	v_addc_co_u32_e32 v183, vcc, 0, v219, vcc
	global_load_dwordx4 v[234:237], v[182:183], off
	global_load_dwordx4 v[238:241], v[168:169], off offset:16
	s_mov_b64 s[28:29], 0x5800
	v_lshl_add_u64 v[168:169], v[218:219], 0, s[28:29]
	global_load_dwordx4 v[242:245], v[182:183], off offset:2048
	global_load_dwordx4 v[246:249], v[168:169], off offset:16
	v_permlane32_swap_b32_e32 v90, v70
	v_permlane32_swap_b32_e32 v91, v71
	v_permlane32_swap_b32_e32 v92, v72
	v_permlane32_swap_b32_e32 v93, v73
	v_permlane16_swap_b32_e32 v90, v70
	v_permlane16_swap_b32_e32 v91, v71
	v_permlane16_swap_b32_e32 v92, v72
	v_permlane16_swap_b32_e32 v93, v73
	v_pk_fma_f32 v[150:151], v[150:151], v[212:213], v[70:71] op_sel_hi:[1,0,1]
	v_pk_fma_f32 v[152:153], v[76:77], v[210:211], v[152:153] op_sel:[0,1,0]
	v_pk_fma_f32 v[146:147], v[66:67], v[210:211], v[146:147] op_sel:[0,1,0] neg_lo:[1,0,0] neg_hi:[1,0,0]
	v_pk_fma_f32 v[152:153], v[152:153], v[212:213], v[72:73] op_sel_hi:[1,0,1]
	v_pk_fma_f32 v[146:147], v[146:147], v[212:213], v[62:63] op_sel_hi:[1,0,1]
	v_pk_fma_f32 v[148:149], v[68:69], v[210:211], v[148:149] op_sel:[0,1,0]
	v_pk_fma_f32 v[138:139], v[86:87], v[214:215], v[138:139] op_sel:[0,1,0] neg_lo:[1,0,0] neg_hi:[1,0,0]
	v_pk_fma_f32 v[148:149], v[148:149], v[212:213], v[64:65] op_sel_hi:[1,0,1]
	v_pk_fma_f32 v[138:139], v[138:139], v[216:217], v[82:83] op_sel_hi:[1,0,1]
	v_pk_fma_f32 v[140:141], v[88:89], v[214:215], v[140:141] op_sel:[0,1,0]
	v_pk_fma_f32 v[134:135], v[74:75], v[214:215], v[134:135] op_sel:[0,1,0] neg_lo:[1,0,0] neg_hi:[1,0,0]
	v_pk_fma_f32 v[140:141], v[140:141], v[216:217], v[84:85] op_sel_hi:[1,0,1]
	v_pk_fma_f32 v[134:135], v[134:135], v[216:217], v[70:71] op_sel_hi:[1,0,1]
	v_pk_fma_f32 v[136:137], v[76:77], v[214:215], v[136:137] op_sel:[0,1,0]
	v_pk_fma_f32 v[130:131], v[66:67], v[214:215], v[130:131] op_sel:[0,1,0] neg_lo:[1,0,0] neg_hi:[1,0,0]
	v_pk_fma_f32 v[136:137], v[136:137], v[216:217], v[72:73] op_sel_hi:[1,0,1]
	v_pk_fma_f32 v[130:131], v[130:131], v[216:217], v[62:63] op_sel_hi:[1,0,1]
	v_pk_fma_f32 v[132:133], v[68:69], v[214:215], v[132:133] op_sel:[0,1,0]
	v_pk_fma_f32 v[122:123], v[86:87], v[178:179], v[122:123] op_sel:[0,1,0] neg_lo:[1,0,0] neg_hi:[1,0,0]
	v_pk_fma_f32 v[132:133], v[132:133], v[216:217], v[64:65] op_sel_hi:[1,0,1]
	v_pk_fma_f32 v[122:123], v[122:123], v[180:181], v[82:83] op_sel_hi:[1,0,1]
	v_pk_fma_f32 v[124:125], v[88:89], v[178:179], v[124:125] op_sel:[0,1,0]
	v_pk_fma_f32 v[118:119], v[74:75], v[178:179], v[118:119] op_sel:[0,1,0] neg_lo:[1,0,0] neg_hi:[1,0,0]
	v_pk_fma_f32 v[124:125], v[124:125], v[180:181], v[84:85] op_sel_hi:[1,0,1]
	v_pk_fma_f32 v[118:119], v[118:119], v[180:181], v[70:71] op_sel_hi:[1,0,1]
	v_pk_fma_f32 v[120:121], v[76:77], v[178:179], v[120:121] op_sel:[0,1,0]
	v_pk_fma_f32 v[114:115], v[66:67], v[178:179], v[114:115] op_sel:[0,1,0] neg_lo:[1,0,0] neg_hi:[1,0,0]
	v_pk_fma_f32 v[120:121], v[120:121], v[180:181], v[72:73] op_sel_hi:[1,0,1]
	v_pk_fma_f32 v[114:115], v[114:115], v[180:181], v[62:63] op_sel_hi:[1,0,1]
	v_pk_fma_f32 v[116:117], v[68:69], v[178:179], v[116:117] op_sel:[0,1,0]
	v_pk_fma_f32 v[106:107], v[86:87], v[170:171], v[106:107] op_sel:[0,1,0] neg_lo:[1,0,0] neg_hi:[1,0,0]
	v_pk_fma_f32 v[116:117], v[116:117], v[180:181], v[64:65] op_sel_hi:[1,0,1]
	v_pk_fma_f32 v[106:107], v[106:107], v[172:173], v[82:83] op_sel_hi:[1,0,1]
	v_pk_fma_f32 v[108:109], v[88:89], v[170:171], v[108:109] op_sel:[0,1,0]
	v_pk_fma_f32 v[102:103], v[74:75], v[170:171], v[102:103] op_sel:[0,1,0] neg_lo:[1,0,0] neg_hi:[1,0,0]
	v_pk_fma_f32 v[108:109], v[108:109], v[172:173], v[84:85] op_sel_hi:[1,0,1]
	v_pk_fma_f32 v[102:103], v[102:103], v[172:173], v[70:71] op_sel_hi:[1,0,1]
	v_pk_fma_f32 v[104:105], v[76:77], v[170:171], v[104:105] op_sel:[0,1,0]
	v_pk_fma_f32 v[98:99], v[66:67], v[170:171], v[98:99] op_sel:[0,1,0] neg_lo:[1,0,0] neg_hi:[1,0,0]
	v_pk_fma_f32 v[104:105], v[104:105], v[172:173], v[72:73] op_sel_hi:[1,0,1]
	v_pk_fma_f32 v[98:99], v[98:99], v[172:173], v[62:63] op_sel_hi:[1,0,1]
	v_pk_fma_f32 v[100:101], v[68:69], v[170:171], v[100:101] op_sel:[0,1,0]
	s_ashr_i32 s1, s9, 8
	v_pk_fma_f32 v[100:101], v[100:101], v[172:173], v[64:65] op_sel_hi:[1,0,1]
	s_lshl_b32 s9, s44, 7
	s_or_b32 s9, s9, s22
	s_waitcnt vmcnt(6)
	v_permlane32_swap_b32_e32 v174, v162
	v_permlane32_swap_b32_e32 v175, v163
	v_permlane32_swap_b32_e32 v176, v164
	v_permlane32_swap_b32_e32 v177, v165
	v_permlane16_swap_b32_e32 v174, v162
	v_permlane16_swap_b32_e32 v175, v163
	v_permlane16_swap_b32_e32 v176, v164
	v_permlane16_swap_b32_e32 v177, v165
	v_mov_b32_e32 v168, v174
	v_mov_b32_e32 v169, v162
	v_mov_b32_e32 v182, v176
	v_mov_b32_e32 v183, v164
	v_pk_add_f32 v[168:169], v[168:169], v[182:183]
	v_mov_b32_e32 v162, v175
	v_pk_add_f32 v[168:169], v[168:169], v[168:169] op_sel:[0,1] op_sel_hi:[1,0]
	v_mov_b32_e32 v164, v177
	v_pk_add_f32 v[162:163], v[162:163], v[164:165]
	v_mov_b32_e32 v0, v168
	v_pk_add_f32 v[162:163], v[162:163], v[162:163] op_sel:[0,1] op_sel_hi:[1,0]
	s_nop 0
	v_permlane16_swap_b32_e32 v168, v0
	v_add_f32_e32 v163, v168, v0
	v_mov_b32_e32 v0, v162
	s_nop 1
	v_permlane16_swap_b32_e32 v162, v0
	v_add_f32_e32 v162, v162, v0
	v_mov_b32_e32 v165, v163
	v_mov_b32_e32 v164, v162
	s_nop 0
	v_permlane32_swap_b32_e32 v163, v165
	v_permlane32_swap_b32_e32 v162, v164
	v_pk_add_f32 v[162:163], v[162:163], v[164:165]
	s_waitcnt vmcnt(5)
; __device__ __forceinline__ float xsum16(float v) { const auto r = __builtin_amdgcn_permlane16_swap(__float_as_uint(v), __float_as_uint(v), false, false); return __uint_as_float(r[0]) + __uint_as_float(r[1]); }
; __device__ __forceinline__ float xsum32(float v) { const auto r = __builtin_amdgcn_permlane32_swap(__float_as_uint(v), __float_as_uint(v), false, false); return __uint_as_float(r[0]) + __uint_as_float(r[1]); }
; __device__ __forceinline__ u32x4 pack8(const f32x4 a, const f32x4 b) { u32x4 w; w.x = cvt_pk_bf16(a[0], a[1]); w.y = cvt_pk_bf16(a[2], a[3]); w.z = cvt_pk_bf16(b[0], b[1]); w.w = cvt_pk_bf16(b[2], b[3]); return w; }
; __device__ __forceinline__ void row_stats4(const float* st, int rowb, int fq, float (&mu)[4], float (&rs)[4]) {
;     f32x4 a[4], b[4];
; #pragma unroll
;     for (int m = 0; m < 4; ++m) { const f32x4* p = (const f32x4*)(st + (size_t)(rowb + m * 16) * 32 + fq * 8); a[m] = p[0]; b[m] = p[1]; }
; #pragma unroll
;     for (int m = 0; m < 4; ++m) { float s1 = (a[m][0] + a[m][2]) + (b[m][0] + b[m][2]), s2 = (a[m][1] + a[m][3]) + (b[m][1] + b[m][3]);
;         s1 = xsum32(xsum16(s1)); s2 = xsum32(xsum16(s2));
;         const float mm = s1 * (1.0f / 1024.0f); mu[m] = mm; rs[m] = rsqrtf(fmaxf(s2 * (1.0f / 1024.0f) - mm * mm, 0.f) + LN_EPS_); }
;     __device__ __forceinline__ void operator()(const f32x4 (&acc)[2][2][4][2], const pg8::Unit& u, int wr, int wc, int fr, int fq) const {
;     ...
;             for (int m = 0; m < 4; ++m) { const float mu = ai ? muB[m] : muA[m], rs = ai ? rsB[m] : rsA[m]; f32x4 h[2];
; #pragma unroll
;                 for (int n = 0; n < 2; ++n) { const f32x4 zg = (acc[ai][0][m][n] - g0[n] * mu) * rs + b0[n], zu = (acc[ai][1][m][n] - g1[n] * mu) * rs + b1[n]; h[n] = silu_mul(zg, zu); }
;                 ow[ai][m] = pack8(h[0], h[1]); }
	v_mov_b32_e32 v164, v188
	v_pk_mul_f32 v[182:183], v[162:163], s[16:17] op_sel_hi:[1,0]
	s_waitcnt vmcnt(4)
	v_mov_b32_e32 v163, v190
	v_fma_f32 v0, -v183, v183, v182
	v_max_f32_e32 v0, 0, v0
	v_add_f32_e32 v0, 0x3727c5ac, v0
	v_cmp_gt_f32_e32 vcc, s2, v0
	v_mul_f32_e32 v162, 0x4b800000, v0
	v_mov_b32_e32 v165, v192
	v_cndmask_b32_e32 v0, v0, v162, vcc
	v_rsq_f32_e32 v0, v0
	v_mov_b32_e32 v190, v187
	v_mov_b32_e32 v192, v189
	s_waitcnt vmcnt(0)
	v_mov_b32_e32 v187, v248
	v_mul_f32_e32 v162, 0x45800000, v0
	v_cndmask_b32_e32 v184, v0, v162, vcc
	v_mov_b32_e32 v162, v186
	v_pk_add_f32 v[162:163], v[162:163], v[164:165]
	v_pk_add_f32 v[164:165], v[190:191], v[192:193]
	v_pk_add_f32 v[162:163], v[162:163], v[162:163] op_sel:[0,1] op_sel_hi:[1,0]
	v_pk_add_f32 v[164:165], v[164:165], v[164:165] op_sel:[0,1] op_sel_hi:[1,0]
	v_mov_b32_e32 v0, v162
	s_nop 1
	v_permlane16_swap_b32_e32 v162, v0
	v_add_f32_e32 v163, v162, v0
	v_mov_b32_e32 v0, v164
	s_nop 1
	v_permlane16_swap_b32_e32 v164, v0
	v_add_f32_e32 v162, v164, v0
	v_mov_b32_e32 v165, v163
	v_mov_b32_e32 v164, v162
	s_nop 0
	v_permlane32_swap_b32_e32 v163, v165
	v_permlane32_swap_b32_e32 v162, v164
	v_pk_add_f32 v[162:163], v[162:163], v[164:165]
	v_mov_b32_e32 v164, v236
	v_pk_mul_f32 v[174:175], v[162:163], s[16:17] op_sel_hi:[1,0]
	v_mov_b32_e32 v163, v238
	v_fma_f32 v0, -v175, v175, v174
	v_max_f32_e32 v0, 0, v0
	v_add_f32_e32 v0, 0x3727c5ac, v0
	v_cmp_gt_f32_e32 vcc, s2, v0
	v_mul_f32_e32 v162, 0x4b800000, v0
	v_mov_b32_e32 v165, v240
	v_cndmask_b32_e32 v0, v0, v162, vcc
	v_rsq_f32_e32 v0, v0
	v_mov_b32_e32 v238, v235
	v_mov_b32_e32 v240, v237
	v_mov_b32_e32 v186, v244
	v_mul_f32_e32 v162, 0x45800000, v0
	v_cndmask_b32_e32 v176, v0, v162, vcc
	v_mov_b32_e32 v162, v234
	v_pk_add_f32 v[162:163], v[162:163], v[164:165]
	v_pk_add_f32 v[164:165], v[238:239], v[240:241]
	v_pk_add_f32 v[162:163], v[162:163], v[162:163] op_sel:[0,1] op_sel_hi:[1,0]
	v_pk_add_f32 v[164:165], v[164:165], v[164:165] op_sel:[0,1] op_sel_hi:[1,0]
	v_mov_b32_e32 v0, v162
	s_nop 1
	v_permlane16_swap_b32_e32 v162, v0
	v_add_f32_e32 v163, v162, v0
	v_mov_b32_e32 v0, v164
	s_nop 1
	v_permlane16_swap_b32_e32 v164, v0
	v_add_f32_e32 v162, v164, v0
	v_mov_b32_e32 v165, v163
	v_mov_b32_e32 v164, v162
	s_nop 0
	v_permlane32_swap_b32_e32 v163, v165
	v_permlane32_swap_b32_e32 v162, v164
	v_pk_add_f32 v[162:163], v[162:163], v[164:165]
	v_mov_b32_e32 v248, v245
	v_pk_mul_f32 v[164:165], v[162:163], s[16:17] op_sel_hi:[1,0]
	v_mov_b32_e32 v163, v246
	v_fma_f32 v0, -v165, v165, v164
	v_max_f32_e32 v0, 0, v0
	v_add_f32_e32 v0, 0x3727c5ac, v0
	v_cmp_gt_f32_e32 vcc, s2, v0
	v_mul_f32_e32 v162, 0x4b800000, v0
	v_mov_b32_e32 v246, v243
	v_cndmask_b32_e32 v0, v0, v162, vcc
	v_rsq_f32_e32 v0, v0
	v_pk_fma_f32 v[78:79], v[94:95], v[182:183], v[78:79] op_sel:[0,1,0] neg_lo:[1,0,0] neg_hi:[1,0,0]
	v_pk_fma_f32 v[58:59], v[86:87], v[182:183], v[58:59] op_sel:[0,1,0] neg_lo:[1,0,0] neg_hi:[1,0,0]
	v_pk_fma_f32 v[78:79], v[78:79], v[184:185], v[90:91] op_sel_hi:[1,0,1]
	v_mul_f32_e32 v162, 0x45800000, v0
	v_cndmask_b32_e32 v168, v0, v162, vcc
	v_mov_b32_e32 v162, v242
	v_pk_add_f32 v[162:163], v[162:163], v[186:187]
	v_pk_add_f32 v[186:187], v[246:247], v[248:249]
	v_pk_add_f32 v[162:163], v[162:163], v[162:163] op_sel:[0,1] op_sel_hi:[1,0]
	v_pk_add_f32 v[186:187], v[186:187], v[186:187] op_sel:[0,1] op_sel_hi:[1,0]
	v_mov_b32_e32 v0, v162
	s_nop 1
	v_permlane16_swap_b32_e32 v162, v0
	v_add_f32_e32 v163, v162, v0
	v_mov_b32_e32 v0, v186
	s_nop 1
	v_permlane16_swap_b32_e32 v186, v0
	v_add_f32_e32 v162, v186, v0
	v_mov_b32_e32 v187, v163
	v_mov_b32_e32 v186, v162
	s_nop 0
	v_permlane32_swap_b32_e32 v163, v187
	v_permlane32_swap_b32_e32 v162, v186
	v_pk_add_f32 v[162:163], v[162:163], v[186:187]
	v_pk_fma_f32 v[186:187], v[94:95], v[210:211], v[158:159] op_sel:[0,1,0] neg_lo:[1,0,0] neg_hi:[1,0,0]
	v_pk_mul_f32 v[162:163], v[162:163], s[16:17] op_sel_hi:[1,0]
	v_xor_b32_e32 v159, 0x80000000, v97
	v_fma_f32 v0, -v163, v163, v162
	v_max_f32_e32 v0, 0, v0
	v_add_f32_e32 v0, 0x3727c5ac, v0
	v_cmp_gt_f32_e32 vcc, s2, v0
	v_mul_f32_e32 v167, 0x4b800000, v0
	v_xor_b32_e32 v158, 0x80000000, v96
	v_cndmask_b32_e32 v0, v0, v167, vcc
	v_rsq_f32_e32 v0, v0
	v_pk_fma_f32 v[96:97], v[158:159], v[210:211], v[160:161] op_sel:[0,1,0]
	v_pk_fma_f32 v[160:161], v[186:187], v[212:213], v[90:91] op_sel_hi:[1,0,1]
	v_pk_fma_f32 v[96:97], v[96:97], v[212:213], v[92:93] op_sel_hi:[1,0,1]
	v_mul_f32_e32 v167, 0x45800000, v0
	v_cndmask_b32_e32 v0, v0, v167, vcc
	v_mul_f32_e32 v167, 0xbfb8aa3b, v160
	v_exp_f32_e32 v167, v167
	v_pk_fma_f32 v[80:81], v[158:159], v[182:183], v[80:81] op_sel:[0,1,0]
	v_pk_fma_f32 v[58:59], v[58:59], v[184:185], v[82:83] op_sel_hi:[1,0,1]
	v_pk_fma_f32 v[80:81], v[80:81], v[184:185], v[92:93] op_sel_hi:[1,0,1]
	v_add_f32_e32 v167, 1.0, v167
	v_rcp_f32_e32 v186, v167
	v_mul_f32_e32 v167, 0xbfb8aa3b, v161
	v_exp_f32_e32 v167, v167
	v_pk_fma_f32 v[60:61], v[88:89], v[182:183], v[60:61] op_sel:[0,1,0]
	v_pk_fma_f32 v[54:55], v[74:75], v[182:183], v[54:55] op_sel:[0,1,0] neg_lo:[1,0,0] neg_hi:[1,0,0]
	v_pk_fma_f32 v[60:61], v[60:61], v[184:185], v[84:85] op_sel_hi:[1,0,1]
	v_add_f32_e32 v167, 1.0, v167
	v_rcp_f32_e32 v187, v167
	v_pk_fma_f32 v[54:55], v[54:55], v[184:185], v[70:71] op_sel_hi:[1,0,1]
	v_pk_fma_f32 v[56:57], v[76:77], v[182:183], v[56:57] op_sel:[0,1,0]
	v_pk_fma_f32 v[50:51], v[66:67], v[182:183], v[50:51] op_sel:[0,1,0] neg_lo:[1,0,0] neg_hi:[1,0,0]
	v_pk_mul_f32 v[160:161], v[160:161], v[186:187]
	v_pk_fma_f32 v[56:57], v[56:57], v[184:185], v[72:73] op_sel_hi:[1,0,1]
	v_pk_mul_f32 v[154:155], v[154:155], v[160:161]
; __device__ __forceinline__ u32x4 pack8(const f32x4 a, const f32x4 b) { u32x4 w; w.x = cvt_pk_bf16(a[0], a[1]); w.y = cvt_pk_bf16(a[2], a[3]); w.z = cvt_pk_bf16(b[0], b[1]); w.w = cvt_pk_bf16(b[2], b[3]); return w; }
; __device__ __forceinline__ void unpack8(const u32x4 w, f32x4& a, f32x4& b) {
;     a[0] = __uint_as_float(w.x << 16); a[1] = __uint_as_float(w.x & 0xffff0000u); a[2] = __uint_as_float(w.y << 16); a[3] = __uint_as_float(w.y & 0xffff0000u);
;     b[0] = __uint_as_float(w.z << 16); b[1] = __uint_as_float(w.z & 0xffff0000u); b[2] = __uint_as_float(w.w << 16); b[3] = __uint_as_float(w.w & 0xffff0000u); }
; __device__ __forceinline__ f32x4 silu_mul(const f32x4 g, const f32x4 u) { f32x4 r;
; #pragma unroll
;     for (int e = 0; e < 4; ++e) r[e] = g[e] * sigmoid_f(g[e]) * u[e];
;     return r; }
; __device__ __forceinline__ void row_stats4(const float* st, int rowb, int fq, float (&mu)[4], float (&rs)[4]) {
;     f32x4 a[4], b[4];
; #pragma unroll
;     for (int m = 0; m < 4; ++m) { const f32x4* p = (const f32x4*)(st + (size_t)(rowb + m * 16) * 32 + fq * 8); a[m] = p[0]; b[m] = p[1]; }
; #pragma unroll
;     for (int m = 0; m < 4; ++m) { float s1 = (a[m][0] + a[m][2]) + (b[m][0] + b[m][2]), s2 = (a[m][1] + a[m][3]) + (b[m][1] + b[m][3]);
;         s1 = xsum32(xsum16(s1)); s2 = xsum32(xsum16(s2));
;         const float mm = s1 * (1.0f / 1024.0f); mu[m] = mm; rs[m] = rsqrtf(fmaxf(s2 * (1.0f / 1024.0f) - mm * mm, 0.f) + LN_EPS_); }
;     asm volatile("" ::: "memory");
; }
;     __device__ __forceinline__ void operator()(const f32x4 (&acc)[2][2][4][2], const pg8::Unit& u, int wr, int wc, int fr, int fq) const {
;         const int row0 = u.pm * 256 + wr * 64 + fr, cl = wc * 32 + fq * 8, cB0 = u.pn * 256 + cl;
;         f32x4 g0[2], g1[2], b0[2], b1[2];
; #pragma unroll
;         for (int n = 0; n < 2; ++n) { g0[n] = *(const f32x4*)(gW + cB0 + 4 * n); g1[n] = *(const f32x4*)(gW + cB0 + 128 + 4 * n); b0[n] = *(const f32x4*)(bW + cB0 + 4 * n); b1[n] = *(const f32x4*)(bW + cB0 + 128 + 4 * n); }
;         float muA[4], rsA[4], muB[4], rsB[4]; row_stats4(st, row0, fq, muA, rsA); row_stats4(st, row0 + 128, fq, muB, rsB);
;         u32x4 ow[2][4];
; #pragma unroll
;         for (int ai = 0; ai < 2; ++ai)
; #pragma unroll
;             for (int m = 0; m < 4; ++m) { const float mu = ai ? muB[m] : muA[m], rs = ai ? rsB[m] : rsA[m]; f32x4 h[2];
; #pragma unroll
	v_mul_f32_e32 v160, 0xbfb8aa3b, v96
	v_mul_f32_e32 v161, 0xbfb8aa3b, v97
	v_exp_f32_e32 v160, v160
	v_exp_f32_e32 v161, v161
	v_pk_fma_f32 v[50:51], v[50:51], v[184:185], v[62:63] op_sel_hi:[1,0,1]
	v_pk_fma_f32 v[52:53], v[68:69], v[182:183], v[52:53] op_sel:[0,1,0]
	v_add_f32_e32 v160, 1.0, v160
	v_add_f32_e32 v161, 1.0, v161
	v_rcp_f32_e32 v160, v160
	v_rcp_f32_e32 v161, v161
	v_pk_fma_f32 v[46:47], v[94:95], v[174:175], v[46:47] op_sel:[0,1,0] neg_lo:[1,0,0] neg_hi:[1,0,0]
	v_pk_fma_f32 v[52:53], v[52:53], v[184:185], v[64:65] op_sel_hi:[1,0,1]
	v_pk_fma_f32 v[46:47], v[46:47], v[176:177], v[90:91] op_sel_hi:[1,0,1]
	v_pk_mul_f32 v[96:97], v[96:97], v[160:161]
	v_pk_fma_f32 v[48:49], v[158:159], v[174:175], v[48:49] op_sel:[0,1,0]
	v_pk_mul_f32 v[96:97], v[156:157], v[96:97]
	v_mul_f32_e32 v156, 0xbfb8aa3b, v150
	v_mul_f32_e32 v157, 0xbfb8aa3b, v151
	v_exp_f32_e32 v156, v156
	v_exp_f32_e32 v157, v157
	v_pk_fma_f32 v[42:43], v[86:87], v[174:175], v[42:43] op_sel:[0,1,0] neg_lo:[1,0,0] neg_hi:[1,0,0]
	v_pk_fma_f32 v[48:49], v[48:49], v[176:177], v[92:93] op_sel_hi:[1,0,1]
	v_add_f32_e32 v156, 1.0, v156
	v_add_f32_e32 v157, 1.0, v157
	v_rcp_f32_e32 v156, v156
	v_rcp_f32_e32 v157, v157
	v_pk_fma_f32 v[42:43], v[42:43], v[176:177], v[82:83] op_sel_hi:[1,0,1]
	v_pk_fma_f32 v[44:45], v[88:89], v[174:175], v[44:45] op_sel:[0,1,0]
	v_pk_fma_f32 v[38:39], v[74:75], v[174:175], v[38:39] op_sel:[0,1,0] neg_lo:[1,0,0] neg_hi:[1,0,0]
	v_pk_mul_f32 v[150:151], v[150:151], v[156:157]
	v_pk_fma_f32 v[44:45], v[44:45], v[176:177], v[84:85] op_sel_hi:[1,0,1]
	v_pk_mul_f32 v[150:151], v[146:147], v[150:151]
	v_mul_f32_e32 v146, 0xbfb8aa3b, v152
	v_mul_f32_e32 v147, 0xbfb8aa3b, v153
	v_exp_f32_e32 v146, v146
	v_exp_f32_e32 v147, v147
	v_pk_fma_f32 v[38:39], v[38:39], v[176:177], v[70:71] op_sel_hi:[1,0,1]
	v_pk_fma_f32 v[40:41], v[76:77], v[174:175], v[40:41] op_sel:[0,1,0]
	v_add_f32_e32 v146, 1.0, v146
	v_add_f32_e32 v147, 1.0, v147
	v_rcp_f32_e32 v146, v146
	v_rcp_f32_e32 v147, v147
	v_pk_fma_f32 v[34:35], v[66:67], v[174:175], v[34:35] op_sel:[0,1,0] neg_lo:[1,0,0] neg_hi:[1,0,0]
	v_pk_fma_f32 v[40:41], v[40:41], v[176:177], v[72:73] op_sel_hi:[1,0,1]
	v_pk_fma_f32 v[34:35], v[34:35], v[176:177], v[62:63] op_sel_hi:[1,0,1]
	v_pk_mul_f32 v[146:147], v[152:153], v[146:147]
	v_pk_fma_f32 v[36:37], v[68:69], v[174:175], v[36:37] op_sel:[0,1,0]
	v_pk_mul_f32 v[152:153], v[148:149], v[146:147]
	v_cvt_pk_bf16_f32 v147, v96, v97
	v_pk_fma_f32 v[96:97], v[94:95], v[214:215], v[142:143] op_sel:[0,1,0] neg_lo:[1,0,0] neg_hi:[1,0,0]
	v_pk_fma_f32 v[142:143], v[158:159], v[214:215], v[144:145] op_sel:[0,1,0]
	v_pk_fma_f32 v[96:97], v[96:97], v[216:217], v[90:91] op_sel_hi:[1,0,1]
	v_pk_fma_f32 v[142:143], v[142:143], v[216:217], v[92:93] op_sel_hi:[1,0,1]
	v_mul_f32_e32 v144, 0xbfb8aa3b, v96
	v_mul_f32_e32 v145, 0xbfb8aa3b, v97
	v_exp_f32_e32 v144, v144
	v_exp_f32_e32 v145, v145
	v_pk_fma_f32 v[30:31], v[94:95], v[164:165], v[30:31] op_sel:[0,1,0] neg_lo:[1,0,0] neg_hi:[1,0,0]
	v_pk_fma_f32 v[36:37], v[36:37], v[176:177], v[64:65] op_sel_hi:[1,0,1]
	v_add_f32_e32 v144, 1.0, v144
	v_add_f32_e32 v145, 1.0, v145
	v_rcp_f32_e32 v144, v144
	v_rcp_f32_e32 v145, v145
	v_pk_fma_f32 v[30:31], v[30:31], v[168:169], v[90:91] op_sel_hi:[1,0,1]
	v_pk_fma_f32 v[32:33], v[158:159], v[164:165], v[32:33] op_sel:[0,1,0]
	v_pk_fma_f32 v[26:27], v[86:87], v[164:165], v[26:27] op_sel:[0,1,0] neg_lo:[1,0,0] neg_hi:[1,0,0]
	v_pk_mul_f32 v[96:97], v[96:97], v[144:145]
	v_pk_fma_f32 v[32:33], v[32:33], v[168:169], v[92:93] op_sel_hi:[1,0,1]
	v_pk_mul_f32 v[96:97], v[138:139], v[96:97]
	v_mul_f32_e32 v138, 0xbfb8aa3b, v142
	v_mul_f32_e32 v139, 0xbfb8aa3b, v143
	v_exp_f32_e32 v138, v138
	v_exp_f32_e32 v139, v139
	v_pk_fma_f32 v[26:27], v[26:27], v[168:169], v[82:83] op_sel_hi:[1,0,1]
	v_pk_fma_f32 v[28:29], v[88:89], v[164:165], v[28:29] op_sel:[0,1,0]
	v_add_f32_e32 v138, 1.0, v138
	v_add_f32_e32 v139, 1.0, v139
	v_rcp_f32_e32 v138, v138
	v_rcp_f32_e32 v139, v139
	v_pk_fma_f32 v[22:23], v[74:75], v[164:165], v[22:23] op_sel:[0,1,0] neg_lo:[1,0,0] neg_hi:[1,0,0]
	v_pk_fma_f32 v[28:29], v[28:29], v[168:169], v[84:85] op_sel_hi:[1,0,1]
	v_pk_fma_f32 v[22:23], v[22:23], v[168:169], v[70:71] op_sel_hi:[1,0,1]
	v_pk_mul_f32 v[138:139], v[142:143], v[138:139]
	v_pk_fma_f32 v[24:25], v[76:77], v[164:165], v[24:25] op_sel:[0,1,0]
	v_pk_mul_f32 v[138:139], v[140:141], v[138:139]
	v_mul_f32_e32 v140, 0xbfb8aa3b, v134
	v_mul_f32_e32 v141, 0xbfb8aa3b, v135
	v_exp_f32_e32 v140, v140
	v_exp_f32_e32 v141, v141
	v_pk_fma_f32 v[18:19], v[66:67], v[164:165], v[18:19] op_sel:[0,1,0] neg_lo:[1,0,0] neg_hi:[1,0,0]
	v_pk_fma_f32 v[24:25], v[24:25], v[168:169], v[72:73] op_sel_hi:[1,0,1]
	v_add_f32_e32 v140, 1.0, v140
	v_add_f32_e32 v141, 1.0, v141
	v_rcp_f32_e32 v140, v140
	v_rcp_f32_e32 v141, v141
	v_pk_fma_f32 v[18:19], v[18:19], v[168:169], v[62:63] op_sel_hi:[1,0,1]
	v_pk_fma_f32 v[20:21], v[68:69], v[164:165], v[20:21] op_sel:[0,1,0]
	v_pk_fma_f32 v[14:15], v[94:95], v[162:163], v[14:15] op_sel:[0,1,0] neg_lo:[1,0,0] neg_hi:[1,0,0]
	v_pk_mul_f32 v[134:135], v[134:135], v[140:141]
	v_pk_fma_f32 v[20:21], v[20:21], v[168:169], v[64:65] op_sel_hi:[1,0,1]
	v_pk_mul_f32 v[134:135], v[130:131], v[134:135]
	v_mul_f32_e32 v130, 0xbfb8aa3b, v136
	v_mul_f32_e32 v131, 0xbfb8aa3b, v137
	v_exp_f32_e32 v130, v130
	v_exp_f32_e32 v131, v131
	v_pk_fma_f32 v[14:15], v[14:15], v[0:1], v[90:91] op_sel_hi:[1,0,1]
	v_pk_fma_f32 v[16:17], v[158:159], v[162:163], v[16:17] op_sel:[0,1,0]
	v_add_f32_e32 v130, 1.0, v130
	v_add_f32_e32 v131, 1.0, v131
	v_rcp_f32_e32 v130, v130
	v_rcp_f32_e32 v131, v131
; __device__ __forceinline__ float sigmoid_f(float x) { return fast_rcp(1.0f + fast_exp2(-1.4426950408889634f * x)); }
; __device__ __forceinline__ size_t blk_off(int r, int c, int K) { return (size_t)(r >> 8) * 256 * K + (size_t)(c >> 6) * (256 * 64) + (size_t)((r & 255) * 64 + (c & 63)); }
; __device__ __forceinline__ u32x4 pack8(const f32x4 a, const f32x4 b) { u32x4 w; w.x = cvt_pk_bf16(a[0], a[1]); w.y = cvt_pk_bf16(a[2], a[3]); w.z = cvt_pk_bf16(b[0], b[1]); w.w = cvt_pk_bf16(b[2], b[3]); return w; }
; __device__ __forceinline__ f32x4 silu_mul(const f32x4 g, const f32x4 u) { f32x4 r;
; #pragma unroll
;     for (int e = 0; e < 4; ++e) r[e] = g[e] * sigmoid_f(g[e]) * u[e];
;     return r; }
;     __device__ __forceinline__ void operator()(const f32x4 (&acc)[2][2][4][2], const pg8::Unit& u, int wr, int wc, int fr, int fq) const {
;     ...
;             for (int m = 0; m < 4; ++m) { const float mu = ai ? muB[m] : muA[m], rs = ai ? rsB[m] : rsA[m]; f32x4 h[2];
; #pragma unroll
;                 for (int n = 0; n < 2; ++n) { const f32x4 zg = (acc[ai][0][m][n] - g0[n] * mu) * rs + b0[n], zu = (acc[ai][1][m][n] - g1[n] * mu) * rs + b1[n]; h[n] = silu_mul(zg, zu); }
;                 ow[ai][m] = pack8(h[0], h[1]); }
;         asm volatile("" ::: "memory");
; #pragma unroll
;         for (int ai = 0; ai < 2; ++ai)
; #pragma unroll
;             for (int m = 0; m < 4; ++m) *(u32x4*)(H + blk_off(row0 + ai * 128 + m * 16, u.pn * 128 + cl, FF_)) = ow[ai][m];
	v_pk_fma_f32 v[10:11], v[86:87], v[162:163], v[10:11] op_sel:[0,1,0] neg_lo:[1,0,0] neg_hi:[1,0,0]
	v_pk_fma_f32 v[16:17], v[16:17], v[0:1], v[92:93] op_sel_hi:[1,0,1]
	v_pk_fma_f32 v[10:11], v[10:11], v[0:1], v[82:83] op_sel_hi:[1,0,1]
	v_pk_mul_f32 v[130:131], v[136:137], v[130:131]
	v_pk_fma_f32 v[6:7], v[74:75], v[162:163], v[6:7] op_sel:[0,1,0] neg_lo:[1,0,0] neg_hi:[1,0,0]
	v_pk_mul_f32 v[136:137], v[132:133], v[130:131]
	v_cvt_pk_bf16_f32 v130, v96, v97
	v_pk_fma_f32 v[96:97], v[94:95], v[178:179], v[126:127] op_sel:[0,1,0] neg_lo:[1,0,0] neg_hi:[1,0,0]
	v_pk_fma_f32 v[126:127], v[158:159], v[178:179], v[128:129] op_sel:[0,1,0]
	v_pk_fma_f32 v[96:97], v[96:97], v[180:181], v[90:91] op_sel_hi:[1,0,1]
	v_pk_fma_f32 v[126:127], v[126:127], v[180:181], v[92:93] op_sel_hi:[1,0,1]
	v_mul_f32_e32 v128, 0xbfb8aa3b, v96
	v_mul_f32_e32 v129, 0xbfb8aa3b, v97
	v_exp_f32_e32 v128, v128
	v_exp_f32_e32 v129, v129
	v_pk_fma_f32 v[12:13], v[88:89], v[162:163], v[12:13] op_sel:[0,1,0]
	v_pk_fma_f32 v[8:9], v[76:77], v[162:163], v[8:9] op_sel:[0,1,0]
	v_add_f32_e32 v128, 1.0, v128
	v_add_f32_e32 v129, 1.0, v129
	v_rcp_f32_e32 v128, v128
	v_rcp_f32_e32 v129, v129
	v_pk_fma_f32 v[6:7], v[6:7], v[0:1], v[70:71] op_sel_hi:[1,0,1]
	v_pk_fma_f32 v[2:3], v[66:67], v[162:163], v[2:3] op_sel:[0,1,0] neg_lo:[1,0,0] neg_hi:[1,0,0]
	v_pk_fma_f32 v[4:5], v[68:69], v[162:163], v[4:5] op_sel:[0,1,0]
	v_pk_mul_f32 v[96:97], v[96:97], v[128:129]
	v_pk_fma_f32 v[12:13], v[12:13], v[0:1], v[84:85] op_sel_hi:[1,0,1]
	v_pk_mul_f32 v[96:97], v[122:123], v[96:97]
	v_mul_f32_e32 v122, 0xbfb8aa3b, v126
	v_mul_f32_e32 v123, 0xbfb8aa3b, v127
	v_exp_f32_e32 v122, v122
	v_exp_f32_e32 v123, v123
	v_pk_fma_f32 v[8:9], v[8:9], v[0:1], v[72:73] op_sel_hi:[1,0,1]
	v_pk_fma_f32 v[4:5], v[4:5], v[0:1], v[64:65] op_sel_hi:[1,0,1]
	v_add_f32_e32 v122, 1.0, v122
	v_add_f32_e32 v123, 1.0, v123
	v_rcp_f32_e32 v122, v122
	v_rcp_f32_e32 v123, v123
	v_pk_fma_f32 v[2:3], v[2:3], v[0:1], v[62:63] op_sel_hi:[1,0,1]
	v_mul_f32_e32 v0, 0xbfb8aa3b, v6
	v_exp_f32_e32 v0, v0
	v_pk_mul_f32 v[122:123], v[126:127], v[122:123]
	s_ashr_i32 s16, s9, 6
	v_pk_mul_f32 v[122:123], v[124:125], v[122:123]
	v_mul_f32_e32 v124, 0xbfb8aa3b, v118
	v_mul_f32_e32 v125, 0xbfb8aa3b, v119
	v_exp_f32_e32 v124, v124
	v_exp_f32_e32 v125, v125
	v_add_f32_e32 v0, 1.0, v0
	s_mul_hi_i32 s2, s1, 0x160000
	v_add_f32_e32 v124, 1.0, v124
	v_add_f32_e32 v125, 1.0, v125
	v_rcp_f32_e32 v124, v124
	v_rcp_f32_e32 v125, v125
	s_mul_i32 s1, s1, 0x160000
	s_ashr_i32 s17, s16, 31
	s_add_u32 s1, s30, s1
	v_pk_mul_f32 v[118:119], v[118:119], v[124:125]
	s_addc_u32 s2, s31, s2
	v_pk_mul_f32 v[118:119], v[114:115], v[118:119]
	v_mul_f32_e32 v114, 0xbfb8aa3b, v120
	v_mul_f32_e32 v115, 0xbfb8aa3b, v121
	v_exp_f32_e32 v114, v114
	v_exp_f32_e32 v115, v115
	s_lshl_b64 s[16:17], s[16:17], 15
	s_add_u32 s28, s1, s16
	v_add_f32_e32 v114, 1.0, v114
	v_add_f32_e32 v115, 1.0, v115
	v_rcp_f32_e32 v114, v114
	v_rcp_f32_e32 v115, v115
	s_addc_u32 s29, s2, s17
	s_movk_i32 s1, 0x1000
	v_cvt_pk_bf16_f32 v146, v154, v155
	v_pk_mul_f32 v[114:115], v[120:121], v[114:115]
	v_cvt_pk_bf16_f32 v148, v150, v151
	v_pk_mul_f32 v[120:121], v[116:117], v[114:115]
	v_cvt_pk_bf16_f32 v114, v96, v97
	v_pk_fma_f32 v[96:97], v[94:95], v[170:171], v[110:111] op_sel:[0,1,0] neg_lo:[1,0,0] neg_hi:[1,0,0]
	v_pk_fma_f32 v[110:111], v[158:159], v[170:171], v[112:113] op_sel:[0,1,0]
	v_pk_fma_f32 v[96:97], v[96:97], v[172:173], v[90:91] op_sel_hi:[1,0,1]
	v_pk_fma_f32 v[110:111], v[110:111], v[172:173], v[92:93] op_sel_hi:[1,0,1]
	v_mul_f32_e32 v112, 0xbfb8aa3b, v96
	v_mul_f32_e32 v113, 0xbfb8aa3b, v97
	v_exp_f32_e32 v112, v112
	v_exp_f32_e32 v113, v113
	v_cvt_pk_bf16_f32 v149, v152, v153
	v_cvt_pk_bf16_f32 v115, v122, v123
	v_add_f32_e32 v112, 1.0, v112
	v_add_f32_e32 v113, 1.0, v113
	v_rcp_f32_e32 v112, v112
	v_rcp_f32_e32 v113, v113
	v_cvt_pk_bf16_f32 v116, v118, v119
	v_cvt_pk_bf16_f32 v117, v120, v121
	v_cvt_pk_bf16_f32 v131, v138, v139
	v_pk_mul_f32 v[96:97], v[96:97], v[112:113]
	v_cvt_pk_bf16_f32 v132, v134, v135
	v_pk_mul_f32 v[96:97], v[106:107], v[96:97]
	v_mul_f32_e32 v106, 0xbfb8aa3b, v110
	v_mul_f32_e32 v107, 0xbfb8aa3b, v111
	v_exp_f32_e32 v106, v106
	v_exp_f32_e32 v107, v107
	v_cvt_pk_bf16_f32 v133, v136, v137
	v_cvt_pk_bf16_f32 v96, v96, v97
	v_add_f32_e32 v106, 1.0, v106
	v_add_f32_e32 v107, 1.0, v107
	v_rcp_f32_e32 v106, v106
	v_rcp_f32_e32 v107, v107
	s_nop 0
	v_pk_mul_f32 v[106:107], v[110:111], v[106:107]
	s_nop 0
	v_pk_mul_f32 v[106:107], v[108:109], v[106:107]
	v_mul_f32_e32 v108, 0xbfb8aa3b, v102
	v_mul_f32_e32 v109, 0xbfb8aa3b, v103
	v_exp_f32_e32 v108, v108
	v_exp_f32_e32 v109, v109
	v_cvt_pk_bf16_f32 v97, v106, v107
	v_add_f32_e32 v108, 1.0, v108
	v_add_f32_e32 v109, 1.0, v109
	v_rcp_f32_e32 v108, v108
	v_rcp_f32_e32 v109, v109
	s_nop 0
	v_pk_mul_f32 v[102:103], v[102:103], v[108:109]
	s_nop 0
	v_pk_mul_f32 v[98:99], v[98:99], v[102:103]
	v_mul_f32_e32 v102, 0xbfb8aa3b, v104
	v_mul_f32_e32 v103, 0xbfb8aa3b, v105
	v_exp_f32_e32 v102, v102
	v_exp_f32_e32 v103, v103
	v_cvt_pk_bf16_f32 v98, v98, v99
	v_add_f32_e32 v102, 1.0, v102
	v_add_f32_e32 v103, 1.0, v103
	v_rcp_f32_e32 v102, v102
	v_rcp_f32_e32 v103, v103
	s_nop 0
	v_pk_mul_f32 v[102:103], v[104:105], v[102:103]
	s_nop 0
	v_pk_mul_f32 v[100:101], v[100:101], v[102:103]
	s_nop 0
	v_cvt_pk_bf16_f32 v99, v100, v101
	v_mul_f32_e32 v100, 0xbfb8aa3b, v78
	v_mul_f32_e32 v101, 0xbfb8aa3b, v79
	v_exp_f32_e32 v100, v100
	v_exp_f32_e32 v101, v101
	v_add_f32_e32 v100, 1.0, v100
	v_add_f32_e32 v101, 1.0, v101
	v_rcp_f32_e32 v100, v100
	v_rcp_f32_e32 v101, v101
	s_nop 0
	v_pk_mul_f32 v[78:79], v[78:79], v[100:101]
; __device__ __forceinline__ size_t blk_off(int r, int c, int K) { return (size_t)(r >> 8) * 256 * K + (size_t)(c >> 6) * (256 * 64) + (size_t)((r & 255) * 64 + (c & 63)); }
; #define PG8_BAR __builtin_amdgcn_s_barrier()
; __device__ __forceinline__ u32x4 pack8(const f32x4 a, const f32x4 b) { u32x4 w; w.x = cvt_pk_bf16(a[0], a[1]); w.y = cvt_pk_bf16(a[2], a[3]); w.z = cvt_pk_bf16(b[0], b[1]); w.w = cvt_pk_bf16(b[2], b[3]); return w; }
; template <class Epi, class Sched, bool ALIGN_EPI = false, bool SP2 = false>
; __device__ __forceinline__ void gemm_phase(PG8_LAS unsigned char* lds, const Gemm g, const Sched& S, const Epi& E) {
;     ...
;         if constexpr (ALIGN_EPI) { if (wr == 0) PG8_BAR; }
;         if constexpr (!Epi::AFTER_DRAIN) { E(acc, cur, wr, wc, fr, fq); S.done(cur); }
;         if (!has_next) break;
; #pragma unroll
;         for (int a = 0; a < 2; ++a)
; #pragma unroll
;             for (int b = 0; b < 2; ++b)
; #pragma unroll
;                 for (int m = 0; m < 4; ++m)
; #pragma unroll
;                     for (int n = 0; n < 2; ++n) acc[a][b][m][n] = (f32x4){0.f, 0.f, 0.f, 0.f};
;         cur = nxt; cA = nA; cB = nB; ++ui;
;         if constexpr (ALIGN_EPI) { if (wr == 1) PG8_BAR; }
;     __device__ __forceinline__ void operator()(const f32x4 (&acc)[2][2][4][2], const pg8::Unit& u, int wr, int wc, int fr, int fq) const {
;     ...
;             for (int m = 0; m < 4; ++m) { const float mu = ai ? muB[m] : muA[m], rs = ai ? rsB[m] : rsA[m]; f32x4 h[2];
; #pragma unroll
;                 for (int n = 0; n < 2; ++n) { const f32x4 zg = (acc[ai][0][m][n] - g0[n] * mu) * rs + b0[n], zu = (acc[ai][1][m][n] - g1[n] * mu) * rs + b1[n]; h[n] = silu_mul(zg, zu); }
;                 ow[ai][m] = pack8(h[0], h[1]); }
;         asm volatile("" ::: "memory");
; #pragma unroll
;         for (int ai = 0; ai < 2; ++ai)
; #pragma unroll
;             for (int m = 0; m < 4; ++m) *(u32x4*)(H + blk_off(row0 + ai * 128 + m * 16, u.pn * 128 + cl, FF_)) = ow[ai][m];
	s_nop 0
	v_pk_mul_f32 v[58:59], v[58:59], v[78:79]
	v_mul_f32_e32 v78, 0xbfb8aa3b, v80
	v_mul_f32_e32 v79, 0xbfb8aa3b, v81
	v_exp_f32_e32 v78, v78
	v_exp_f32_e32 v79, v79
	v_add_f32_e32 v78, 1.0, v78
	v_add_f32_e32 v79, 1.0, v79
	v_rcp_f32_e32 v78, v78
	v_rcp_f32_e32 v79, v79
	s_nop 0
	v_pk_mul_f32 v[78:79], v[80:81], v[78:79]
	s_nop 0
	v_pk_mul_f32 v[60:61], v[60:61], v[78:79]
	v_mul_f32_e32 v78, 0xbfb8aa3b, v54
	v_mul_f32_e32 v79, 0xbfb8aa3b, v55
	v_exp_f32_e32 v78, v78
	v_exp_f32_e32 v79, v79
	v_add_f32_e32 v78, 1.0, v78
	v_add_f32_e32 v79, 1.0, v79
	v_rcp_f32_e32 v78, v78
	v_rcp_f32_e32 v79, v79
	s_nop 0
	v_pk_mul_f32 v[54:55], v[54:55], v[78:79]
	s_nop 0
	v_pk_mul_f32 v[54:55], v[50:51], v[54:55]
	v_mul_f32_e32 v50, 0xbfb8aa3b, v56
	v_mul_f32_e32 v51, 0xbfb8aa3b, v57
	v_exp_f32_e32 v50, v50
	v_exp_f32_e32 v51, v51
	v_add_f32_e32 v50, 1.0, v50
	v_add_f32_e32 v51, 1.0, v51
	v_rcp_f32_e32 v50, v50
	v_rcp_f32_e32 v51, v51
	s_nop 0
	v_pk_mul_f32 v[50:51], v[56:57], v[50:51]
	s_nop 0
	v_pk_mul_f32 v[56:57], v[52:53], v[50:51]
	v_cvt_pk_bf16_f32 v52, v54, v55
	v_mul_f32_e32 v54, 0xbfb8aa3b, v46
	v_mul_f32_e32 v55, 0xbfb8aa3b, v47
	v_exp_f32_e32 v54, v54
	v_exp_f32_e32 v55, v55
	v_cvt_pk_bf16_f32 v50, v58, v59
	v_cvt_pk_bf16_f32 v51, v60, v61
	v_add_f32_e32 v54, 1.0, v54
	v_add_f32_e32 v55, 1.0, v55
	v_rcp_f32_e32 v54, v54
	v_rcp_f32_e32 v55, v55
	v_cvt_pk_bf16_f32 v53, v56, v57
	v_pk_mul_f32 v[46:47], v[46:47], v[54:55]
	s_nop 0
	v_pk_mul_f32 v[42:43], v[42:43], v[46:47]
	v_mul_f32_e32 v46, 0xbfb8aa3b, v48
	v_mul_f32_e32 v47, 0xbfb8aa3b, v49
	v_exp_f32_e32 v46, v46
	v_exp_f32_e32 v47, v47
	v_add_f32_e32 v46, 1.0, v46
	v_add_f32_e32 v47, 1.0, v47
	v_rcp_f32_e32 v46, v46
	v_rcp_f32_e32 v47, v47
	s_nop 0
	v_pk_mul_f32 v[46:47], v[48:49], v[46:47]
	s_nop 0
	v_pk_mul_f32 v[44:45], v[44:45], v[46:47]
	v_mul_f32_e32 v46, 0xbfb8aa3b, v38
	v_mul_f32_e32 v47, 0xbfb8aa3b, v39
	v_exp_f32_e32 v46, v46
	v_exp_f32_e32 v47, v47
	v_add_f32_e32 v46, 1.0, v46
	v_add_f32_e32 v47, 1.0, v47
	v_rcp_f32_e32 v46, v46
	v_rcp_f32_e32 v47, v47
	s_nop 0
	v_pk_mul_f32 v[38:39], v[38:39], v[46:47]
	s_nop 0
	v_pk_mul_f32 v[38:39], v[34:35], v[38:39]
	v_mul_f32_e32 v34, 0xbfb8aa3b, v40
	v_mul_f32_e32 v35, 0xbfb8aa3b, v41
	v_exp_f32_e32 v34, v34
	v_exp_f32_e32 v35, v35
	v_add_f32_e32 v34, 1.0, v34
	v_add_f32_e32 v35, 1.0, v35
	v_rcp_f32_e32 v34, v34
	v_rcp_f32_e32 v35, v35
	s_nop 0
	v_pk_mul_f32 v[34:35], v[40:41], v[34:35]
	s_nop 0
	v_pk_mul_f32 v[40:41], v[36:37], v[34:35]
	v_cvt_pk_bf16_f32 v36, v38, v39
	v_mul_f32_e32 v38, 0xbfb8aa3b, v30
	v_mul_f32_e32 v39, 0xbfb8aa3b, v31
	v_exp_f32_e32 v38, v38
	v_exp_f32_e32 v39, v39
	v_cvt_pk_bf16_f32 v34, v42, v43
	v_cvt_pk_bf16_f32 v35, v44, v45
	v_add_f32_e32 v38, 1.0, v38
	v_add_f32_e32 v39, 1.0, v39
	v_rcp_f32_e32 v38, v38
	v_rcp_f32_e32 v39, v39
	v_cvt_pk_bf16_f32 v37, v40, v41
	v_pk_mul_f32 v[30:31], v[30:31], v[38:39]
	s_nop 0
	v_pk_mul_f32 v[26:27], v[26:27], v[30:31]
	v_mul_f32_e32 v30, 0xbfb8aa3b, v32
	v_mul_f32_e32 v31, 0xbfb8aa3b, v33
	v_exp_f32_e32 v30, v30
	v_exp_f32_e32 v31, v31
	v_add_f32_e32 v30, 1.0, v30
	v_add_f32_e32 v31, 1.0, v31
	v_rcp_f32_e32 v30, v30
	v_rcp_f32_e32 v31, v31
	s_nop 0
	v_pk_mul_f32 v[30:31], v[32:33], v[30:31]
	s_nop 0
	v_pk_mul_f32 v[28:29], v[28:29], v[30:31]
	v_mul_f32_e32 v30, 0xbfb8aa3b, v22
	v_mul_f32_e32 v31, 0xbfb8aa3b, v23
	v_exp_f32_e32 v30, v30
	v_exp_f32_e32 v31, v31
	v_add_f32_e32 v30, 1.0, v30
	v_add_f32_e32 v31, 1.0, v31
	v_rcp_f32_e32 v30, v30
	v_rcp_f32_e32 v31, v31
	s_nop 0
	v_pk_mul_f32 v[22:23], v[22:23], v[30:31]
	s_nop 0
	v_pk_mul_f32 v[22:23], v[18:19], v[22:23]
	v_mul_f32_e32 v18, 0xbfb8aa3b, v24
	v_mul_f32_e32 v19, 0xbfb8aa3b, v25
	v_exp_f32_e32 v18, v18
	v_exp_f32_e32 v19, v19
	v_add_f32_e32 v18, 1.0, v18
	v_add_f32_e32 v19, 1.0, v19
	v_rcp_f32_e32 v18, v18
	v_rcp_f32_e32 v19, v19
	s_nop 0
	v_pk_mul_f32 v[18:19], v[24:25], v[18:19]
	s_nop 0
	v_pk_mul_f32 v[24:25], v[20:21], v[18:19]
	v_cvt_pk_bf16_f32 v20, v22, v23
	v_mul_f32_e32 v22, 0xbfb8aa3b, v14
	v_mul_f32_e32 v23, 0xbfb8aa3b, v15
	v_exp_f32_e32 v22, v22
	v_exp_f32_e32 v23, v23
	v_cvt_pk_bf16_f32 v18, v26, v27
	v_cvt_pk_bf16_f32 v19, v28, v29
	v_add_f32_e32 v22, 1.0, v22
	v_add_f32_e32 v23, 1.0, v23
	v_rcp_f32_e32 v22, v22
	v_rcp_f32_e32 v23, v23
	v_cvt_pk_bf16_f32 v21, v24, v25
	v_pk_mul_f32 v[14:15], v[14:15], v[22:23]
	s_nop 0
	v_pk_mul_f32 v[10:11], v[10:11], v[14:15]
	v_mul_f32_e32 v14, 0xbfb8aa3b, v16
	v_mul_f32_e32 v15, 0xbfb8aa3b, v17
	v_exp_f32_e32 v14, v14
	v_exp_f32_e32 v15, v15
	v_add_f32_e32 v14, 1.0, v14
	v_add_f32_e32 v15, 1.0, v15
	v_rcp_f32_e32 v14, v14
	v_rcp_f32_e32 v15, v15
	s_nop 0
	v_pk_mul_f32 v[14:15], v[16:17], v[14:15]
	s_nop 0
	v_pk_mul_f32 v[12:13], v[12:13], v[14:15]
	v_rcp_f32_e32 v14, v0
	v_mul_f32_e32 v0, 0xbfb8aa3b, v7
	v_exp_f32_e32 v0, v0
	s_nop 0
	v_add_f32_e32 v0, 1.0, v0
	v_rcp_f32_e32 v15, v0
	v_mul_f32_e32 v0, 0xbfb8aa3b, v8
	v_exp_f32_e32 v0, v0
	v_pk_mul_f32 v[6:7], v[6:7], v[14:15]
	s_nop 0
	v_pk_mul_f32 v[6:7], v[2:3], v[6:7]
	v_add_f32_e32 v0, 1.0, v0
	v_rcp_f32_e32 v2, v0
	v_mul_f32_e32 v0, 0xbfb8aa3b, v9
	v_exp_f32_e32 v0, v0
	s_nop 0
	v_add_f32_e32 v0, 1.0, v0
	v_rcp_f32_e32 v3, v0
	v_lshlrev_b32_e32 v0, 6, v208
	v_and_or_b32 v0, v0, s11, v221
	v_lshlrev_b32_e32 v0, 1, v0
	v_pk_mul_f32 v[2:3], v[8:9], v[2:3]
	global_store_dwordx4 v0, v[146:149], s[28:29]
	global_store_dwordx4 v0, v[130:133], s[28:29] offset:2048
	v_pk_mul_f32 v[8:9], v[4:5], v[2:3]
	v_cvt_pk_bf16_f32 v4, v6, v7
	v_lshl_add_u64 v[6:7], s[28:29], 0, v[0:1]
	v_add_co_u32_e32 v6, vcc, s1, v6
	v_lshrrev_b32_e32 v0, 8, v166
	s_nop 0
	v_addc_co_u32_e32 v7, vcc, 0, v7, vcc
	global_store_dwordx4 v[6:7], v[114:117], off
	global_store_dwordx4 v[6:7], v[96:99], off offset:2048
	v_lshlrev_b32_e32 v6, 6, v166
	v_cvt_pk_bf16_f32 v5, v8, v9
	v_and_or_b32 v8, v6, s11, v221
	v_mul_hi_i32_i24_e32 v7, 0x160000, v0
	v_mul_i32_i24_e32 v6, 0x160000, v0
	v_lshl_add_u64 v[6:7], s[30:31], 0, v[6:7]
	v_lshl_add_u64 v[6:7], v[6:7], 0, s[16:17]
	v_lshlrev_b32_e32 v0, 1, v8
	v_lshl_add_u64 v[6:7], v[6:7], 0, v[0:1]
	global_store_dwordx4 v[6:7], v[50:53], off
	global_store_dwordx4 v[6:7], v[34:37], off offset:2048
	v_add_co_u32_e32 v6, vcc, 0x1000, v6
	s_mov_b64 s[28:29], -1
	s_nop 0
	v_addc_co_u32_e32 v7, vcc, 0, v7, vcc
	s_andn2_b64 vcc, exec, s[40:41]
	v_cvt_pk_bf16_f32 v2, v10, v11
	v_cvt_pk_bf16_f32 v3, v12, v13
	global_store_dwordx4 v[6:7], v[18:21], off
	global_store_dwordx4 v[6:7], v[2:5], off offset:2048
	s_cbranch_vccnz .LBB0_1617
	s_andn2_b64 vcc, exec, s[4:5]
	s_cbranch_vccnz .LBB0_1616
	s_barrier
	s_branch .LBB0_1616
